# MLA: K / V / rope-K tiles go global to LDS by global_load_lds with pre-swizzled source addresses (no staging registers, no ds_write)
# speedup vs baseline: 1.0090x; 1.0090x over previous
; #define SLOAD() do { vs0 = *(const bf16x8*)(Vh + voff); vs1 = *(const bf16x8*)(Vh + voff + 32u * (unsigned)ldv); \
;     ks0 = *(const bf16x8*)(Kh + koff); ks1 = *(const bf16x8*)(Kh + koff + 32u * (unsigned)ldk); \
;     if constexpr (NR > 0) { kr = *(const bf16x8*)(Krh + kroff); kroff += 64u * 64u; } voff += 64u * (unsigned)ldv; koff += 64u * (unsigned)ldk; } while (0)
; #define SWRITE(b) do { *(bf16x8*)(V_lds + (b) * SHM_V + vst0) = vs0; *(bf16x8*)(V_lds + (b) * SHM_V + vst1) = vs1; const int kc = sc * 2;  \
;     *(bf16x8*)(K_lds + (b) * SHM_K + KSWZ(sr, kc)) = ks0; *(bf16x8*)(K_lds + (b) * SHM_K + KSWZ(32 + sr, kc)) = ks1; \
;     if constexpr (NR > 0) *(bf16x8*)(Kr_lds + (b) * SHM_KR + krst) = kr; } while (0)
; __device__ __forceinline__ v8i32 cat8(v4i32 a, v4i32 b) { return (v8i32){a[0], a[1], a[2], a[3], b[0], b[1], b[2], b[3]}; }
; __device__ __forceinline__ void attn_unit7(const unsigned char* __restrict__ Q8, int ldq, const unsigned char* __restrict__ Kn8, int ldk, const unsigned char* __restrict__ Kr8, ...
;     ...
;   float m_reg = 0.f, l_reg = 0; f32x16 o[4] = {}; v8i32 qf[3];
;   { const unsigned char* Qw = Q8 + (unsigned)((wid * 32 + r32) * ldq + hi * 32);
; #pragma unroll
;     for (int s = 0; s < 3; ++s) qf[s] = cat8(*reinterpret_cast<const v4i32*>(Qw + s * 64), *reinterpret_cast<const v4i32*>(Qw + s * 64 + 16)); }
;   const int vtr = tid >> 2, vtc = tid & 3, vtst = vtr * 64 + ((vtc ^ ((vtr >> 2) & 3)) << 4);
;   const int knr = tid >> 3, knc = tid & 7, knst = KN8SW(knr, knc);
;   const int krr = (tid >> 2) & 63, krc = tid & 3, krst = KR8SW(krr, krc);
;   const bool krw = tid < 256;
;   unsigned vtoff = (unsigned)(tid * 16), knoff = (unsigned)(knr * ldk + knc * 16), kroff = (unsigned)(krr * 64 + krc * 16);
;   v4i32 vt, kn, kr;
;     ...
;   f32x16 pA0, pA1, pB0, pB1; float alA, alB; v8i32 p8;
;   SLOAD(); SWRITE(0); __syncthreads();
;   SLOAD();
;   qkt9(pA0, pA1, Kn_lds, Kr_lds, qf, 7.0f - m_reg, r32, hi); partialSM9(pA0, pA1, m_reg, alA, thr_raw);
;   SWRITE(1); __syncthreads();
;   for (int j = 1; j + 1 < NT; j += 2) {
;     SLOAD();
;     qkt9(pB0, pB1, Kn_lds + 8192, Kr_lds + 4096, qf, 7.0f - m_reg, r32, hi);
;     finishSM9(pA0, pA1, alA, l_reg, p8);
;     pv8(o, Vt_lds, p8, r32, hi); partialSM9(pB0, pB1, m_reg, alB, thr_raw);
.LBB0_1320:
	s_or_b64 exec, exec, s[20:21]
	v_and_b32_e32 v0, 0x3fffffc0, v12
	s_mov_b32 s20, 0x60000
	v_lshl_add_u32 v187, v0, 2, 0
	v_add3_u32 v178, v13, v14, s20
	v_add_u32_e32 v0, v15, v16
	v_mov_b32_e32 v14, v1
	v_mov_b32_e32 v15, v1
	v_and_b32_e32 v184, 63, v12
	v_lshl_add_u64 v[180:181], s[12:13], 0, v[0:1]
	v_mov_b32_e32 v0, v1
	v_mov_b32_e32 v2, v1
	v_mov_b32_e32 v3, v1
	v_mov_b32_e32 v4, v1
	v_mov_b32_e32 v5, v1
	v_mov_b32_e32 v6, v1
	v_mov_b32_e32 v7, v1
	v_mov_b32_e32 v8, v1
	v_mov_b32_e32 v9, v1
	v_mov_b32_e32 v10, v1
	v_mov_b32_e32 v11, v1
	v_mov_b32_e32 v12, v1
	v_mov_b32_e32 v13, v1
	v_mov_b64_e32 v[64:65], v[14:15]
	v_mov_b64_e32 v[48:49], v[14:15]
	v_mov_b64_e32 v[32:33], v[14:15]
	v_mov_b64_e32 v[62:63], v[12:13]
	v_mov_b64_e32 v[60:61], v[10:11]
	v_mov_b64_e32 v[58:59], v[8:9]
	v_mov_b64_e32 v[56:57], v[6:7]
	v_mov_b64_e32 v[54:55], v[4:5]
	v_mov_b64_e32 v[52:53], v[2:3]
	v_mov_b64_e32 v[50:51], v[0:1]
	v_mov_b64_e32 v[46:47], v[12:13]
	v_mov_b64_e32 v[44:45], v[10:11]
	v_mov_b64_e32 v[42:43], v[8:9]
	v_mov_b64_e32 v[40:41], v[6:7]
	v_mov_b64_e32 v[38:39], v[4:5]
	v_mov_b64_e32 v[36:37], v[2:3]
	v_mov_b64_e32 v[34:35], v[0:1]
	v_mov_b64_e32 v[30:31], v[12:13]
	v_mov_b64_e32 v[28:29], v[10:11]
	v_mov_b64_e32 v[26:27], v[8:9]
	v_mov_b64_e32 v[24:25], v[6:7]
	v_mov_b64_e32 v[22:23], v[4:5]
	v_mov_b64_e32 v[20:21], v[2:3]
	v_mov_b64_e32 v[18:19], v[0:1]
	v_mov_b64_e32 v[16:17], v[14:15]
	s_lshl_b32 s29, s29, 8
	v_cmp_gt_u32_e64 s[40:41], 32, v184
	v_lshl_add_u32 v208, v183, 2, v187
	v_lshlrev_b32_e32 v207, 4, v175
	v_add_u32_e32 v176, 0x6000, v174
	v_mov_b32_e32 v209, 0
	s_mov_b32 s30, -1
	v_mov_b64_e32 v[14:15], v[12:13]
	v_mov_b64_e32 v[12:13], v[10:11]
	v_mov_b64_e32 v[10:11], v[8:9]
	v_mov_b64_e32 v[8:9], v[6:7]
	v_mov_b64_e32 v[6:7], v[4:5]
	v_mov_b64_e32 v[4:5], v[2:3]
	v_mov_b64_e32 v[2:3], v[0:1]
	v_add_u32_e32 v176, 0xffffe000, v176
	v_add_u32_e32 v178, 0xfffe0000, v178
	v_sub_f32_e32 v230, 0x40e00000, v217
	v_mov_b32_e32 v231, v230
	v_mov_b32_e32 v232, v230
	v_mov_b32_e32 v233, v230
	v_mov_b32_e32 v234, v230
	v_mov_b32_e32 v235, v230
	v_mov_b32_e32 v236, v230
	v_mov_b32_e32 v237, v230
	v_mov_b32_e32 v238, v230
	v_mov_b32_e32 v239, v230
	v_mov_b32_e32 v240, v230
	v_mov_b32_e32 v241, v230
	v_mov_b32_e32 v242, v230
	v_mov_b32_e32 v243, v230
	v_mov_b32_e32 v244, v230
	v_mov_b32_e32 v245, v230
	s_mov_b32 s30, 0
	v_lshrrev_b32_e32 v222, 4, v189
	v_and_b32_e32 v223, 3, v222
	v_and_b32_e32 v222, 7, v222
	v_lshlrev_b32_e32 v223, 4, v223
	v_lshlrev_b32_e32 v222, 4, v222
	v_xor_b32_e32 v176, v176, v223
	v_xor_b32_e32 v180, v180, v223
	v_xor_b32_e32 v178, v178, v222
	v_lshrrev_b32_e32 v222, 6, v189
	s_nop 0
	v_readfirstlane_b32 s98, v222
	s_nop 3
	s_lshl_b32 s98, s98, 10
	s_waitcnt lgkmcnt(0)
	s_barrier
	s_cmp_eq_u64 s[42:43], 0
	s_cbranch_scc1 .Lmla_stag_entry
.LBB0_1321:
	ds_read_b128 v[114:117], v215 offset:24576
	ds_read_b128 v[118:121], v216 offset:24576
	ds_read_b128 v[222:225], v215 offset:28672
	ds_read_b128 v[226:229], v216 offset:28672
	s_add_i32 m0, s98, 0xa800
	s_nop 0
	global_load_lds_dwordx4 v176, s[18:19]
	s_add_i32 m0, s98, 0xc800
	s_nop 0
	global_load_lds_dwordx4 v178, s[16:17]
	s_add_i32 m0, s98, 0xe800
	s_nop 0
	global_load_lds_dwordx4 v[180:181], off
	v_add_u32_e32 v176, 0x2000, v176
	v_add_u32_e32 v178, 0x20000, v178
	s_mov_b64 s[20:21], 0x1000
	v_lshl_add_u64 v[180:181], v[180:181], 0, s[20:21]
	v_exp_f32_e32 v0, v82
	v_exp_f32_e32 v177, v83
	v_exp_f32_e32 v179, v84
	v_exp_f32_e32 v254, v85
	v_add_f32_e32 v219, v0, v177
	v_cvt_pk_fp8_f32 v246, v0, v177
	v_add_f32_e32 v219, v179, v219
	v_add_f32_e32 v219, v254, v219
	v_cvt_pk_fp8_f32 v246, v179, v254 op_sel:[0,0,1]
	s_waitcnt lgkmcnt(2)
	v_mfma_scale_f32_32x32x64_f8f6f4 v[114:129], v[114:121], v[146:153], v[230:245], v194, v193 op_sel_hi:[0,0,0]
	v_exp_f32_e32 v0, v86
	v_exp_f32_e32 v177, v87
	v_exp_f32_e32 v179, v88
	v_exp_f32_e32 v254, v89
	v_add_f32_e32 v219, v0, v219
	v_add_f32_e32 v219, v177, v219
	v_cvt_pk_fp8_f32 v247, v0, v177
	v_add_f32_e32 v219, v179, v219
	v_add_f32_e32 v219, v254, v219
	v_cvt_pk_fp8_f32 v247, v179, v254 op_sel:[0,0,1]
	ds_read_b128 v[82:85], v213 offset:24576
	ds_read_b128 v[86:89], v214 offset:24576
	s_waitcnt lgkmcnt(2)
	v_mfma_scale_f32_32x32x64_f8f6f4 v[98:113], v[222:229], v[146:153], v[230:245], v194, v193 op_sel_hi:[0,0,0]
	ds_read_b128 v[222:225], v213 offset:28672
	ds_read_b128 v[226:229], v214 offset:28672
	v_exp_f32_e32 v0, v90
	v_exp_f32_e32 v177, v91
	v_exp_f32_e32 v179, v92
	v_exp_f32_e32 v254, v93
	v_add_f32_e32 v219, v0, v219
	v_add_f32_e32 v219, v177, v219
	v_cvt_pk_fp8_f32 v248, v0, v177
	v_add_f32_e32 v219, v179, v219
	v_add_f32_e32 v219, v254, v219
	v_cvt_pk_fp8_f32 v248, v179, v254 op_sel:[0,0,1]
	v_exp_f32_e32 v0, v94
	v_exp_f32_e32 v177, v95
	v_exp_f32_e32 v179, v96
	v_exp_f32_e32 v254, v97
	v_add_f32_e32 v219, v0, v219
	v_add_f32_e32 v219, v177, v219
	v_cvt_pk_fp8_f32 v249, v0, v177
	v_add_f32_e32 v219, v179, v219
	v_add_f32_e32 v219, v254, v219
	v_cvt_pk_fp8_f32 v249, v179, v254 op_sel:[0,0,1]
	ds_read_b128 v[90:93], v185 offset:36864
	ds_read_b128 v[94:97], v186 offset:36864
	s_waitcnt lgkmcnt(4)
	v_mfma_scale_f32_32x32x64_f8f6f4 v[114:129], v[82:89], v[138:145], v[114:129], v194, v193 op_sel_hi:[0,0,0]
	v_exp_f32_e32 v0, v66
	v_exp_f32_e32 v177, v67
	v_exp_f32_e32 v179, v68
	v_exp_f32_e32 v254, v69
	v_add_f32_e32 v219, v0, v219
	v_add_f32_e32 v219, v177, v219
	v_cvt_pk_fp8_f32 v250, v0, v177
	v_add_f32_e32 v219, v179, v219
	v_add_f32_e32 v219, v254, v219
	v_cvt_pk_fp8_f32 v250, v179, v254 op_sel:[0,0,1]
	s_waitcnt lgkmcnt(2)
; __device__ __forceinline__ void finishSM9(f32x16& p0, f32x16& p1, float alpha, float& l_reg, v8i32& p8) {
; #pragma unroll
;   for (int r = 0; r < 16; ++r) { p0[r] = __builtin_amdgcn_exp2f(p0[r]); p1[r] = __builtin_amdgcn_exp2f(p1[r]); }
;   float ps = 0;
; #pragma unroll
;   for (int r = 0; r < 16; ++r) ps += p0[r];
; #pragma unroll
;   for (int r = 0; r < 16; ++r) ps += p1[r];
;   { auto rr = __builtin_amdgcn_permlane32_swap(__float_as_uint(ps), __float_as_uint(ps), false, false);
;     ps = __uint_as_float(rr[0]) + __uint_as_float(rr[1]); }
;   l_reg = l_reg * alpha + ps;
; #pragma unroll
;   for (int g = 0; g < 4; ++g) {
;     int w = __builtin_amdgcn_cvt_pk_fp8_f32(p0[4 * g], p0[4 * g + 1], 0, false); p8[g] = __builtin_amdgcn_cvt_pk_fp8_f32(p0[4 * g + 2], p0[4 * g + 3], w, true);
;     int u = __builtin_amdgcn_cvt_pk_fp8_f32(p1[4 * g], p1[4 * g + 1], 0, false); p8[4 + g] = __builtin_amdgcn_cvt_pk_fp8_f32(p1[4 * g + 2], p1[4 * g + 3], u, true); }
; }
; __device__ __forceinline__ void pv8(f32x16* o, const char* Vt, const v8i32 p8, int r32, int hi) {
;   const int sw = (r32 >> 2) & 3, a0 = r32 * 64 + (((hi * 2) ^ sw) << 4), a1 = r32 * 64 + (((hi * 2 + 1) ^ sw) << 4);
; #pragma unroll
;   for (int d0 = 0; d0 < 4; ++d0) {
;     const v8i32 vf = cat8(*reinterpret_cast<const v4i32*>(Vt + d0 * 2048 + a0), *reinterpret_cast<const v4i32*>(Vt + d0 * 2048 + a1));
;     o[d0] = __builtin_amdgcn_mfma_scale_f32_32x32x64_f8f6f4(p8, vf, o[d0], 0, 0, 0, 127, 0, 127); }
; }
; __device__ __forceinline__ void qkt9(f32x16& p0, f32x16& p1, const char* Kn, const char* Kr, const v8i32* qf, const float init, int r32, int hi) {
; #pragma unroll
;   for (int r = 0; r < 16; ++r) { p0[r] = init; p1[r] = init; }
; #pragma unroll
;   for (int s = 0; s < 2; ++s) { const int c0 = s * 4 + hi * 2;
;     const v8i32 a0 = cat8(*reinterpret_cast<const v4i32*>(Kn + KN8SW(r32, c0)), *reinterpret_cast<const v4i32*>(Kn + KN8SW(r32, c0 + 1)));
;     const v8i32 a1 = cat8(*reinterpret_cast<const v4i32*>(Kn + 4096 + KN8SW(r32, c0)), *reinterpret_cast<const v4i32*>(Kn + 4096 + KN8SW(r32, c0 + 1)));
;     p0 = __builtin_amdgcn_mfma_scale_f32_32x32x64_f8f6f4(a0, qf[s], p0, 0, 0, 0, 127, 0, 124);
;     p1 = __builtin_amdgcn_mfma_scale_f32_32x32x64_f8f6f4(a1, qf[s], p1, 0, 0, 0, 127, 0, 124); }
;   { const int c0 = hi * 2;
	v_mfma_scale_f32_32x32x64_f8f6f4 v[98:113], v[222:229], v[138:145], v[98:113], v194, v193 op_sel_hi:[0,0,0]
	ds_read_b128 v[222:225], v185 offset:38912
	ds_read_b128 v[226:229], v186 offset:38912
	v_exp_f32_e32 v0, v70
	v_exp_f32_e32 v177, v71
	v_exp_f32_e32 v179, v72
	v_exp_f32_e32 v254, v73
	v_add_f32_e32 v219, v0, v219
	v_add_f32_e32 v219, v177, v219
	v_cvt_pk_fp8_f32 v251, v0, v177
	v_add_f32_e32 v219, v179, v219
	v_add_f32_e32 v219, v254, v219
	v_cvt_pk_fp8_f32 v251, v179, v254 op_sel:[0,0,1]
	v_exp_f32_e32 v0, v74
	v_exp_f32_e32 v177, v75
	v_exp_f32_e32 v179, v76
	v_exp_f32_e32 v254, v77
	v_add_f32_e32 v219, v0, v219
	v_add_f32_e32 v219, v177, v219
	v_cvt_pk_fp8_f32 v252, v0, v177
	v_add_f32_e32 v219, v179, v219
	v_add_f32_e32 v219, v254, v219
	v_cvt_pk_fp8_f32 v252, v179, v254 op_sel:[0,0,1]
	s_waitcnt lgkmcnt(2)
	v_mfma_scale_f32_32x32x64_f8f6f4 v[114:129], v[90:97], v[130:137], v[114:129], v194, v193 op_sel_hi:[0,0,0]
	v_exp_f32_e32 v0, v78
	v_exp_f32_e32 v177, v79
	v_exp_f32_e32 v179, v80
	v_exp_f32_e32 v254, v81
	v_add_f32_e32 v219, v0, v219
	v_add_f32_e32 v219, v177, v219
	v_cvt_pk_fp8_f32 v253, v0, v177
	v_add_f32_e32 v219, v179, v219
	v_add_f32_e32 v219, v254, v219
	v_cvt_pk_fp8_f32 v253, v179, v254 op_sel:[0,0,1]
	ds_read_b128 v[90:93], v185 offset:0
	ds_read_b128 v[94:97], v186 offset:0
	ds_read_b128 v[82:85], v185 offset:2048
	ds_read_b128 v[86:89], v186 offset:2048
	ds_read_b128 v[74:77], v185 offset:4096
	ds_read_b128 v[78:81], v186 offset:4096
	ds_read_b128 v[66:69], v185 offset:6144
	ds_read_b128 v[70:73], v186 offset:6144
	s_waitcnt lgkmcnt(8)
	v_mfma_scale_f32_32x32x64_f8f6f4 v[98:113], v[222:229], v[130:137], v[98:113], v194, v193 op_sel_hi:[0,0,0]
	v_mov_b32_e32 v0, v219
	s_nop 1
	v_permlane32_swap_b32_e32 v219, v0
	v_add_f32_e32 v219, v219, v0
	v_fma_f32 v209, v209, v218, v219
	v_max_f32_e32 v177, v114, v115
	v_max3_f32 v177, v177, v116, v117
	v_max3_f32 v177, v177, v118, v119
	v_max3_f32 v177, v177, v120, v121
	v_max3_f32 v177, v177, v122, v123
	v_max3_f32 v177, v177, v124, v125
	v_max3_f32 v177, v177, v126, v127
	v_max3_f32 v177, v177, v128, v129
	s_waitcnt lgkmcnt(6)
	v_mfma_scale_f32_32x32x64_f8f6f4 v[50:65], v[246:253], v[90:97], v[50:65], v194, v194 op_sel_hi:[0,0,0]
	s_waitcnt lgkmcnt(4)
	v_mfma_scale_f32_32x32x64_f8f6f4 v[34:49], v[246:253], v[82:89], v[34:49], v194, v194 op_sel_hi:[0,0,0]
	s_waitcnt lgkmcnt(2)
	v_mfma_scale_f32_32x32x64_f8f6f4 v[18:33], v[246:253], v[74:81], v[18:33], v194, v194 op_sel_hi:[0,0,0]
	s_waitcnt lgkmcnt(0)
	v_mfma_scale_f32_32x32x64_f8f6f4 v[2:17], v[246:253], v[66:73], v[2:17], v194, v194 op_sel_hi:[0,0,0]
	s_waitcnt vmcnt(0)
	s_waitcnt lgkmcnt(0)
	s_barrier
	v_max_f32_e32 v0, v98, v99
	v_max3_f32 v0, v0, v100, v101
	v_max3_f32 v0, v0, v102, v103
	v_max3_f32 v0, v0, v104, v105
	v_max3_f32 v0, v0, v106, v107
	v_max3_f32 v0, v0, v108, v109
	v_max3_f32 v0, v0, v110, v111
	v_max3_f32 v0, v0, v112, v113
	v_max_f32_e32 v177, v177, v0
	v_mov_b32_e32 v0, v177
	v_mov_b32_e32 v221, 1.0
	s_nop 0
	v_permlane32_swap_b32_e32 v177, v0
	v_max_f32_e32 v177, v177, v0
	v_cmp_ge_f32_e32 vcc, s90, v177
	s_cmp_eq_u64 vcc, exec
	s_cbranch_scc0 .Lmla_h0_newmax
.Lmla_h0_cont:
	ds_read_b128 v[82:85], v215 offset:51200
	ds_read_b128 v[86:89], v216 offset:51200
	ds_read_b128 v[222:225], v215 offset:55296
	ds_read_b128 v[226:229], v216 offset:55296
	s_add_i32 m0, s98, 0x0
	s_nop 0
	global_load_lds_dwordx4 v176, s[18:19]
	s_add_i32 m0, s98, 0x4000
	s_nop 0
	global_load_lds_dwordx4 v178, s[16:17]
	s_add_i32 m0, s98, 0x8000
	s_nop 0
	global_load_lds_dwordx4 v[180:181], off
	v_add_u32_e32 v176, 0x2000, v176
	v_add_u32_e32 v178, 0x20000, v178
	s_mov_b64 s[20:21], 0x1000
	v_lshl_add_u64 v[180:181], v[180:181], 0, s[20:21]
	v_exp_f32_e32 v0, v114
	v_exp_f32_e32 v177, v115
	v_exp_f32_e32 v179, v116
	v_exp_f32_e32 v254, v117
	v_add_f32_e32 v219, v0, v177
	v_cvt_pk_fp8_f32 v246, v0, v177
	v_add_f32_e32 v219, v179, v219
	v_add_f32_e32 v219, v254, v219
	v_cvt_pk_fp8_f32 v246, v179, v254 op_sel:[0,0,1]
	s_waitcnt lgkmcnt(2)
	v_mfma_scale_f32_32x32x64_f8f6f4 v[82:97], v[82:89], v[146:153], v[230:245], v194, v193 op_sel_hi:[0,0,0]
	v_exp_f32_e32 v0, v118
	v_exp_f32_e32 v177, v119
	v_exp_f32_e32 v179, v120
	v_exp_f32_e32 v254, v121
	v_add_f32_e32 v219, v0, v219
	v_add_f32_e32 v219, v177, v219
	v_cvt_pk_fp8_f32 v247, v0, v177
	v_add_f32_e32 v219, v179, v219
	v_add_f32_e32 v219, v254, v219
	v_cvt_pk_fp8_f32 v247, v179, v254 op_sel:[0,0,1]
	ds_read_b128 v[114:117], v213 offset:51200
	ds_read_b128 v[118:121], v214 offset:51200
	s_waitcnt lgkmcnt(2)
	v_mfma_scale_f32_32x32x64_f8f6f4 v[66:81], v[222:229], v[146:153], v[230:245], v194, v193 op_sel_hi:[0,0,0]
	ds_read_b128 v[222:225], v213 offset:55296
	ds_read_b128 v[226:229], v214 offset:55296
	v_exp_f32_e32 v0, v122
	v_exp_f32_e32 v177, v123
	v_exp_f32_e32 v179, v124
	v_exp_f32_e32 v254, v125
	v_add_f32_e32 v219, v0, v219
	v_add_f32_e32 v219, v177, v219
	v_cvt_pk_fp8_f32 v248, v0, v177
	v_add_f32_e32 v219, v179, v219
	v_add_f32_e32 v219, v254, v219
	v_cvt_pk_fp8_f32 v248, v179, v254 op_sel:[0,0,1]
	v_exp_f32_e32 v0, v126
	v_exp_f32_e32 v177, v127
	v_exp_f32_e32 v179, v128
	v_exp_f32_e32 v254, v129
	v_add_f32_e32 v219, v0, v219
	v_add_f32_e32 v219, v177, v219
	v_cvt_pk_fp8_f32 v249, v0, v177
	v_add_f32_e32 v219, v179, v219
	v_add_f32_e32 v219, v254, v219
	v_cvt_pk_fp8_f32 v249, v179, v254 op_sel:[0,0,1]
	ds_read_b128 v[122:125], v185 offset:59392
	ds_read_b128 v[126:129], v186 offset:59392
	s_waitcnt lgkmcnt(4)
; __device__ __forceinline__ void finishSM9(f32x16& p0, f32x16& p1, float alpha, float& l_reg, v8i32& p8) {
; #pragma unroll
;   for (int r = 0; r < 16; ++r) { p0[r] = __builtin_amdgcn_exp2f(p0[r]); p1[r] = __builtin_amdgcn_exp2f(p1[r]); }
;   float ps = 0;
; #pragma unroll
;   for (int r = 0; r < 16; ++r) ps += p0[r];
; #pragma unroll
;   for (int r = 0; r < 16; ++r) ps += p1[r];
;   { auto rr = __builtin_amdgcn_permlane32_swap(__float_as_uint(ps), __float_as_uint(ps), false, false);
;     ps = __uint_as_float(rr[0]) + __uint_as_float(rr[1]); }
;   l_reg = l_reg * alpha + ps;
; #pragma unroll
;   for (int g = 0; g < 4; ++g) {
;     int w = __builtin_amdgcn_cvt_pk_fp8_f32(p0[4 * g], p0[4 * g + 1], 0, false); p8[g] = __builtin_amdgcn_cvt_pk_fp8_f32(p0[4 * g + 2], p0[4 * g + 3], w, true);
;     int u = __builtin_amdgcn_cvt_pk_fp8_f32(p1[4 * g], p1[4 * g + 1], 0, false); p8[4 + g] = __builtin_amdgcn_cvt_pk_fp8_f32(p1[4 * g + 2], p1[4 * g + 3], u, true); }
; }
; __device__ __forceinline__ void pv8(f32x16* o, const char* Vt, const v8i32 p8, int r32, int hi) {
;   const int sw = (r32 >> 2) & 3, a0 = r32 * 64 + (((hi * 2) ^ sw) << 4), a1 = r32 * 64 + (((hi * 2 + 1) ^ sw) << 4);
; #pragma unroll
;   for (int d0 = 0; d0 < 4; ++d0) {
;     const v8i32 vf = cat8(*reinterpret_cast<const v4i32*>(Vt + d0 * 2048 + a0), *reinterpret_cast<const v4i32*>(Vt + d0 * 2048 + a1));
;     o[d0] = __builtin_amdgcn_mfma_scale_f32_32x32x64_f8f6f4(p8, vf, o[d0], 0, 0, 0, 127, 0, 127); }
; }
; __device__ __forceinline__ void qkt9(f32x16& p0, f32x16& p1, const char* Kn, const char* Kr, const v8i32* qf, const float init, int r32, int hi) {
; #pragma unroll
;   for (int r = 0; r < 16; ++r) { p0[r] = init; p1[r] = init; }
; #pragma unroll
;   for (int s = 0; s < 2; ++s) { const int c0 = s * 4 + hi * 2;
;     const v8i32 a0 = cat8(*reinterpret_cast<const v4i32*>(Kn + KN8SW(r32, c0)), *reinterpret_cast<const v4i32*>(Kn + KN8SW(r32, c0 + 1)));
;     const v8i32 a1 = cat8(*reinterpret_cast<const v4i32*>(Kn + 4096 + KN8SW(r32, c0)), *reinterpret_cast<const v4i32*>(Kn + 4096 + KN8SW(r32, c0 + 1)));
;     p0 = __builtin_amdgcn_mfma_scale_f32_32x32x64_f8f6f4(a0, qf[s], p0, 0, 0, 0, 127, 0, 124);
;     p1 = __builtin_amdgcn_mfma_scale_f32_32x32x64_f8f6f4(a1, qf[s], p1, 0, 0, 0, 127, 0, 124); }
;   { const int c0 = hi * 2;
	v_mfma_scale_f32_32x32x64_f8f6f4 v[82:97], v[114:121], v[138:145], v[82:97], v194, v193 op_sel_hi:[0,0,0]
	v_exp_f32_e32 v0, v98
	v_exp_f32_e32 v177, v99
	v_exp_f32_e32 v179, v100
	v_exp_f32_e32 v254, v101
	v_add_f32_e32 v219, v0, v219
	v_add_f32_e32 v219, v177, v219
	v_cvt_pk_fp8_f32 v250, v0, v177
	v_add_f32_e32 v219, v179, v219
	v_add_f32_e32 v219, v254, v219
	v_cvt_pk_fp8_f32 v250, v179, v254 op_sel:[0,0,1]
	s_waitcnt lgkmcnt(2)
	v_mfma_scale_f32_32x32x64_f8f6f4 v[66:81], v[222:229], v[138:145], v[66:81], v194, v193 op_sel_hi:[0,0,0]
	ds_read_b128 v[222:225], v185 offset:61440
	ds_read_b128 v[226:229], v186 offset:61440
	v_exp_f32_e32 v0, v102
	v_exp_f32_e32 v177, v103
	v_exp_f32_e32 v179, v104
	v_exp_f32_e32 v254, v105
	v_add_f32_e32 v219, v0, v219
	v_add_f32_e32 v219, v177, v219
	v_cvt_pk_fp8_f32 v251, v0, v177
	v_add_f32_e32 v219, v179, v219
	v_add_f32_e32 v219, v254, v219
	v_cvt_pk_fp8_f32 v251, v179, v254 op_sel:[0,0,1]
	v_exp_f32_e32 v0, v106
	v_exp_f32_e32 v177, v107
	v_exp_f32_e32 v179, v108
	v_exp_f32_e32 v254, v109
	v_add_f32_e32 v219, v0, v219
	v_add_f32_e32 v219, v177, v219
	v_cvt_pk_fp8_f32 v252, v0, v177
	v_add_f32_e32 v219, v179, v219
	v_add_f32_e32 v219, v254, v219
	v_cvt_pk_fp8_f32 v252, v179, v254 op_sel:[0,0,1]
	s_waitcnt lgkmcnt(2)
	v_mfma_scale_f32_32x32x64_f8f6f4 v[82:97], v[122:129], v[130:137], v[82:97], v194, v193 op_sel_hi:[0,0,0]
	v_exp_f32_e32 v0, v110
	v_exp_f32_e32 v177, v111
	v_exp_f32_e32 v179, v112
	v_exp_f32_e32 v254, v113
	v_add_f32_e32 v219, v0, v219
	v_add_f32_e32 v219, v177, v219
	v_cvt_pk_fp8_f32 v253, v0, v177
	v_add_f32_e32 v219, v179, v219
	v_add_f32_e32 v219, v254, v219
	v_cvt_pk_fp8_f32 v253, v179, v254 op_sel:[0,0,1]
	ds_read_b128 v[122:125], v185 offset:8192
	ds_read_b128 v[126:129], v186 offset:8192
	ds_read_b128 v[114:117], v185 offset:10240
	ds_read_b128 v[118:121], v186 offset:10240
	ds_read_b128 v[106:109], v185 offset:12288
	ds_read_b128 v[110:113], v186 offset:12288
	ds_read_b128 v[98:101], v185 offset:14336
	ds_read_b128 v[102:105], v186 offset:14336
	s_waitcnt lgkmcnt(8)
	v_mfma_scale_f32_32x32x64_f8f6f4 v[66:81], v[222:229], v[130:137], v[66:81], v194, v193 op_sel_hi:[0,0,0]
	v_mov_b32_e32 v0, v219
	s_nop 1
	v_permlane32_swap_b32_e32 v219, v0
	v_add_f32_e32 v219, v219, v0
	v_fma_f32 v209, v209, v221, v219
	v_max_f32_e32 v177, v82, v83
	v_max3_f32 v177, v177, v84, v85
	v_max3_f32 v177, v177, v86, v87
	v_max3_f32 v177, v177, v88, v89
	v_max3_f32 v177, v177, v90, v91
	v_max3_f32 v177, v177, v92, v93
	v_max3_f32 v177, v177, v94, v95
	v_max3_f32 v177, v177, v96, v97
	s_waitcnt lgkmcnt(6)
	v_mfma_scale_f32_32x32x64_f8f6f4 v[50:65], v[246:253], v[122:129], v[50:65], v194, v194 op_sel_hi:[0,0,0]
	s_waitcnt lgkmcnt(4)
	v_mfma_scale_f32_32x32x64_f8f6f4 v[34:49], v[246:253], v[114:121], v[34:49], v194, v194 op_sel_hi:[0,0,0]
	s_waitcnt lgkmcnt(2)
	v_mfma_scale_f32_32x32x64_f8f6f4 v[18:33], v[246:253], v[106:113], v[18:33], v194, v194 op_sel_hi:[0,0,0]
	s_waitcnt lgkmcnt(0)
	v_mfma_scale_f32_32x32x64_f8f6f4 v[2:17], v[246:253], v[98:105], v[2:17], v194, v194 op_sel_hi:[0,0,0]
	s_waitcnt vmcnt(0)
	s_waitcnt lgkmcnt(0)
	s_barrier
	v_max_f32_e32 v0, v66, v67
	v_max3_f32 v0, v0, v68, v69
	v_max3_f32 v0, v0, v70, v71
	v_max3_f32 v0, v0, v72, v73
	v_max3_f32 v0, v0, v74, v75
	v_max3_f32 v0, v0, v76, v77
	v_max3_f32 v0, v0, v78, v79
	v_max3_f32 v0, v0, v80, v81
	v_max_f32_e32 v177, v177, v0
	v_mov_b32_e32 v0, v177
	v_mov_b32_e32 v218, 1.0
	s_nop 0
	v_permlane32_swap_b32_e32 v177, v0
	v_max_f32_e32 v177, v177, v0
	v_cmp_ge_f32_e32 vcc, s90, v177
	s_cmp_eq_u64 vcc, exec
	s_cbranch_scc0 .Lmla_h1_newmax
.Lmla_h1_cont:
	ds_read_b128 v[114:117], v215 offset:16384
	ds_read_b128 v[118:121], v216 offset:16384
	ds_read_b128 v[222:225], v215 offset:20480
	ds_read_b128 v[226:229], v216 offset:20480
	s_add_i32 m0, s98, 0x2000
	s_nop 0
	global_load_lds_dwordx4 v176, s[18:19]
	s_add_i32 m0, s98, 0x6000
	s_nop 0
	global_load_lds_dwordx4 v178, s[16:17]
	s_add_i32 m0, s98, 0x9000
	s_nop 0
	global_load_lds_dwordx4 v[180:181], off
	v_add_u32_e32 v176, 0x2000, v176
	v_add_u32_e32 v178, 0x20000, v178
	s_mov_b64 s[20:21], 0x1000
	v_lshl_add_u64 v[180:181], v[180:181], 0, s[20:21]
	v_exp_f32_e32 v0, v82
	v_exp_f32_e32 v177, v83
	v_exp_f32_e32 v179, v84
	v_exp_f32_e32 v254, v85
	v_add_f32_e32 v219, v0, v177
	v_cvt_pk_fp8_f32 v246, v0, v177
	v_add_f32_e32 v219, v179, v219
	v_add_f32_e32 v219, v254, v219
	v_cvt_pk_fp8_f32 v246, v179, v254 op_sel:[0,0,1]
	s_waitcnt lgkmcnt(2)
	v_mfma_scale_f32_32x32x64_f8f6f4 v[114:129], v[114:121], v[146:153], v[230:245], v194, v193 op_sel_hi:[0,0,0]
	v_exp_f32_e32 v0, v86
	v_exp_f32_e32 v177, v87
	v_exp_f32_e32 v179, v88
	v_exp_f32_e32 v254, v89
	v_add_f32_e32 v219, v0, v219
	v_add_f32_e32 v219, v177, v219
	v_cvt_pk_fp8_f32 v247, v0, v177
	v_add_f32_e32 v219, v179, v219
	v_add_f32_e32 v219, v254, v219
	v_cvt_pk_fp8_f32 v247, v179, v254 op_sel:[0,0,1]
	ds_read_b128 v[82:85], v213 offset:16384
	ds_read_b128 v[86:89], v214 offset:16384
	s_waitcnt lgkmcnt(2)
	v_mfma_scale_f32_32x32x64_f8f6f4 v[98:113], v[222:229], v[146:153], v[230:245], v194, v193 op_sel_hi:[0,0,0]
	ds_read_b128 v[222:225], v213 offset:20480
	ds_read_b128 v[226:229], v214 offset:20480
	v_exp_f32_e32 v0, v90
	v_exp_f32_e32 v177, v91
	v_exp_f32_e32 v179, v92
	v_exp_f32_e32 v254, v93
	v_add_f32_e32 v219, v0, v219
	v_add_f32_e32 v219, v177, v219
	v_cvt_pk_fp8_f32 v248, v0, v177
	v_add_f32_e32 v219, v179, v219
	v_add_f32_e32 v219, v254, v219
	v_cvt_pk_fp8_f32 v248, v179, v254 op_sel:[0,0,1]
	v_exp_f32_e32 v0, v94
	v_exp_f32_e32 v177, v95
	v_exp_f32_e32 v179, v96
	v_exp_f32_e32 v254, v97
	v_add_f32_e32 v219, v0, v219
	v_add_f32_e32 v219, v177, v219
	v_cvt_pk_fp8_f32 v249, v0, v177
	v_add_f32_e32 v219, v179, v219
	v_add_f32_e32 v219, v254, v219
	v_cvt_pk_fp8_f32 v249, v179, v254 op_sel:[0,0,1]
	ds_read_b128 v[90:93], v185 offset:32768
	ds_read_b128 v[94:97], v186 offset:32768
	s_waitcnt lgkmcnt(4)
; __device__ __forceinline__ void finishSM9(f32x16& p0, f32x16& p1, float alpha, float& l_reg, v8i32& p8) {
; #pragma unroll
;   for (int r = 0; r < 16; ++r) { p0[r] = __builtin_amdgcn_exp2f(p0[r]); p1[r] = __builtin_amdgcn_exp2f(p1[r]); }
;   float ps = 0;
; #pragma unroll
;   for (int r = 0; r < 16; ++r) ps += p0[r];
; #pragma unroll
;   for (int r = 0; r < 16; ++r) ps += p1[r];
;   { auto rr = __builtin_amdgcn_permlane32_swap(__float_as_uint(ps), __float_as_uint(ps), false, false);
;     ps = __uint_as_float(rr[0]) + __uint_as_float(rr[1]); }
;   l_reg = l_reg * alpha + ps;
; #pragma unroll
;   for (int g = 0; g < 4; ++g) {
;     int w = __builtin_amdgcn_cvt_pk_fp8_f32(p0[4 * g], p0[4 * g + 1], 0, false); p8[g] = __builtin_amdgcn_cvt_pk_fp8_f32(p0[4 * g + 2], p0[4 * g + 3], w, true);
;     int u = __builtin_amdgcn_cvt_pk_fp8_f32(p1[4 * g], p1[4 * g + 1], 0, false); p8[4 + g] = __builtin_amdgcn_cvt_pk_fp8_f32(p1[4 * g + 2], p1[4 * g + 3], u, true); }
; }
; __device__ __forceinline__ void pv8(f32x16* o, const char* Vt, const v8i32 p8, int r32, int hi) {
;   const int sw = (r32 >> 2) & 3, a0 = r32 * 64 + (((hi * 2) ^ sw) << 4), a1 = r32 * 64 + (((hi * 2 + 1) ^ sw) << 4);
; #pragma unroll
;   for (int d0 = 0; d0 < 4; ++d0) {
;     const v8i32 vf = cat8(*reinterpret_cast<const v4i32*>(Vt + d0 * 2048 + a0), *reinterpret_cast<const v4i32*>(Vt + d0 * 2048 + a1));
;     o[d0] = __builtin_amdgcn_mfma_scale_f32_32x32x64_f8f6f4(p8, vf, o[d0], 0, 0, 0, 127, 0, 127); }
; }
; __device__ __forceinline__ void qkt9(f32x16& p0, f32x16& p1, const char* Kn, const char* Kr, const v8i32* qf, const float init, int r32, int hi) {
; #pragma unroll
;   for (int r = 0; r < 16; ++r) { p0[r] = init; p1[r] = init; }
; #pragma unroll
;   for (int s = 0; s < 2; ++s) { const int c0 = s * 4 + hi * 2;
;     const v8i32 a0 = cat8(*reinterpret_cast<const v4i32*>(Kn + KN8SW(r32, c0)), *reinterpret_cast<const v4i32*>(Kn + KN8SW(r32, c0 + 1)));
;     const v8i32 a1 = cat8(*reinterpret_cast<const v4i32*>(Kn + 4096 + KN8SW(r32, c0)), *reinterpret_cast<const v4i32*>(Kn + 4096 + KN8SW(r32, c0 + 1)));
;     p0 = __builtin_amdgcn_mfma_scale_f32_32x32x64_f8f6f4(a0, qf[s], p0, 0, 0, 0, 127, 0, 124);
;     p1 = __builtin_amdgcn_mfma_scale_f32_32x32x64_f8f6f4(a1, qf[s], p1, 0, 0, 0, 127, 0, 124); }
;   { const int c0 = hi * 2;
	v_mfma_scale_f32_32x32x64_f8f6f4 v[114:129], v[82:89], v[138:145], v[114:129], v194, v193 op_sel_hi:[0,0,0]
	v_exp_f32_e32 v0, v66
	v_exp_f32_e32 v177, v67
	v_exp_f32_e32 v179, v68
	v_exp_f32_e32 v254, v69
	v_add_f32_e32 v219, v0, v219
	v_add_f32_e32 v219, v177, v219
	v_cvt_pk_fp8_f32 v250, v0, v177
	v_add_f32_e32 v219, v179, v219
	v_add_f32_e32 v219, v254, v219
	v_cvt_pk_fp8_f32 v250, v179, v254 op_sel:[0,0,1]
	s_waitcnt lgkmcnt(2)
	v_mfma_scale_f32_32x32x64_f8f6f4 v[98:113], v[222:229], v[138:145], v[98:113], v194, v193 op_sel_hi:[0,0,0]
	ds_read_b128 v[222:225], v185 offset:34816
	ds_read_b128 v[226:229], v186 offset:34816
	v_exp_f32_e32 v0, v70
	v_exp_f32_e32 v177, v71
	v_exp_f32_e32 v179, v72
	v_exp_f32_e32 v254, v73
	v_add_f32_e32 v219, v0, v219
	v_add_f32_e32 v219, v177, v219
	v_cvt_pk_fp8_f32 v251, v0, v177
	v_add_f32_e32 v219, v179, v219
	v_add_f32_e32 v219, v254, v219
	v_cvt_pk_fp8_f32 v251, v179, v254 op_sel:[0,0,1]
	v_exp_f32_e32 v0, v74
	v_exp_f32_e32 v177, v75
	v_exp_f32_e32 v179, v76
	v_exp_f32_e32 v254, v77
	v_add_f32_e32 v219, v0, v219
	v_add_f32_e32 v219, v177, v219
	v_cvt_pk_fp8_f32 v252, v0, v177
	v_add_f32_e32 v219, v179, v219
	v_add_f32_e32 v219, v254, v219
	v_cvt_pk_fp8_f32 v252, v179, v254 op_sel:[0,0,1]
	s_waitcnt lgkmcnt(2)
	v_mfma_scale_f32_32x32x64_f8f6f4 v[114:129], v[90:97], v[130:137], v[114:129], v194, v193 op_sel_hi:[0,0,0]
	v_exp_f32_e32 v0, v78
	v_exp_f32_e32 v177, v79
	v_exp_f32_e32 v179, v80
	v_exp_f32_e32 v254, v81
	v_add_f32_e32 v219, v0, v219
	v_add_f32_e32 v219, v177, v219
	v_cvt_pk_fp8_f32 v253, v0, v177
	v_add_f32_e32 v219, v179, v219
	v_add_f32_e32 v219, v254, v219
	v_cvt_pk_fp8_f32 v253, v179, v254 op_sel:[0,0,1]
	ds_read_b128 v[90:93], v185 offset:43008
	ds_read_b128 v[94:97], v186 offset:43008
	ds_read_b128 v[82:85], v185 offset:45056
	ds_read_b128 v[86:89], v186 offset:45056
	ds_read_b128 v[74:77], v185 offset:47104
	ds_read_b128 v[78:81], v186 offset:47104
	ds_read_b128 v[66:69], v185 offset:49152
	ds_read_b128 v[70:73], v186 offset:49152
	s_waitcnt lgkmcnt(8)
	v_mfma_scale_f32_32x32x64_f8f6f4 v[98:113], v[222:229], v[130:137], v[98:113], v194, v193 op_sel_hi:[0,0,0]
	v_mov_b32_e32 v0, v219
	s_nop 1
	v_permlane32_swap_b32_e32 v219, v0
	v_add_f32_e32 v219, v219, v0
	v_fma_f32 v209, v209, v218, v219
	v_max_f32_e32 v177, v114, v115
	v_max3_f32 v177, v177, v116, v117
	v_max3_f32 v177, v177, v118, v119
	v_max3_f32 v177, v177, v120, v121
	v_max3_f32 v177, v177, v122, v123
	v_max3_f32 v177, v177, v124, v125
	v_max3_f32 v177, v177, v126, v127
	v_max3_f32 v177, v177, v128, v129
	s_waitcnt lgkmcnt(6)
	v_mfma_scale_f32_32x32x64_f8f6f4 v[50:65], v[246:253], v[90:97], v[50:65], v194, v194 op_sel_hi:[0,0,0]
	s_waitcnt lgkmcnt(4)
	v_mfma_scale_f32_32x32x64_f8f6f4 v[34:49], v[246:253], v[82:89], v[34:49], v194, v194 op_sel_hi:[0,0,0]
	s_waitcnt lgkmcnt(2)
	v_mfma_scale_f32_32x32x64_f8f6f4 v[18:33], v[246:253], v[74:81], v[18:33], v194, v194 op_sel_hi:[0,0,0]
	s_waitcnt lgkmcnt(0)
	v_mfma_scale_f32_32x32x64_f8f6f4 v[2:17], v[246:253], v[66:73], v[2:17], v194, v194 op_sel_hi:[0,0,0]
	s_waitcnt vmcnt(0)
	s_waitcnt lgkmcnt(0)
	s_barrier
	v_max_f32_e32 v0, v98, v99
	v_max3_f32 v0, v0, v100, v101
	v_max3_f32 v0, v0, v102, v103
	v_max3_f32 v0, v0, v104, v105
	v_max3_f32 v0, v0, v106, v107
	v_max3_f32 v0, v0, v108, v109
	v_max3_f32 v0, v0, v110, v111
	v_max3_f32 v0, v0, v112, v113
	v_max_f32_e32 v177, v177, v0
	v_mov_b32_e32 v0, v177
	v_mov_b32_e32 v221, 1.0
	s_nop 0
	v_permlane32_swap_b32_e32 v177, v0
	v_max_f32_e32 v177, v177, v0
	v_cmp_ge_f32_e32 vcc, s90, v177
	s_cmp_eq_u64 vcc, exec
	s_cbranch_scc0 .Lmla_h2_newmax
.Lmla_h2_cont:
	ds_read_b128 v[82:85], v215 offset:24576
	ds_read_b128 v[86:89], v216 offset:24576
	ds_read_b128 v[222:225], v215 offset:28672
	ds_read_b128 v[226:229], v216 offset:28672
	s_add_i32 m0, s98, 0xa800
	s_nop 0
	global_load_lds_dwordx4 v176, s[18:19]
	s_add_i32 m0, s98, 0xc800
	s_nop 0
	global_load_lds_dwordx4 v178, s[16:17]
	s_add_i32 m0, s98, 0xe800
	s_nop 0
	global_load_lds_dwordx4 v[180:181], off
	v_add_u32_e32 v176, 0x2000, v176
	v_add_u32_e32 v178, 0x20000, v178
	s_mov_b64 s[20:21], 0x1000
	v_lshl_add_u64 v[180:181], v[180:181], 0, s[20:21]
	v_exp_f32_e32 v0, v114
	v_exp_f32_e32 v177, v115
	v_exp_f32_e32 v179, v116
	v_exp_f32_e32 v254, v117
	v_add_f32_e32 v219, v0, v177
	v_cvt_pk_fp8_f32 v246, v0, v177
	v_add_f32_e32 v219, v179, v219
	v_add_f32_e32 v219, v254, v219
	v_cvt_pk_fp8_f32 v246, v179, v254 op_sel:[0,0,1]
	s_waitcnt lgkmcnt(2)
	v_mfma_scale_f32_32x32x64_f8f6f4 v[82:97], v[82:89], v[146:153], v[230:245], v194, v193 op_sel_hi:[0,0,0]
	v_exp_f32_e32 v0, v118
	v_exp_f32_e32 v177, v119
	v_exp_f32_e32 v179, v120
	v_exp_f32_e32 v254, v121
	v_add_f32_e32 v219, v0, v219
	v_add_f32_e32 v219, v177, v219
	v_cvt_pk_fp8_f32 v247, v0, v177
	v_add_f32_e32 v219, v179, v219
	v_add_f32_e32 v219, v254, v219
	v_cvt_pk_fp8_f32 v247, v179, v254 op_sel:[0,0,1]
	ds_read_b128 v[114:117], v213 offset:24576
	ds_read_b128 v[118:121], v214 offset:24576
	s_waitcnt lgkmcnt(2)
	v_mfma_scale_f32_32x32x64_f8f6f4 v[66:81], v[222:229], v[146:153], v[230:245], v194, v193 op_sel_hi:[0,0,0]
	ds_read_b128 v[222:225], v213 offset:28672
	ds_read_b128 v[226:229], v214 offset:28672
	v_exp_f32_e32 v0, v122
	v_exp_f32_e32 v177, v123
	v_exp_f32_e32 v179, v124
	v_exp_f32_e32 v254, v125
	v_add_f32_e32 v219, v0, v219
	v_add_f32_e32 v219, v177, v219
	v_cvt_pk_fp8_f32 v248, v0, v177
	v_add_f32_e32 v219, v179, v219
	v_add_f32_e32 v219, v254, v219
	v_cvt_pk_fp8_f32 v248, v179, v254 op_sel:[0,0,1]
	v_exp_f32_e32 v0, v126
	v_exp_f32_e32 v177, v127
	v_exp_f32_e32 v179, v128
	v_exp_f32_e32 v254, v129
	v_add_f32_e32 v219, v0, v219
	v_add_f32_e32 v219, v177, v219
	v_cvt_pk_fp8_f32 v249, v0, v177
	v_add_f32_e32 v219, v179, v219
	v_add_f32_e32 v219, v254, v219
	v_cvt_pk_fp8_f32 v249, v179, v254 op_sel:[0,0,1]
	ds_read_b128 v[122:125], v185 offset:36864
	ds_read_b128 v[126:129], v186 offset:36864
	s_waitcnt lgkmcnt(4)
; __device__ __forceinline__ void finishSM9(f32x16& p0, f32x16& p1, float alpha, float& l_reg, v8i32& p8) {
; #pragma unroll
;   for (int r = 0; r < 16; ++r) { p0[r] = __builtin_amdgcn_exp2f(p0[r]); p1[r] = __builtin_amdgcn_exp2f(p1[r]); }
;   float ps = 0;
; #pragma unroll
;   for (int r = 0; r < 16; ++r) ps += p0[r];
; #pragma unroll
;   for (int r = 0; r < 16; ++r) ps += p1[r];
;   { auto rr = __builtin_amdgcn_permlane32_swap(__float_as_uint(ps), __float_as_uint(ps), false, false);
;     ps = __uint_as_float(rr[0]) + __uint_as_float(rr[1]); }
;   l_reg = l_reg * alpha + ps;
; #pragma unroll
;   for (int g = 0; g < 4; ++g) {
;     int w = __builtin_amdgcn_cvt_pk_fp8_f32(p0[4 * g], p0[4 * g + 1], 0, false); p8[g] = __builtin_amdgcn_cvt_pk_fp8_f32(p0[4 * g + 2], p0[4 * g + 3], w, true);
;     int u = __builtin_amdgcn_cvt_pk_fp8_f32(p1[4 * g], p1[4 * g + 1], 0, false); p8[4 + g] = __builtin_amdgcn_cvt_pk_fp8_f32(p1[4 * g + 2], p1[4 * g + 3], u, true); }
; }
; __device__ __forceinline__ void pv8(f32x16* o, const char* Vt, const v8i32 p8, int r32, int hi) {
;   const int sw = (r32 >> 2) & 3, a0 = r32 * 64 + (((hi * 2) ^ sw) << 4), a1 = r32 * 64 + (((hi * 2 + 1) ^ sw) << 4);
; #pragma unroll
;   for (int d0 = 0; d0 < 4; ++d0) {
;     const v8i32 vf = cat8(*reinterpret_cast<const v4i32*>(Vt + d0 * 2048 + a0), *reinterpret_cast<const v4i32*>(Vt + d0 * 2048 + a1));
;     o[d0] = __builtin_amdgcn_mfma_scale_f32_32x32x64_f8f6f4(p8, vf, o[d0], 0, 0, 0, 127, 0, 127); }
; }
; __device__ __forceinline__ void qkt9(f32x16& p0, f32x16& p1, const char* Kn, const char* Kr, const v8i32* qf, const float init, int r32, int hi) {
; #pragma unroll
;   for (int r = 0; r < 16; ++r) { p0[r] = init; p1[r] = init; }
; #pragma unroll
;   for (int s = 0; s < 2; ++s) { const int c0 = s * 4 + hi * 2;
;     const v8i32 a0 = cat8(*reinterpret_cast<const v4i32*>(Kn + KN8SW(r32, c0)), *reinterpret_cast<const v4i32*>(Kn + KN8SW(r32, c0 + 1)));
;     const v8i32 a1 = cat8(*reinterpret_cast<const v4i32*>(Kn + 4096 + KN8SW(r32, c0)), *reinterpret_cast<const v4i32*>(Kn + 4096 + KN8SW(r32, c0 + 1)));
;     p0 = __builtin_amdgcn_mfma_scale_f32_32x32x64_f8f6f4(a0, qf[s], p0, 0, 0, 0, 127, 0, 124);
;     p1 = __builtin_amdgcn_mfma_scale_f32_32x32x64_f8f6f4(a1, qf[s], p1, 0, 0, 0, 127, 0, 124); }
;   { const int c0 = hi * 2;
	v_mfma_scale_f32_32x32x64_f8f6f4 v[82:97], v[114:121], v[138:145], v[82:97], v194, v193 op_sel_hi:[0,0,0]
	v_exp_f32_e32 v0, v98
	v_exp_f32_e32 v177, v99
	v_exp_f32_e32 v179, v100
	v_exp_f32_e32 v254, v101
	v_add_f32_e32 v219, v0, v219
	v_add_f32_e32 v219, v177, v219
	v_cvt_pk_fp8_f32 v250, v0, v177
	v_add_f32_e32 v219, v179, v219
	v_add_f32_e32 v219, v254, v219
	v_cvt_pk_fp8_f32 v250, v179, v254 op_sel:[0,0,1]
	s_waitcnt lgkmcnt(2)
	v_mfma_scale_f32_32x32x64_f8f6f4 v[66:81], v[222:229], v[138:145], v[66:81], v194, v193 op_sel_hi:[0,0,0]
	ds_read_b128 v[222:225], v185 offset:38912
	ds_read_b128 v[226:229], v186 offset:38912
	v_exp_f32_e32 v0, v102
	v_exp_f32_e32 v177, v103
	v_exp_f32_e32 v179, v104
	v_exp_f32_e32 v254, v105
	v_add_f32_e32 v219, v0, v219
	v_add_f32_e32 v219, v177, v219
	v_cvt_pk_fp8_f32 v251, v0, v177
	v_add_f32_e32 v219, v179, v219
	v_add_f32_e32 v219, v254, v219
	v_cvt_pk_fp8_f32 v251, v179, v254 op_sel:[0,0,1]
	v_exp_f32_e32 v0, v106
	v_exp_f32_e32 v177, v107
	v_exp_f32_e32 v179, v108
	v_exp_f32_e32 v254, v109
	v_add_f32_e32 v219, v0, v219
	v_add_f32_e32 v219, v177, v219
	v_cvt_pk_fp8_f32 v252, v0, v177
	v_add_f32_e32 v219, v179, v219
	v_add_f32_e32 v219, v254, v219
	v_cvt_pk_fp8_f32 v252, v179, v254 op_sel:[0,0,1]
	s_waitcnt lgkmcnt(2)
	v_mfma_scale_f32_32x32x64_f8f6f4 v[82:97], v[122:129], v[130:137], v[82:97], v194, v193 op_sel_hi:[0,0,0]
	v_exp_f32_e32 v0, v110
	v_exp_f32_e32 v177, v111
	v_exp_f32_e32 v179, v112
	v_exp_f32_e32 v254, v113
	v_add_f32_e32 v219, v0, v219
	v_add_f32_e32 v219, v177, v219
	v_cvt_pk_fp8_f32 v253, v0, v177
	v_add_f32_e32 v219, v179, v219
	v_add_f32_e32 v219, v254, v219
	v_cvt_pk_fp8_f32 v253, v179, v254 op_sel:[0,0,1]
	ds_read_b128 v[122:125], v185 offset:0
	ds_read_b128 v[126:129], v186 offset:0
	ds_read_b128 v[114:117], v185 offset:2048
	ds_read_b128 v[118:121], v186 offset:2048
	ds_read_b128 v[106:109], v185 offset:4096
	ds_read_b128 v[110:113], v186 offset:4096
	ds_read_b128 v[98:101], v185 offset:6144
	ds_read_b128 v[102:105], v186 offset:6144
	s_waitcnt lgkmcnt(8)
	v_mfma_scale_f32_32x32x64_f8f6f4 v[66:81], v[222:229], v[130:137], v[66:81], v194, v193 op_sel_hi:[0,0,0]
	v_mov_b32_e32 v0, v219
	s_nop 1
	v_permlane32_swap_b32_e32 v219, v0
	v_add_f32_e32 v219, v219, v0
	v_fma_f32 v209, v209, v221, v219
	v_max_f32_e32 v177, v82, v83
	v_max3_f32 v177, v177, v84, v85
	v_max3_f32 v177, v177, v86, v87
	v_max3_f32 v177, v177, v88, v89
	v_max3_f32 v177, v177, v90, v91
	v_max3_f32 v177, v177, v92, v93
	v_max3_f32 v177, v177, v94, v95
	v_max3_f32 v177, v177, v96, v97
	s_waitcnt lgkmcnt(6)
	v_mfma_scale_f32_32x32x64_f8f6f4 v[50:65], v[246:253], v[122:129], v[50:65], v194, v194 op_sel_hi:[0,0,0]
	s_waitcnt lgkmcnt(4)
	v_mfma_scale_f32_32x32x64_f8f6f4 v[34:49], v[246:253], v[114:121], v[34:49], v194, v194 op_sel_hi:[0,0,0]
	s_waitcnt lgkmcnt(2)
	v_mfma_scale_f32_32x32x64_f8f6f4 v[18:33], v[246:253], v[106:113], v[18:33], v194, v194 op_sel_hi:[0,0,0]
	s_waitcnt lgkmcnt(0)
	v_mfma_scale_f32_32x32x64_f8f6f4 v[2:17], v[246:253], v[98:105], v[2:17], v194, v194 op_sel_hi:[0,0,0]
	s_waitcnt vmcnt(0)
	s_waitcnt lgkmcnt(0)
	s_barrier
	v_max_f32_e32 v0, v66, v67
	v_max3_f32 v0, v0, v68, v69
	v_max3_f32 v0, v0, v70, v71
	v_max3_f32 v0, v0, v72, v73
	v_max3_f32 v0, v0, v74, v75
	v_max3_f32 v0, v0, v76, v77
	v_max3_f32 v0, v0, v78, v79
	v_max3_f32 v0, v0, v80, v81
	v_max_f32_e32 v177, v177, v0
	v_mov_b32_e32 v0, v177
	v_mov_b32_e32 v218, 1.0
	s_nop 0
	v_permlane32_swap_b32_e32 v177, v0
	v_max_f32_e32 v177, v177, v0
	v_cmp_ge_f32_e32 vcc, s90, v177
	s_cmp_eq_u64 vcc, exec
	s_cbranch_scc0 .Lmla_h3_newmax
.Lmla_h3_cont:
	ds_read_b128 v[114:117], v215 offset:51200
	ds_read_b128 v[118:121], v216 offset:51200
	ds_read_b128 v[222:225], v215 offset:55296
	ds_read_b128 v[226:229], v216 offset:55296
	s_add_i32 m0, s98, 0x0
	s_nop 0
	global_load_lds_dwordx4 v176, s[18:19]
	s_add_i32 m0, s98, 0x4000
	s_nop 0
	global_load_lds_dwordx4 v178, s[16:17]
	s_add_i32 m0, s98, 0x8000
	s_nop 0
	global_load_lds_dwordx4 v[180:181], off
	v_add_u32_e32 v176, 0x2000, v176
	v_add_u32_e32 v178, 0x20000, v178
	s_mov_b64 s[20:21], 0x1000
	v_lshl_add_u64 v[180:181], v[180:181], 0, s[20:21]
	v_exp_f32_e32 v0, v82
	v_exp_f32_e32 v177, v83
	v_exp_f32_e32 v179, v84
	v_exp_f32_e32 v254, v85
	v_add_f32_e32 v219, v0, v177
	v_cvt_pk_fp8_f32 v246, v0, v177
	v_add_f32_e32 v219, v179, v219
	v_add_f32_e32 v219, v254, v219
	v_cvt_pk_fp8_f32 v246, v179, v254 op_sel:[0,0,1]
	s_waitcnt lgkmcnt(2)
	v_mfma_scale_f32_32x32x64_f8f6f4 v[114:129], v[114:121], v[146:153], v[230:245], v194, v193 op_sel_hi:[0,0,0]
	v_exp_f32_e32 v0, v86
	v_exp_f32_e32 v177, v87
	v_exp_f32_e32 v179, v88
	v_exp_f32_e32 v254, v89
	v_add_f32_e32 v219, v0, v219
	v_add_f32_e32 v219, v177, v219
	v_cvt_pk_fp8_f32 v247, v0, v177
	v_add_f32_e32 v219, v179, v219
	v_add_f32_e32 v219, v254, v219
	v_cvt_pk_fp8_f32 v247, v179, v254 op_sel:[0,0,1]
	ds_read_b128 v[82:85], v213 offset:51200
	ds_read_b128 v[86:89], v214 offset:51200
	s_waitcnt lgkmcnt(2)
	v_mfma_scale_f32_32x32x64_f8f6f4 v[98:113], v[222:229], v[146:153], v[230:245], v194, v193 op_sel_hi:[0,0,0]
	ds_read_b128 v[222:225], v213 offset:55296
	ds_read_b128 v[226:229], v214 offset:55296
	v_exp_f32_e32 v0, v90
	v_exp_f32_e32 v177, v91
	v_exp_f32_e32 v179, v92
	v_exp_f32_e32 v254, v93
	v_add_f32_e32 v219, v0, v219
	v_add_f32_e32 v219, v177, v219
	v_cvt_pk_fp8_f32 v248, v0, v177
	v_add_f32_e32 v219, v179, v219
	v_add_f32_e32 v219, v254, v219
	v_cvt_pk_fp8_f32 v248, v179, v254 op_sel:[0,0,1]
	v_exp_f32_e32 v0, v94
	v_exp_f32_e32 v177, v95
	v_exp_f32_e32 v179, v96
	v_exp_f32_e32 v254, v97
	v_add_f32_e32 v219, v0, v219
	v_add_f32_e32 v219, v177, v219
	v_cvt_pk_fp8_f32 v249, v0, v177
	v_add_f32_e32 v219, v179, v219
	v_add_f32_e32 v219, v254, v219
	v_cvt_pk_fp8_f32 v249, v179, v254 op_sel:[0,0,1]
	ds_read_b128 v[90:93], v185 offset:59392
	ds_read_b128 v[94:97], v186 offset:59392
	s_waitcnt lgkmcnt(4)
; __device__ __forceinline__ void finishSM9(f32x16& p0, f32x16& p1, float alpha, float& l_reg, v8i32& p8) {
; #pragma unroll
;   for (int r = 0; r < 16; ++r) { p0[r] = __builtin_amdgcn_exp2f(p0[r]); p1[r] = __builtin_amdgcn_exp2f(p1[r]); }
;   float ps = 0;
; #pragma unroll
;   for (int r = 0; r < 16; ++r) ps += p0[r];
; #pragma unroll
;   for (int r = 0; r < 16; ++r) ps += p1[r];
;   { auto rr = __builtin_amdgcn_permlane32_swap(__float_as_uint(ps), __float_as_uint(ps), false, false);
;     ps = __uint_as_float(rr[0]) + __uint_as_float(rr[1]); }
;   l_reg = l_reg * alpha + ps;
; #pragma unroll
;   for (int g = 0; g < 4; ++g) {
;     int w = __builtin_amdgcn_cvt_pk_fp8_f32(p0[4 * g], p0[4 * g + 1], 0, false); p8[g] = __builtin_amdgcn_cvt_pk_fp8_f32(p0[4 * g + 2], p0[4 * g + 3], w, true);
;     int u = __builtin_amdgcn_cvt_pk_fp8_f32(p1[4 * g], p1[4 * g + 1], 0, false); p8[4 + g] = __builtin_amdgcn_cvt_pk_fp8_f32(p1[4 * g + 2], p1[4 * g + 3], u, true); }
; }
; __device__ __forceinline__ void pv8(f32x16* o, const char* Vt, const v8i32 p8, int r32, int hi) {
;   const int sw = (r32 >> 2) & 3, a0 = r32 * 64 + (((hi * 2) ^ sw) << 4), a1 = r32 * 64 + (((hi * 2 + 1) ^ sw) << 4);
; #pragma unroll
;   for (int d0 = 0; d0 < 4; ++d0) {
;     const v8i32 vf = cat8(*reinterpret_cast<const v4i32*>(Vt + d0 * 2048 + a0), *reinterpret_cast<const v4i32*>(Vt + d0 * 2048 + a1));
;     o[d0] = __builtin_amdgcn_mfma_scale_f32_32x32x64_f8f6f4(p8, vf, o[d0], 0, 0, 0, 127, 0, 127); }
; }
; __device__ __forceinline__ void qkt9(f32x16& p0, f32x16& p1, const char* Kn, const char* Kr, const v8i32* qf, const float init, int r32, int hi) {
; #pragma unroll
;   for (int r = 0; r < 16; ++r) { p0[r] = init; p1[r] = init; }
; #pragma unroll
;   for (int s = 0; s < 2; ++s) { const int c0 = s * 4 + hi * 2;
;     const v8i32 a0 = cat8(*reinterpret_cast<const v4i32*>(Kn + KN8SW(r32, c0)), *reinterpret_cast<const v4i32*>(Kn + KN8SW(r32, c0 + 1)));
;     const v8i32 a1 = cat8(*reinterpret_cast<const v4i32*>(Kn + 4096 + KN8SW(r32, c0)), *reinterpret_cast<const v4i32*>(Kn + 4096 + KN8SW(r32, c0 + 1)));
;     p0 = __builtin_amdgcn_mfma_scale_f32_32x32x64_f8f6f4(a0, qf[s], p0, 0, 0, 0, 127, 0, 124);
;     p1 = __builtin_amdgcn_mfma_scale_f32_32x32x64_f8f6f4(a1, qf[s], p1, 0, 0, 0, 127, 0, 124); }
;   { const int c0 = hi * 2;
	v_mfma_scale_f32_32x32x64_f8f6f4 v[114:129], v[82:89], v[138:145], v[114:129], v194, v193 op_sel_hi:[0,0,0]
	v_exp_f32_e32 v0, v66
	v_exp_f32_e32 v177, v67
	v_exp_f32_e32 v179, v68
	v_exp_f32_e32 v254, v69
	v_add_f32_e32 v219, v0, v219
	v_add_f32_e32 v219, v177, v219
	v_cvt_pk_fp8_f32 v250, v0, v177
	v_add_f32_e32 v219, v179, v219
	v_add_f32_e32 v219, v254, v219
	v_cvt_pk_fp8_f32 v250, v179, v254 op_sel:[0,0,1]
	s_waitcnt lgkmcnt(2)
	v_mfma_scale_f32_32x32x64_f8f6f4 v[98:113], v[222:229], v[138:145], v[98:113], v194, v193 op_sel_hi:[0,0,0]
	ds_read_b128 v[222:225], v185 offset:61440
	ds_read_b128 v[226:229], v186 offset:61440
	v_exp_f32_e32 v0, v70
	v_exp_f32_e32 v177, v71
	v_exp_f32_e32 v179, v72
	v_exp_f32_e32 v254, v73
	v_add_f32_e32 v219, v0, v219
	v_add_f32_e32 v219, v177, v219
	v_cvt_pk_fp8_f32 v251, v0, v177
	v_add_f32_e32 v219, v179, v219
	v_add_f32_e32 v219, v254, v219
	v_cvt_pk_fp8_f32 v251, v179, v254 op_sel:[0,0,1]
	v_exp_f32_e32 v0, v74
	v_exp_f32_e32 v177, v75
	v_exp_f32_e32 v179, v76
	v_exp_f32_e32 v254, v77
	v_add_f32_e32 v219, v0, v219
	v_add_f32_e32 v219, v177, v219
	v_cvt_pk_fp8_f32 v252, v0, v177
	v_add_f32_e32 v219, v179, v219
	v_add_f32_e32 v219, v254, v219
	v_cvt_pk_fp8_f32 v252, v179, v254 op_sel:[0,0,1]
	s_waitcnt lgkmcnt(2)
	v_mfma_scale_f32_32x32x64_f8f6f4 v[114:129], v[90:97], v[130:137], v[114:129], v194, v193 op_sel_hi:[0,0,0]
	v_exp_f32_e32 v0, v78
	v_exp_f32_e32 v177, v79
	v_exp_f32_e32 v179, v80
	v_exp_f32_e32 v254, v81
	v_add_f32_e32 v219, v0, v219
	v_add_f32_e32 v219, v177, v219
	v_cvt_pk_fp8_f32 v253, v0, v177
	v_add_f32_e32 v219, v179, v219
	v_add_f32_e32 v219, v254, v219
	v_cvt_pk_fp8_f32 v253, v179, v254 op_sel:[0,0,1]
	ds_read_b128 v[90:93], v185 offset:8192
	ds_read_b128 v[94:97], v186 offset:8192
	ds_read_b128 v[82:85], v185 offset:10240
	ds_read_b128 v[86:89], v186 offset:10240
	ds_read_b128 v[74:77], v185 offset:12288
	ds_read_b128 v[78:81], v186 offset:12288
	ds_read_b128 v[66:69], v185 offset:14336
	ds_read_b128 v[70:73], v186 offset:14336
	s_waitcnt lgkmcnt(8)
	v_mfma_scale_f32_32x32x64_f8f6f4 v[98:113], v[222:229], v[130:137], v[98:113], v194, v193 op_sel_hi:[0,0,0]
	v_mov_b32_e32 v0, v219
	s_nop 1
	v_permlane32_swap_b32_e32 v219, v0
	v_add_f32_e32 v219, v219, v0
	v_fma_f32 v209, v209, v218, v219
	v_max_f32_e32 v177, v114, v115
	v_max3_f32 v177, v177, v116, v117
	v_max3_f32 v177, v177, v118, v119
	v_max3_f32 v177, v177, v120, v121
	v_max3_f32 v177, v177, v122, v123
	v_max3_f32 v177, v177, v124, v125
	v_max3_f32 v177, v177, v126, v127
	v_max3_f32 v177, v177, v128, v129
	s_waitcnt lgkmcnt(6)
	v_mfma_scale_f32_32x32x64_f8f6f4 v[50:65], v[246:253], v[90:97], v[50:65], v194, v194 op_sel_hi:[0,0,0]
	s_waitcnt lgkmcnt(4)
	v_mfma_scale_f32_32x32x64_f8f6f4 v[34:49], v[246:253], v[82:89], v[34:49], v194, v194 op_sel_hi:[0,0,0]
	s_waitcnt lgkmcnt(2)
	v_mfma_scale_f32_32x32x64_f8f6f4 v[18:33], v[246:253], v[74:81], v[18:33], v194, v194 op_sel_hi:[0,0,0]
	s_waitcnt lgkmcnt(0)
	v_mfma_scale_f32_32x32x64_f8f6f4 v[2:17], v[246:253], v[66:73], v[2:17], v194, v194 op_sel_hi:[0,0,0]
	s_waitcnt vmcnt(0)
	s_waitcnt lgkmcnt(0)
	s_barrier
	v_max_f32_e32 v0, v98, v99
	v_max3_f32 v0, v0, v100, v101
	v_max3_f32 v0, v0, v102, v103
	v_max3_f32 v0, v0, v104, v105
	v_max3_f32 v0, v0, v106, v107
	v_max3_f32 v0, v0, v108, v109
	v_max3_f32 v0, v0, v110, v111
	v_max3_f32 v0, v0, v112, v113
	v_max_f32_e32 v177, v177, v0
	v_mov_b32_e32 v0, v177
	v_mov_b32_e32 v221, 1.0
	s_nop 0
	v_permlane32_swap_b32_e32 v177, v0
	v_max_f32_e32 v177, v177, v0
	v_cmp_ge_f32_e32 vcc, s90, v177
	s_cmp_eq_u64 vcc, exec
	s_cbranch_scc0 .Lmla_h4_newmax
.Lmla_h4_cont:
	ds_read_b128 v[82:85], v215 offset:16384
	ds_read_b128 v[86:89], v216 offset:16384
	ds_read_b128 v[222:225], v215 offset:20480
	ds_read_b128 v[226:229], v216 offset:20480
	s_add_i32 m0, s98, 0x2000
	s_nop 0
	global_load_lds_dwordx4 v176, s[18:19]
	s_add_i32 m0, s98, 0x6000
	s_nop 0
	global_load_lds_dwordx4 v178, s[16:17]
	s_add_i32 m0, s98, 0x9000
	s_nop 0
	global_load_lds_dwordx4 v[180:181], off
	v_add_u32_e32 v176, 0x2000, v176
	v_add_u32_e32 v178, 0x20000, v178
	s_mov_b64 s[20:21], 0x1000
	v_lshl_add_u64 v[180:181], v[180:181], 0, s[20:21]
	v_exp_f32_e32 v0, v114
	v_exp_f32_e32 v177, v115
	v_exp_f32_e32 v179, v116
	v_exp_f32_e32 v254, v117
	v_add_f32_e32 v219, v0, v177
	v_cvt_pk_fp8_f32 v246, v0, v177
	v_add_f32_e32 v219, v179, v219
	v_add_f32_e32 v219, v254, v219
	v_cvt_pk_fp8_f32 v246, v179, v254 op_sel:[0,0,1]
	s_waitcnt lgkmcnt(2)
	v_mfma_scale_f32_32x32x64_f8f6f4 v[82:97], v[82:89], v[146:153], v[230:245], v194, v193 op_sel_hi:[0,0,0]
	v_exp_f32_e32 v0, v118
	v_exp_f32_e32 v177, v119
	v_exp_f32_e32 v179, v120
	v_exp_f32_e32 v254, v121
	v_add_f32_e32 v219, v0, v219
	v_add_f32_e32 v219, v177, v219
	v_cvt_pk_fp8_f32 v247, v0, v177
	v_add_f32_e32 v219, v179, v219
	v_add_f32_e32 v219, v254, v219
	v_cvt_pk_fp8_f32 v247, v179, v254 op_sel:[0,0,1]
	ds_read_b128 v[114:117], v213 offset:16384
	ds_read_b128 v[118:121], v214 offset:16384
	s_waitcnt lgkmcnt(2)
	v_mfma_scale_f32_32x32x64_f8f6f4 v[66:81], v[222:229], v[146:153], v[230:245], v194, v193 op_sel_hi:[0,0,0]
	ds_read_b128 v[222:225], v213 offset:20480
	ds_read_b128 v[226:229], v214 offset:20480
	v_exp_f32_e32 v0, v122
	v_exp_f32_e32 v177, v123
	v_exp_f32_e32 v179, v124
	v_exp_f32_e32 v254, v125
	v_add_f32_e32 v219, v0, v219
	v_add_f32_e32 v219, v177, v219
	v_cvt_pk_fp8_f32 v248, v0, v177
	v_add_f32_e32 v219, v179, v219
	v_add_f32_e32 v219, v254, v219
	v_cvt_pk_fp8_f32 v248, v179, v254 op_sel:[0,0,1]
	v_exp_f32_e32 v0, v126
	v_exp_f32_e32 v177, v127
	v_exp_f32_e32 v179, v128
	v_exp_f32_e32 v254, v129
	v_add_f32_e32 v219, v0, v219
	v_add_f32_e32 v219, v177, v219
	v_cvt_pk_fp8_f32 v249, v0, v177
	v_add_f32_e32 v219, v179, v219
	v_add_f32_e32 v219, v254, v219
	v_cvt_pk_fp8_f32 v249, v179, v254 op_sel:[0,0,1]
	ds_read_b128 v[122:125], v185 offset:32768
	ds_read_b128 v[126:129], v186 offset:32768
	s_waitcnt lgkmcnt(4)
; __device__ __forceinline__ void finishSM9(f32x16& p0, f32x16& p1, float alpha, float& l_reg, v8i32& p8) {
; #pragma unroll
;   for (int r = 0; r < 16; ++r) { p0[r] = __builtin_amdgcn_exp2f(p0[r]); p1[r] = __builtin_amdgcn_exp2f(p1[r]); }
;   float ps = 0;
; #pragma unroll
;   for (int r = 0; r < 16; ++r) ps += p0[r];
; #pragma unroll
;   for (int r = 0; r < 16; ++r) ps += p1[r];
;   { auto rr = __builtin_amdgcn_permlane32_swap(__float_as_uint(ps), __float_as_uint(ps), false, false);
;     ps = __uint_as_float(rr[0]) + __uint_as_float(rr[1]); }
;   l_reg = l_reg * alpha + ps;
; #pragma unroll
;   for (int g = 0; g < 4; ++g) {
;     int w = __builtin_amdgcn_cvt_pk_fp8_f32(p0[4 * g], p0[4 * g + 1], 0, false); p8[g] = __builtin_amdgcn_cvt_pk_fp8_f32(p0[4 * g + 2], p0[4 * g + 3], w, true);
;     int u = __builtin_amdgcn_cvt_pk_fp8_f32(p1[4 * g], p1[4 * g + 1], 0, false); p8[4 + g] = __builtin_amdgcn_cvt_pk_fp8_f32(p1[4 * g + 2], p1[4 * g + 3], u, true); }
; }
; __device__ __forceinline__ void pv8(f32x16* o, const char* Vt, const v8i32 p8, int r32, int hi) {
;   const int sw = (r32 >> 2) & 3, a0 = r32 * 64 + (((hi * 2) ^ sw) << 4), a1 = r32 * 64 + (((hi * 2 + 1) ^ sw) << 4);
; #pragma unroll
;   for (int d0 = 0; d0 < 4; ++d0) {
;     const v8i32 vf = cat8(*reinterpret_cast<const v4i32*>(Vt + d0 * 2048 + a0), *reinterpret_cast<const v4i32*>(Vt + d0 * 2048 + a1));
;     o[d0] = __builtin_amdgcn_mfma_scale_f32_32x32x64_f8f6f4(p8, vf, o[d0], 0, 0, 0, 127, 0, 127); }
; }
; __device__ __forceinline__ void qkt9(f32x16& p0, f32x16& p1, const char* Kn, const char* Kr, const v8i32* qf, const float init, int r32, int hi) {
; #pragma unroll
;   for (int r = 0; r < 16; ++r) { p0[r] = init; p1[r] = init; }
; #pragma unroll
;   for (int s = 0; s < 2; ++s) { const int c0 = s * 4 + hi * 2;
;     const v8i32 a0 = cat8(*reinterpret_cast<const v4i32*>(Kn + KN8SW(r32, c0)), *reinterpret_cast<const v4i32*>(Kn + KN8SW(r32, c0 + 1)));
;     const v8i32 a1 = cat8(*reinterpret_cast<const v4i32*>(Kn + 4096 + KN8SW(r32, c0)), *reinterpret_cast<const v4i32*>(Kn + 4096 + KN8SW(r32, c0 + 1)));
;     p0 = __builtin_amdgcn_mfma_scale_f32_32x32x64_f8f6f4(a0, qf[s], p0, 0, 0, 0, 127, 0, 124);
;     p1 = __builtin_amdgcn_mfma_scale_f32_32x32x64_f8f6f4(a1, qf[s], p1, 0, 0, 0, 127, 0, 124); }
;   { const int c0 = hi * 2;
	v_mfma_scale_f32_32x32x64_f8f6f4 v[82:97], v[114:121], v[138:145], v[82:97], v194, v193 op_sel_hi:[0,0,0]
	v_exp_f32_e32 v0, v98
	v_exp_f32_e32 v177, v99
	v_exp_f32_e32 v179, v100
	v_exp_f32_e32 v254, v101
	v_add_f32_e32 v219, v0, v219
	v_add_f32_e32 v219, v177, v219
	v_cvt_pk_fp8_f32 v250, v0, v177
	v_add_f32_e32 v219, v179, v219
	v_add_f32_e32 v219, v254, v219
	v_cvt_pk_fp8_f32 v250, v179, v254 op_sel:[0,0,1]
	s_waitcnt lgkmcnt(2)
	v_mfma_scale_f32_32x32x64_f8f6f4 v[66:81], v[222:229], v[138:145], v[66:81], v194, v193 op_sel_hi:[0,0,0]
	ds_read_b128 v[222:225], v185 offset:34816
	ds_read_b128 v[226:229], v186 offset:34816
	v_exp_f32_e32 v0, v102
	v_exp_f32_e32 v177, v103
	v_exp_f32_e32 v179, v104
	v_exp_f32_e32 v254, v105
	v_add_f32_e32 v219, v0, v219
	v_add_f32_e32 v219, v177, v219
	v_cvt_pk_fp8_f32 v251, v0, v177
	v_add_f32_e32 v219, v179, v219
	v_add_f32_e32 v219, v254, v219
	v_cvt_pk_fp8_f32 v251, v179, v254 op_sel:[0,0,1]
	v_exp_f32_e32 v0, v106
	v_exp_f32_e32 v177, v107
	v_exp_f32_e32 v179, v108
	v_exp_f32_e32 v254, v109
	v_add_f32_e32 v219, v0, v219
	v_add_f32_e32 v219, v177, v219
	v_cvt_pk_fp8_f32 v252, v0, v177
	v_add_f32_e32 v219, v179, v219
	v_add_f32_e32 v219, v254, v219
	v_cvt_pk_fp8_f32 v252, v179, v254 op_sel:[0,0,1]
	s_waitcnt lgkmcnt(2)
	v_mfma_scale_f32_32x32x64_f8f6f4 v[82:97], v[122:129], v[130:137], v[82:97], v194, v193 op_sel_hi:[0,0,0]
	v_exp_f32_e32 v0, v110
	v_exp_f32_e32 v177, v111
	v_exp_f32_e32 v179, v112
	v_exp_f32_e32 v254, v113
	v_add_f32_e32 v219, v0, v219
	v_add_f32_e32 v219, v177, v219
	v_cvt_pk_fp8_f32 v253, v0, v177
	v_add_f32_e32 v219, v179, v219
	v_add_f32_e32 v219, v254, v219
	v_cvt_pk_fp8_f32 v253, v179, v254 op_sel:[0,0,1]
	ds_read_b128 v[122:125], v185 offset:43008
	ds_read_b128 v[126:129], v186 offset:43008
	ds_read_b128 v[114:117], v185 offset:45056
	ds_read_b128 v[118:121], v186 offset:45056
	ds_read_b128 v[106:109], v185 offset:47104
	ds_read_b128 v[110:113], v186 offset:47104
	ds_read_b128 v[98:101], v185 offset:49152
	ds_read_b128 v[102:105], v186 offset:49152
	s_waitcnt lgkmcnt(8)
	v_mfma_scale_f32_32x32x64_f8f6f4 v[66:81], v[222:229], v[130:137], v[66:81], v194, v193 op_sel_hi:[0,0,0]
	v_mov_b32_e32 v0, v219
	s_nop 1
	v_permlane32_swap_b32_e32 v219, v0
	v_add_f32_e32 v219, v219, v0
	v_fma_f32 v209, v209, v221, v219
	v_max_f32_e32 v177, v82, v83
	v_max3_f32 v177, v177, v84, v85
	v_max3_f32 v177, v177, v86, v87
	v_max3_f32 v177, v177, v88, v89
	v_max3_f32 v177, v177, v90, v91
	v_max3_f32 v177, v177, v92, v93
	v_max3_f32 v177, v177, v94, v95
	v_max3_f32 v177, v177, v96, v97
	s_waitcnt lgkmcnt(6)
	v_mfma_scale_f32_32x32x64_f8f6f4 v[50:65], v[246:253], v[122:129], v[50:65], v194, v194 op_sel_hi:[0,0,0]
	s_waitcnt lgkmcnt(4)
	v_mfma_scale_f32_32x32x64_f8f6f4 v[34:49], v[246:253], v[114:121], v[34:49], v194, v194 op_sel_hi:[0,0,0]
	s_waitcnt lgkmcnt(2)
	v_mfma_scale_f32_32x32x64_f8f6f4 v[18:33], v[246:253], v[106:113], v[18:33], v194, v194 op_sel_hi:[0,0,0]
	s_waitcnt lgkmcnt(0)
	v_mfma_scale_f32_32x32x64_f8f6f4 v[2:17], v[246:253], v[98:105], v[2:17], v194, v194 op_sel_hi:[0,0,0]
	s_waitcnt vmcnt(0)
	s_waitcnt lgkmcnt(0)
	s_barrier
	v_max_f32_e32 v0, v66, v67
	v_max3_f32 v0, v0, v68, v69
	v_max3_f32 v0, v0, v70, v71
	v_max3_f32 v0, v0, v72, v73
	v_max3_f32 v0, v0, v74, v75
	v_max3_f32 v0, v0, v76, v77
	v_max3_f32 v0, v0, v78, v79
	v_max3_f32 v0, v0, v80, v81
	v_max_f32_e32 v177, v177, v0
	v_mov_b32_e32 v0, v177
	v_mov_b32_e32 v218, 1.0
	s_nop 0
	v_permlane32_swap_b32_e32 v177, v0
	v_max_f32_e32 v177, v177, v0
	v_cmp_ge_f32_e32 vcc, s90, v177
	s_cmp_eq_u64 vcc, exec
	s_cbranch_scc0 .Lmla_h5_newmax
; __device__ __forceinline__ void finishSM9(f32x16& p0, f32x16& p1, float alpha, float& l_reg, v8i32& p8) {
; #pragma unroll
;   for (int r = 0; r < 16; ++r) { p0[r] = __builtin_amdgcn_exp2f(p0[r]); p1[r] = __builtin_amdgcn_exp2f(p1[r]); }
;   float ps = 0;
; #pragma unroll
;   for (int r = 0; r < 16; ++r) ps += p0[r];
; #pragma unroll
;   for (int r = 0; r < 16; ++r) ps += p1[r];
;   { auto rr = __builtin_amdgcn_permlane32_swap(__float_as_uint(ps), __float_as_uint(ps), false, false);
;     ps = __uint_as_float(rr[0]) + __uint_as_float(rr[1]); }
;   l_reg = l_reg * alpha + ps;
; #pragma unroll
;   for (int g = 0; g < 4; ++g) {
;     int w = __builtin_amdgcn_cvt_pk_fp8_f32(p0[4 * g], p0[4 * g + 1], 0, false); p8[g] = __builtin_amdgcn_cvt_pk_fp8_f32(p0[4 * g + 2], p0[4 * g + 3], w, true);
;     int u = __builtin_amdgcn_cvt_pk_fp8_f32(p1[4 * g], p1[4 * g + 1], 0, false); p8[4 + g] = __builtin_amdgcn_cvt_pk_fp8_f32(p1[4 * g + 2], p1[4 * g + 3], u, true); }
; }
; __device__ __forceinline__ void pv8(f32x16* o, const char* Vt, const v8i32 p8, int r32, int hi) {
;   const int sw = (r32 >> 2) & 3, a0 = r32 * 64 + (((hi * 2) ^ sw) << 4), a1 = r32 * 64 + (((hi * 2 + 1) ^ sw) << 4);
; #pragma unroll
;   for (int d0 = 0; d0 < 4; ++d0) {
;     const v8i32 vf = cat8(*reinterpret_cast<const v4i32*>(Vt + d0 * 2048 + a0), *reinterpret_cast<const v4i32*>(Vt + d0 * 2048 + a1));
;     o[d0] = __builtin_amdgcn_mfma_scale_f32_32x32x64_f8f6f4(p8, vf, o[d0], 0, 0, 0, 127, 0, 127); }
; }
; __device__ __forceinline__ void qkt9(f32x16& p0, f32x16& p1, const char* Kn, const char* Kr, const v8i32* qf, const float init, int r32, int hi) {
; #pragma unroll
;   for (int r = 0; r < 16; ++r) { p0[r] = init; p1[r] = init; }
; #pragma unroll
;   for (int s = 0; s < 2; ++s) { const int c0 = s * 4 + hi * 2;
;     const v8i32 a0 = cat8(*reinterpret_cast<const v4i32*>(Kn + KN8SW(r32, c0)), *reinterpret_cast<const v4i32*>(Kn + KN8SW(r32, c0 + 1)));
;     const v8i32 a1 = cat8(*reinterpret_cast<const v4i32*>(Kn + 4096 + KN8SW(r32, c0)), *reinterpret_cast<const v4i32*>(Kn + 4096 + KN8SW(r32, c0 + 1)));
;     p0 = __builtin_amdgcn_mfma_scale_f32_32x32x64_f8f6f4(a0, qf[s], p0, 0, 0, 0, 127, 0, 124);
;     p1 = __builtin_amdgcn_mfma_scale_f32_32x32x64_f8f6f4(a1, qf[s], p1, 0, 0, 0, 127, 0, 124); }
;   { const int c0 = hi * 2;
.Lmla_h5_cont:
	s_add_i32 s30, s30, 1
	s_cmpk_lt_u32 s30, 42
	s_cbranch_scc1 .LBB0_1321
	ds_read_b128 v[114:117], v215 offset:24576
	ds_read_b128 v[118:121], v216 offset:24576
	ds_read_b128 v[222:225], v215 offset:28672
	ds_read_b128 v[226:229], v216 offset:28672
	s_add_i32 m0, s98, 0xa800
	s_nop 0
	global_load_lds_dwordx4 v176, s[18:19]
	s_add_i32 m0, s98, 0xc800
	s_nop 0
	global_load_lds_dwordx4 v178, s[16:17]
	s_add_i32 m0, s98, 0xe800
	s_nop 0
	global_load_lds_dwordx4 v[180:181], off
	v_add_u32_e32 v176, 0x2000, v176
	v_add_u32_e32 v178, 0x20000, v178
	s_mov_b64 s[20:21], 0x1000
	v_lshl_add_u64 v[180:181], v[180:181], 0, s[20:21]
	v_exp_f32_e32 v0, v82
	v_exp_f32_e32 v177, v83
	v_exp_f32_e32 v179, v84
	v_exp_f32_e32 v254, v85
	v_add_f32_e32 v219, v0, v177
	v_cvt_pk_fp8_f32 v246, v0, v177
	v_add_f32_e32 v219, v179, v219
	v_add_f32_e32 v219, v254, v219
	v_cvt_pk_fp8_f32 v246, v179, v254 op_sel:[0,0,1]
	s_waitcnt lgkmcnt(2)
	v_mfma_scale_f32_32x32x64_f8f6f4 v[114:129], v[114:121], v[146:153], v[230:245], v194, v193 op_sel_hi:[0,0,0]
	v_exp_f32_e32 v0, v86
	v_exp_f32_e32 v177, v87
	v_exp_f32_e32 v179, v88
	v_exp_f32_e32 v254, v89
	v_add_f32_e32 v219, v0, v219
	v_add_f32_e32 v219, v177, v219
	v_cvt_pk_fp8_f32 v247, v0, v177
	v_add_f32_e32 v219, v179, v219
	v_add_f32_e32 v219, v254, v219
	v_cvt_pk_fp8_f32 v247, v179, v254 op_sel:[0,0,1]
	ds_read_b128 v[82:85], v213 offset:24576
	ds_read_b128 v[86:89], v214 offset:24576
	s_waitcnt lgkmcnt(2)
	v_mfma_scale_f32_32x32x64_f8f6f4 v[98:113], v[222:229], v[146:153], v[230:245], v194, v193 op_sel_hi:[0,0,0]
	ds_read_b128 v[222:225], v213 offset:28672
	ds_read_b128 v[226:229], v214 offset:28672
	v_exp_f32_e32 v0, v90
	v_exp_f32_e32 v177, v91
	v_exp_f32_e32 v179, v92
	v_exp_f32_e32 v254, v93
	v_add_f32_e32 v219, v0, v219
	v_add_f32_e32 v219, v177, v219
	v_cvt_pk_fp8_f32 v248, v0, v177
	v_add_f32_e32 v219, v179, v219
	v_add_f32_e32 v219, v254, v219
	v_cvt_pk_fp8_f32 v248, v179, v254 op_sel:[0,0,1]
	v_exp_f32_e32 v0, v94
	v_exp_f32_e32 v177, v95
	v_exp_f32_e32 v179, v96
	v_exp_f32_e32 v254, v97
	v_add_f32_e32 v219, v0, v219
	v_add_f32_e32 v219, v177, v219
	v_cvt_pk_fp8_f32 v249, v0, v177
	v_add_f32_e32 v219, v179, v219
	v_add_f32_e32 v219, v254, v219
	v_cvt_pk_fp8_f32 v249, v179, v254 op_sel:[0,0,1]
	ds_read_b128 v[90:93], v185 offset:36864
	ds_read_b128 v[94:97], v186 offset:36864
	s_waitcnt lgkmcnt(4)
	v_mfma_scale_f32_32x32x64_f8f6f4 v[114:129], v[82:89], v[138:145], v[114:129], v194, v193 op_sel_hi:[0,0,0]
	v_exp_f32_e32 v0, v66
	v_exp_f32_e32 v177, v67
	v_exp_f32_e32 v179, v68
	v_exp_f32_e32 v254, v69
	v_add_f32_e32 v219, v0, v219
	v_add_f32_e32 v219, v177, v219
	v_cvt_pk_fp8_f32 v250, v0, v177
	v_add_f32_e32 v219, v179, v219
	v_add_f32_e32 v219, v254, v219
	v_cvt_pk_fp8_f32 v250, v179, v254 op_sel:[0,0,1]
	s_waitcnt lgkmcnt(2)
	v_mfma_scale_f32_32x32x64_f8f6f4 v[98:113], v[222:229], v[138:145], v[98:113], v194, v193 op_sel_hi:[0,0,0]
	ds_read_b128 v[222:225], v185 offset:38912
	ds_read_b128 v[226:229], v186 offset:38912
	v_exp_f32_e32 v0, v70
	v_exp_f32_e32 v177, v71
	v_exp_f32_e32 v179, v72
	v_exp_f32_e32 v254, v73
	v_add_f32_e32 v219, v0, v219
	v_add_f32_e32 v219, v177, v219
	v_cvt_pk_fp8_f32 v251, v0, v177
	v_add_f32_e32 v219, v179, v219
	v_add_f32_e32 v219, v254, v219
	v_cvt_pk_fp8_f32 v251, v179, v254 op_sel:[0,0,1]
	v_exp_f32_e32 v0, v74
	v_exp_f32_e32 v177, v75
	v_exp_f32_e32 v179, v76
	v_exp_f32_e32 v254, v77
	v_add_f32_e32 v219, v0, v219
	v_add_f32_e32 v219, v177, v219
	v_cvt_pk_fp8_f32 v252, v0, v177
	v_add_f32_e32 v219, v179, v219
	v_add_f32_e32 v219, v254, v219
	v_cvt_pk_fp8_f32 v252, v179, v254 op_sel:[0,0,1]
	s_waitcnt lgkmcnt(2)
	v_mfma_scale_f32_32x32x64_f8f6f4 v[114:129], v[90:97], v[130:137], v[114:129], v194, v193 op_sel_hi:[0,0,0]
	v_exp_f32_e32 v0, v78
	v_exp_f32_e32 v177, v79
	v_exp_f32_e32 v179, v80
	v_exp_f32_e32 v254, v81
	v_add_f32_e32 v219, v0, v219
	v_add_f32_e32 v219, v177, v219
	v_cvt_pk_fp8_f32 v253, v0, v177
	v_add_f32_e32 v219, v179, v219
	v_add_f32_e32 v219, v254, v219
	v_cvt_pk_fp8_f32 v253, v179, v254 op_sel:[0,0,1]
	ds_read_b128 v[90:93], v185 offset:0
	ds_read_b128 v[94:97], v186 offset:0
	ds_read_b128 v[82:85], v185 offset:2048
	ds_read_b128 v[86:89], v186 offset:2048
	ds_read_b128 v[74:77], v185 offset:4096
	ds_read_b128 v[78:81], v186 offset:4096
	ds_read_b128 v[66:69], v185 offset:6144
	ds_read_b128 v[70:73], v186 offset:6144
	s_waitcnt lgkmcnt(8)
	v_mfma_scale_f32_32x32x64_f8f6f4 v[98:113], v[222:229], v[130:137], v[98:113], v194, v193 op_sel_hi:[0,0,0]
	v_mov_b32_e32 v0, v219
	s_nop 1
	v_permlane32_swap_b32_e32 v219, v0
	v_add_f32_e32 v219, v219, v0
	v_fma_f32 v209, v209, v218, v219
	v_max_f32_e32 v177, v114, v115
	v_max3_f32 v177, v177, v116, v117
	v_max3_f32 v177, v177, v118, v119
	v_max3_f32 v177, v177, v120, v121
	v_max3_f32 v177, v177, v122, v123
	v_max3_f32 v177, v177, v124, v125
	v_max3_f32 v177, v177, v126, v127
	v_max3_f32 v177, v177, v128, v129
	s_waitcnt lgkmcnt(6)
	v_mfma_scale_f32_32x32x64_f8f6f4 v[50:65], v[246:253], v[90:97], v[50:65], v194, v194 op_sel_hi:[0,0,0]
	s_waitcnt lgkmcnt(4)
	v_mfma_scale_f32_32x32x64_f8f6f4 v[34:49], v[246:253], v[82:89], v[34:49], v194, v194 op_sel_hi:[0,0,0]
	s_waitcnt lgkmcnt(2)
	v_mfma_scale_f32_32x32x64_f8f6f4 v[18:33], v[246:253], v[74:81], v[18:33], v194, v194 op_sel_hi:[0,0,0]
	s_waitcnt lgkmcnt(0)
	v_mfma_scale_f32_32x32x64_f8f6f4 v[2:17], v[246:253], v[66:73], v[2:17], v194, v194 op_sel_hi:[0,0,0]
	s_waitcnt vmcnt(0)
	s_waitcnt lgkmcnt(0)
	s_barrier
	v_max_f32_e32 v0, v98, v99
	v_max3_f32 v0, v0, v100, v101
	v_max3_f32 v0, v0, v102, v103
	v_max3_f32 v0, v0, v104, v105
	v_max3_f32 v0, v0, v106, v107
	v_max3_f32 v0, v0, v108, v109
	v_max3_f32 v0, v0, v110, v111
	v_max3_f32 v0, v0, v112, v113
	v_max_f32_e32 v177, v177, v0
	v_mov_b32_e32 v0, v177
	v_mov_b32_e32 v221, 1.0
	s_nop 0
	v_permlane32_swap_b32_e32 v177, v0
	v_max_f32_e32 v177, v177, v0
	v_cmp_ge_f32_e32 vcc, s90, v177
	s_cmp_eq_u64 vcc, exec
	s_cbranch_scc0 .Lmla_p0_newmax

; __device__ __forceinline__ void finishSM9(f32x16& p0, f32x16& p1, float alpha, float& l_reg, v8i32& p8) {
; #pragma unroll
;   for (int r = 0; r < 16; ++r) { p0[r] = __builtin_amdgcn_exp2f(p0[r]); p1[r] = __builtin_amdgcn_exp2f(p1[r]); }
;   float ps = 0;
; #pragma unroll
;   for (int r = 0; r < 16; ++r) ps += p0[r];
; #pragma unroll
;   for (int r = 0; r < 16; ++r) ps += p1[r];
;   { auto rr = __builtin_amdgcn_permlane32_swap(__float_as_uint(ps), __float_as_uint(ps), false, false);
;     ps = __uint_as_float(rr[0]) + __uint_as_float(rr[1]); }
;   l_reg = l_reg * alpha + ps;
; #pragma unroll
;   for (int g = 0; g < 4; ++g) {
;     int w = __builtin_amdgcn_cvt_pk_fp8_f32(p0[4 * g], p0[4 * g + 1], 0, false); p8[g] = __builtin_amdgcn_cvt_pk_fp8_f32(p0[4 * g + 2], p0[4 * g + 3], w, true);
;     int u = __builtin_amdgcn_cvt_pk_fp8_f32(p1[4 * g], p1[4 * g + 1], 0, false); p8[4 + g] = __builtin_amdgcn_cvt_pk_fp8_f32(p1[4 * g + 2], p1[4 * g + 3], u, true); }
; }
; __device__ __forceinline__ void pv8(f32x16* o, const char* Vt, const v8i32 p8, int r32, int hi) {
;   const int sw = (r32 >> 2) & 3, a0 = r32 * 64 + (((hi * 2) ^ sw) << 4), a1 = r32 * 64 + (((hi * 2 + 1) ^ sw) << 4);
; #pragma unroll
;   for (int d0 = 0; d0 < 4; ++d0) {
;     const v8i32 vf = cat8(*reinterpret_cast<const v4i32*>(Vt + d0 * 2048 + a0), *reinterpret_cast<const v4i32*>(Vt + d0 * 2048 + a1));
;     o[d0] = __builtin_amdgcn_mfma_scale_f32_32x32x64_f8f6f4(p8, vf, o[d0], 0, 0, 0, 127, 0, 127); }
; }
; __device__ __forceinline__ void qkt9(f32x16& p0, f32x16& p1, const char* Kn, const char* Kr, const v8i32* qf, const float init, int r32, int hi) {
; #pragma unroll
;   for (int r = 0; r < 16; ++r) { p0[r] = init; p1[r] = init; }
; #pragma unroll
;   for (int s = 0; s < 2; ++s) { const int c0 = s * 4 + hi * 2;
;     const v8i32 a0 = cat8(*reinterpret_cast<const v4i32*>(Kn + KN8SW(r32, c0)), *reinterpret_cast<const v4i32*>(Kn + KN8SW(r32, c0 + 1)));
;     const v8i32 a1 = cat8(*reinterpret_cast<const v4i32*>(Kn + 4096 + KN8SW(r32, c0)), *reinterpret_cast<const v4i32*>(Kn + 4096 + KN8SW(r32, c0 + 1)));
;     p0 = __builtin_amdgcn_mfma_scale_f32_32x32x64_f8f6f4(a0, qf[s], p0, 0, 0, 0, 127, 0, 124);
;     p1 = __builtin_amdgcn_mfma_scale_f32_32x32x64_f8f6f4(a1, qf[s], p1, 0, 0, 0, 127, 0, 124); }
;   { const int c0 = hi * 2;
.Lmla_stag_entry:
	s_add_i32 m0, s98, 0xa800
	s_nop 0
	global_load_lds_dwordx4 v176, s[18:19]
	s_add_i32 m0, s98, 0xc800
	s_nop 0
	global_load_lds_dwordx4 v178, s[16:17]
	s_nop 1
	v_add_u32_e32 v176, 0x2000, v176
	v_add_u32_e32 v178, 0x20000, v178
.Lmla_stag_loop:
	ds_read_b128 v[114:117], v215 offset:24576
	ds_read_b128 v[118:121], v216 offset:24576
	ds_read_b128 v[222:225], v215 offset:28672
	ds_read_b128 v[226:229], v216 offset:28672
	v_exp_f32_e32 v0, v82
	v_exp_f32_e32 v177, v83
	v_exp_f32_e32 v179, v84
	v_exp_f32_e32 v254, v85
	v_add_f32_e32 v219, v0, v177
	v_cvt_pk_fp8_f32 v246, v0, v177
	v_add_f32_e32 v219, v179, v219
	v_add_f32_e32 v219, v254, v219
	v_cvt_pk_fp8_f32 v246, v179, v254 op_sel:[0,0,1]
	s_waitcnt lgkmcnt(2)
	v_mfma_scale_f32_32x32x64_f8f6f4 v[114:129], v[114:121], v[146:153], v[230:245], v194, v193 op_sel_hi:[0,0,0]
	v_exp_f32_e32 v0, v86
	v_exp_f32_e32 v177, v87
	v_exp_f32_e32 v179, v88
	v_exp_f32_e32 v254, v89
	v_add_f32_e32 v219, v0, v219
	v_add_f32_e32 v219, v177, v219
	v_cvt_pk_fp8_f32 v247, v0, v177
	v_add_f32_e32 v219, v179, v219
	v_add_f32_e32 v219, v254, v219
	v_cvt_pk_fp8_f32 v247, v179, v254 op_sel:[0,0,1]
	ds_read_b128 v[82:85], v213 offset:24576
	ds_read_b128 v[86:89], v214 offset:24576
	s_waitcnt lgkmcnt(2)
	v_mfma_scale_f32_32x32x64_f8f6f4 v[98:113], v[222:229], v[146:153], v[230:245], v194, v193 op_sel_hi:[0,0,0]
	ds_read_b128 v[222:225], v213 offset:28672
	ds_read_b128 v[226:229], v214 offset:28672
	v_exp_f32_e32 v0, v90
	v_exp_f32_e32 v177, v91
	v_exp_f32_e32 v179, v92
	v_exp_f32_e32 v254, v93
	v_add_f32_e32 v219, v0, v219
	v_add_f32_e32 v219, v177, v219
	v_cvt_pk_fp8_f32 v248, v0, v177
	v_add_f32_e32 v219, v179, v219
	v_add_f32_e32 v219, v254, v219
	v_cvt_pk_fp8_f32 v248, v179, v254 op_sel:[0,0,1]
	v_exp_f32_e32 v0, v94
	v_exp_f32_e32 v177, v95
	v_exp_f32_e32 v179, v96
	v_exp_f32_e32 v254, v97
	v_add_f32_e32 v219, v0, v219
	v_add_f32_e32 v219, v177, v219
	v_cvt_pk_fp8_f32 v249, v0, v177
	v_add_f32_e32 v219, v179, v219
	v_add_f32_e32 v219, v254, v219
	v_cvt_pk_fp8_f32 v249, v179, v254 op_sel:[0,0,1]
	ds_read_b128 v[90:93], v185 offset:36864
	ds_read_b128 v[94:97], v186 offset:36864
	s_waitcnt lgkmcnt(4)
	v_mfma_scale_f32_32x32x64_f8f6f4 v[114:129], v[82:89], v[138:145], v[114:129], v194, v193 op_sel_hi:[0,0,0]
	v_exp_f32_e32 v0, v66
	v_exp_f32_e32 v177, v67
	v_exp_f32_e32 v179, v68
	v_exp_f32_e32 v254, v69
	v_add_f32_e32 v219, v0, v219
	v_add_f32_e32 v219, v177, v219
	v_cvt_pk_fp8_f32 v250, v0, v177
	v_add_f32_e32 v219, v179, v219
	v_add_f32_e32 v219, v254, v219
	v_cvt_pk_fp8_f32 v250, v179, v254 op_sel:[0,0,1]
	s_waitcnt lgkmcnt(2)
	v_mfma_scale_f32_32x32x64_f8f6f4 v[98:113], v[222:229], v[138:145], v[98:113], v194, v193 op_sel_hi:[0,0,0]
	ds_read_b128 v[222:225], v185 offset:38912
	ds_read_b128 v[226:229], v186 offset:38912
	v_exp_f32_e32 v0, v70
	v_exp_f32_e32 v177, v71
	v_exp_f32_e32 v179, v72
	v_exp_f32_e32 v254, v73
	v_add_f32_e32 v219, v0, v219
	v_add_f32_e32 v219, v177, v219
	v_cvt_pk_fp8_f32 v251, v0, v177
	v_add_f32_e32 v219, v179, v219
	v_add_f32_e32 v219, v254, v219
	v_cvt_pk_fp8_f32 v251, v179, v254 op_sel:[0,0,1]
	v_exp_f32_e32 v0, v74
	v_exp_f32_e32 v177, v75
	v_exp_f32_e32 v179, v76
	v_exp_f32_e32 v254, v77
	v_add_f32_e32 v219, v0, v219
	v_add_f32_e32 v219, v177, v219
	v_cvt_pk_fp8_f32 v252, v0, v177
	v_add_f32_e32 v219, v179, v219
	v_add_f32_e32 v219, v254, v219
	v_cvt_pk_fp8_f32 v252, v179, v254 op_sel:[0,0,1]
	s_waitcnt lgkmcnt(2)
	v_mfma_scale_f32_32x32x64_f8f6f4 v[114:129], v[90:97], v[130:137], v[114:129], v194, v193 op_sel_hi:[0,0,0]
	v_exp_f32_e32 v0, v78
	v_exp_f32_e32 v177, v79
	v_exp_f32_e32 v179, v80
	v_exp_f32_e32 v254, v81
	v_add_f32_e32 v219, v0, v219
	v_add_f32_e32 v219, v177, v219
	v_cvt_pk_fp8_f32 v253, v0, v177
	v_add_f32_e32 v219, v179, v219
	v_add_f32_e32 v219, v254, v219
	v_cvt_pk_fp8_f32 v253, v179, v254 op_sel:[0,0,1]
	ds_read_b128 v[90:93], v185 offset:0
	ds_read_b128 v[94:97], v186 offset:0
	ds_read_b128 v[82:85], v185 offset:2048
	ds_read_b128 v[86:89], v186 offset:2048
	ds_read_b128 v[74:77], v185 offset:4096
	ds_read_b128 v[78:81], v186 offset:4096
	ds_read_b128 v[66:69], v185 offset:6144
	ds_read_b128 v[70:73], v186 offset:6144
	s_waitcnt lgkmcnt(8)
	v_mfma_scale_f32_32x32x64_f8f6f4 v[98:113], v[222:229], v[130:137], v[98:113], v194, v193 op_sel_hi:[0,0,0]
	v_mov_b32_e32 v0, v219
	s_nop 1
	v_permlane32_swap_b32_e32 v219, v0
	v_add_f32_e32 v219, v219, v0
	v_fma_f32 v209, v209, v218, v219
	v_max_f32_e32 v177, v114, v115
	v_max3_f32 v177, v177, v116, v117
	v_max3_f32 v177, v177, v118, v119
	v_max3_f32 v177, v177, v120, v121
	v_max3_f32 v177, v177, v122, v123
	v_max3_f32 v177, v177, v124, v125
	v_max3_f32 v177, v177, v126, v127
	v_max3_f32 v177, v177, v128, v129
	s_waitcnt lgkmcnt(6)
	v_mfma_scale_f32_32x32x64_f8f6f4 v[50:65], v[246:253], v[90:97], v[50:65], v194, v194 op_sel_hi:[0,0,0]
	s_waitcnt lgkmcnt(4)
	v_mfma_scale_f32_32x32x64_f8f6f4 v[34:49], v[246:253], v[82:89], v[34:49], v194, v194 op_sel_hi:[0,0,0]
	s_waitcnt vmcnt(0)
	s_waitcnt lgkmcnt(0)
	s_barrier
	s_waitcnt lgkmcnt(2)
	v_mfma_scale_f32_32x32x64_f8f6f4 v[18:33], v[246:253], v[74:81], v[18:33], v194, v194 op_sel_hi:[0,0,0]
	s_add_i32 m0, s98, 0x0
	s_nop 0
	global_load_lds_dwordx4 v176, s[18:19]
	s_add_i32 m0, s98, 0x4000
	s_nop 0
	global_load_lds_dwordx4 v178, s[16:17]
	v_add_u32_e32 v176, 0x2000, v176
	v_add_u32_e32 v178, 0x20000, v178
	s_waitcnt lgkmcnt(0)
	v_mfma_scale_f32_32x32x64_f8f6f4 v[2:17], v[246:253], v[66:73], v[2:17], v194, v194 op_sel_hi:[0,0,0]
	v_max_f32_e32 v0, v98, v99
	v_max3_f32 v0, v0, v100, v101
	v_max3_f32 v0, v0, v102, v103
	v_max3_f32 v0, v0, v104, v105
	v_max3_f32 v0, v0, v106, v107
	v_max3_f32 v0, v0, v108, v109
	v_max3_f32 v0, v0, v110, v111
	v_max3_f32 v0, v0, v112, v113
	v_max_f32_e32 v177, v177, v0
	v_mov_b32_e32 v0, v177
	v_mov_b32_e32 v221, 1.0
	s_nop 0
	v_permlane32_swap_b32_e32 v177, v0
	v_max_f32_e32 v177, v177, v0
	v_cmp_ge_f32_e32 vcc, s90, v177
	s_cmp_eq_u64 vcc, exec
	s_cbranch_scc0 .Lmla_s0_newmax
; __device__ __forceinline__ void finishSM9(f32x16& p0, f32x16& p1, float alpha, float& l_reg, v8i32& p8) {
; #pragma unroll
;   for (int r = 0; r < 16; ++r) { p0[r] = __builtin_amdgcn_exp2f(p0[r]); p1[r] = __builtin_amdgcn_exp2f(p1[r]); }
;   float ps = 0;
; #pragma unroll
;   for (int r = 0; r < 16; ++r) ps += p0[r];
; #pragma unroll
;   for (int r = 0; r < 16; ++r) ps += p1[r];
;   { auto rr = __builtin_amdgcn_permlane32_swap(__float_as_uint(ps), __float_as_uint(ps), false, false);
;     ps = __uint_as_float(rr[0]) + __uint_as_float(rr[1]); }
;   l_reg = l_reg * alpha + ps;
; #pragma unroll
;   for (int g = 0; g < 4; ++g) {
;     int w = __builtin_amdgcn_cvt_pk_fp8_f32(p0[4 * g], p0[4 * g + 1], 0, false); p8[g] = __builtin_amdgcn_cvt_pk_fp8_f32(p0[4 * g + 2], p0[4 * g + 3], w, true);
;     int u = __builtin_amdgcn_cvt_pk_fp8_f32(p1[4 * g], p1[4 * g + 1], 0, false); p8[4 + g] = __builtin_amdgcn_cvt_pk_fp8_f32(p1[4 * g + 2], p1[4 * g + 3], u, true); }
; }
; __device__ __forceinline__ void pv8(f32x16* o, const char* Vt, const v8i32 p8, int r32, int hi) {
;   const int sw = (r32 >> 2) & 3, a0 = r32 * 64 + (((hi * 2) ^ sw) << 4), a1 = r32 * 64 + (((hi * 2 + 1) ^ sw) << 4);
; #pragma unroll
;   for (int d0 = 0; d0 < 4; ++d0) {
;     const v8i32 vf = cat8(*reinterpret_cast<const v4i32*>(Vt + d0 * 2048 + a0), *reinterpret_cast<const v4i32*>(Vt + d0 * 2048 + a1));
;     o[d0] = __builtin_amdgcn_mfma_scale_f32_32x32x64_f8f6f4(p8, vf, o[d0], 0, 0, 0, 127, 0, 127); }
; }
; __device__ __forceinline__ void qkt9(f32x16& p0, f32x16& p1, const char* Kn, const char* Kr, const v8i32* qf, const float init, int r32, int hi) {
; #pragma unroll
;   for (int r = 0; r < 16; ++r) { p0[r] = init; p1[r] = init; }
; #pragma unroll
;   for (int s = 0; s < 2; ++s) { const int c0 = s * 4 + hi * 2;
;     const v8i32 a0 = cat8(*reinterpret_cast<const v4i32*>(Kn + KN8SW(r32, c0)), *reinterpret_cast<const v4i32*>(Kn + KN8SW(r32, c0 + 1)));
;     const v8i32 a1 = cat8(*reinterpret_cast<const v4i32*>(Kn + 4096 + KN8SW(r32, c0)), *reinterpret_cast<const v4i32*>(Kn + 4096 + KN8SW(r32, c0 + 1)));
;     p0 = __builtin_amdgcn_mfma_scale_f32_32x32x64_f8f6f4(a0, qf[s], p0, 0, 0, 0, 127, 0, 124);
;     p1 = __builtin_amdgcn_mfma_scale_f32_32x32x64_f8f6f4(a1, qf[s], p1, 0, 0, 0, 127, 0, 124); }
;   { const int c0 = hi * 2;
.Lmla_s0_cont:
	ds_read_b128 v[82:85], v215 offset:51200
	ds_read_b128 v[86:89], v216 offset:51200
	ds_read_b128 v[222:225], v215 offset:55296
	ds_read_b128 v[226:229], v216 offset:55296
	v_exp_f32_e32 v0, v114
	v_exp_f32_e32 v177, v115
	v_exp_f32_e32 v179, v116
	v_exp_f32_e32 v254, v117
	v_add_f32_e32 v219, v0, v177
	v_cvt_pk_fp8_f32 v246, v0, v177
	v_add_f32_e32 v219, v179, v219
	v_add_f32_e32 v219, v254, v219
	v_cvt_pk_fp8_f32 v246, v179, v254 op_sel:[0,0,1]
	s_waitcnt lgkmcnt(2)
	v_mfma_scale_f32_32x32x64_f8f6f4 v[82:97], v[82:89], v[146:153], v[230:245], v194, v193 op_sel_hi:[0,0,0]
	v_exp_f32_e32 v0, v118
	v_exp_f32_e32 v177, v119
	v_exp_f32_e32 v179, v120
	v_exp_f32_e32 v254, v121
	v_add_f32_e32 v219, v0, v219
	v_add_f32_e32 v219, v177, v219
	v_cvt_pk_fp8_f32 v247, v0, v177
	v_add_f32_e32 v219, v179, v219
	v_add_f32_e32 v219, v254, v219
	v_cvt_pk_fp8_f32 v247, v179, v254 op_sel:[0,0,1]
	ds_read_b128 v[114:117], v213 offset:51200
	ds_read_b128 v[118:121], v214 offset:51200
	s_waitcnt lgkmcnt(2)
	v_mfma_scale_f32_32x32x64_f8f6f4 v[66:81], v[222:229], v[146:153], v[230:245], v194, v193 op_sel_hi:[0,0,0]
	ds_read_b128 v[222:225], v213 offset:55296
	ds_read_b128 v[226:229], v214 offset:55296
	v_exp_f32_e32 v0, v122
	v_exp_f32_e32 v177, v123
	v_exp_f32_e32 v179, v124
	v_exp_f32_e32 v254, v125
	v_add_f32_e32 v219, v0, v219
	v_add_f32_e32 v219, v177, v219
	v_cvt_pk_fp8_f32 v248, v0, v177
	v_add_f32_e32 v219, v179, v219
	v_add_f32_e32 v219, v254, v219
	v_cvt_pk_fp8_f32 v248, v179, v254 op_sel:[0,0,1]
	v_exp_f32_e32 v0, v126
	v_exp_f32_e32 v177, v127
	v_exp_f32_e32 v179, v128
	v_exp_f32_e32 v254, v129
	v_add_f32_e32 v219, v0, v219
	v_add_f32_e32 v219, v177, v219
	v_cvt_pk_fp8_f32 v249, v0, v177
	v_add_f32_e32 v219, v179, v219
	v_add_f32_e32 v219, v254, v219
	v_cvt_pk_fp8_f32 v249, v179, v254 op_sel:[0,0,1]
	ds_read_b128 v[122:125], v185 offset:59392
	ds_read_b128 v[126:129], v186 offset:59392
	s_waitcnt lgkmcnt(4)
	v_mfma_scale_f32_32x32x64_f8f6f4 v[82:97], v[114:121], v[138:145], v[82:97], v194, v193 op_sel_hi:[0,0,0]
	v_exp_f32_e32 v0, v98
	v_exp_f32_e32 v177, v99
	v_exp_f32_e32 v179, v100
	v_exp_f32_e32 v254, v101
	v_add_f32_e32 v219, v0, v219
	v_add_f32_e32 v219, v177, v219
	v_cvt_pk_fp8_f32 v250, v0, v177
	v_add_f32_e32 v219, v179, v219
	v_add_f32_e32 v219, v254, v219
	v_cvt_pk_fp8_f32 v250, v179, v254 op_sel:[0,0,1]
	s_waitcnt lgkmcnt(2)
	v_mfma_scale_f32_32x32x64_f8f6f4 v[66:81], v[222:229], v[138:145], v[66:81], v194, v193 op_sel_hi:[0,0,0]
	ds_read_b128 v[222:225], v185 offset:61440
	ds_read_b128 v[226:229], v186 offset:61440
	v_exp_f32_e32 v0, v102
	v_exp_f32_e32 v177, v103
	v_exp_f32_e32 v179, v104
	v_exp_f32_e32 v254, v105
	v_add_f32_e32 v219, v0, v219
	v_add_f32_e32 v219, v177, v219
	v_cvt_pk_fp8_f32 v251, v0, v177
	v_add_f32_e32 v219, v179, v219
	v_add_f32_e32 v219, v254, v219
	v_cvt_pk_fp8_f32 v251, v179, v254 op_sel:[0,0,1]
	v_exp_f32_e32 v0, v106
	v_exp_f32_e32 v177, v107
	v_exp_f32_e32 v179, v108
	v_exp_f32_e32 v254, v109
	v_add_f32_e32 v219, v0, v219
	v_add_f32_e32 v219, v177, v219
	v_cvt_pk_fp8_f32 v252, v0, v177
	v_add_f32_e32 v219, v179, v219
	v_add_f32_e32 v219, v254, v219
	v_cvt_pk_fp8_f32 v252, v179, v254 op_sel:[0,0,1]
	s_waitcnt lgkmcnt(2)
	v_mfma_scale_f32_32x32x64_f8f6f4 v[82:97], v[122:129], v[130:137], v[82:97], v194, v193 op_sel_hi:[0,0,0]
	v_exp_f32_e32 v0, v110
	v_exp_f32_e32 v177, v111
	v_exp_f32_e32 v179, v112
	v_exp_f32_e32 v254, v113
	v_add_f32_e32 v219, v0, v219
	v_add_f32_e32 v219, v177, v219
	v_cvt_pk_fp8_f32 v253, v0, v177
	v_add_f32_e32 v219, v179, v219
	v_add_f32_e32 v219, v254, v219
	v_cvt_pk_fp8_f32 v253, v179, v254 op_sel:[0,0,1]
	ds_read_b128 v[122:125], v185 offset:8192
	ds_read_b128 v[126:129], v186 offset:8192
	ds_read_b128 v[114:117], v185 offset:10240
	ds_read_b128 v[118:121], v186 offset:10240
	ds_read_b128 v[106:109], v185 offset:12288
	ds_read_b128 v[110:113], v186 offset:12288
	ds_read_b128 v[98:101], v185 offset:14336
	ds_read_b128 v[102:105], v186 offset:14336
	s_waitcnt lgkmcnt(8)
	v_mfma_scale_f32_32x32x64_f8f6f4 v[66:81], v[222:229], v[130:137], v[66:81], v194, v193 op_sel_hi:[0,0,0]
	v_mov_b32_e32 v0, v219
	s_nop 1
	v_permlane32_swap_b32_e32 v219, v0
	v_add_f32_e32 v219, v219, v0
	v_fma_f32 v209, v209, v221, v219
	v_max_f32_e32 v177, v82, v83
	v_max3_f32 v177, v177, v84, v85
	v_max3_f32 v177, v177, v86, v87
	v_max3_f32 v177, v177, v88, v89
	v_max3_f32 v177, v177, v90, v91
	v_max3_f32 v177, v177, v92, v93
	v_max3_f32 v177, v177, v94, v95
	v_max3_f32 v177, v177, v96, v97
	s_waitcnt lgkmcnt(6)
	v_mfma_scale_f32_32x32x64_f8f6f4 v[50:65], v[246:253], v[122:129], v[50:65], v194, v194 op_sel_hi:[0,0,0]
	s_waitcnt lgkmcnt(4)
	v_mfma_scale_f32_32x32x64_f8f6f4 v[34:49], v[246:253], v[114:121], v[34:49], v194, v194 op_sel_hi:[0,0,0]
	s_waitcnt vmcnt(0)
	s_waitcnt lgkmcnt(0)
	s_barrier
	s_waitcnt lgkmcnt(2)
	v_mfma_scale_f32_32x32x64_f8f6f4 v[18:33], v[246:253], v[106:113], v[18:33], v194, v194 op_sel_hi:[0,0,0]
	s_add_i32 m0, s98, 0x2000
	s_nop 0
	global_load_lds_dwordx4 v176, s[18:19]
	s_add_i32 m0, s98, 0x6000
	s_nop 0
	global_load_lds_dwordx4 v178, s[16:17]
	v_add_u32_e32 v176, 0x2000, v176
	v_add_u32_e32 v178, 0x20000, v178
	s_waitcnt lgkmcnt(0)
	v_mfma_scale_f32_32x32x64_f8f6f4 v[2:17], v[246:253], v[98:105], v[2:17], v194, v194 op_sel_hi:[0,0,0]
	v_max_f32_e32 v0, v66, v67
	v_max3_f32 v0, v0, v68, v69
	v_max3_f32 v0, v0, v70, v71
	v_max3_f32 v0, v0, v72, v73
	v_max3_f32 v0, v0, v74, v75
	v_max3_f32 v0, v0, v76, v77
	v_max3_f32 v0, v0, v78, v79
	v_max3_f32 v0, v0, v80, v81
	v_max_f32_e32 v177, v177, v0
	v_mov_b32_e32 v0, v177
	v_mov_b32_e32 v218, 1.0
	s_nop 0
	v_permlane32_swap_b32_e32 v177, v0
	v_max_f32_e32 v177, v177, v0
	v_cmp_ge_f32_e32 vcc, s90, v177
	s_cmp_eq_u64 vcc, exec
	s_cbranch_scc0 .Lmla_s1_newmax
; __device__ __forceinline__ void finishSM9(f32x16& p0, f32x16& p1, float alpha, float& l_reg, v8i32& p8) {
; #pragma unroll
;   for (int r = 0; r < 16; ++r) { p0[r] = __builtin_amdgcn_exp2f(p0[r]); p1[r] = __builtin_amdgcn_exp2f(p1[r]); }
;   float ps = 0;
; #pragma unroll
;   for (int r = 0; r < 16; ++r) ps += p0[r];
; #pragma unroll
;   for (int r = 0; r < 16; ++r) ps += p1[r];
;   { auto rr = __builtin_amdgcn_permlane32_swap(__float_as_uint(ps), __float_as_uint(ps), false, false);
;     ps = __uint_as_float(rr[0]) + __uint_as_float(rr[1]); }
;   l_reg = l_reg * alpha + ps;
; #pragma unroll
;   for (int g = 0; g < 4; ++g) {
;     int w = __builtin_amdgcn_cvt_pk_fp8_f32(p0[4 * g], p0[4 * g + 1], 0, false); p8[g] = __builtin_amdgcn_cvt_pk_fp8_f32(p0[4 * g + 2], p0[4 * g + 3], w, true);
;     int u = __builtin_amdgcn_cvt_pk_fp8_f32(p1[4 * g], p1[4 * g + 1], 0, false); p8[4 + g] = __builtin_amdgcn_cvt_pk_fp8_f32(p1[4 * g + 2], p1[4 * g + 3], u, true); }
; }
; __device__ __forceinline__ void pv8(f32x16* o, const char* Vt, const v8i32 p8, int r32, int hi) {
;   const int sw = (r32 >> 2) & 3, a0 = r32 * 64 + (((hi * 2) ^ sw) << 4), a1 = r32 * 64 + (((hi * 2 + 1) ^ sw) << 4);
; #pragma unroll
;   for (int d0 = 0; d0 < 4; ++d0) {
;     const v8i32 vf = cat8(*reinterpret_cast<const v4i32*>(Vt + d0 * 2048 + a0), *reinterpret_cast<const v4i32*>(Vt + d0 * 2048 + a1));
;     o[d0] = __builtin_amdgcn_mfma_scale_f32_32x32x64_f8f6f4(p8, vf, o[d0], 0, 0, 0, 127, 0, 127); }
; }
; __device__ __forceinline__ void qkt9(f32x16& p0, f32x16& p1, const char* Kn, const char* Kr, const v8i32* qf, const float init, int r32, int hi) {
; #pragma unroll
;   for (int r = 0; r < 16; ++r) { p0[r] = init; p1[r] = init; }
; #pragma unroll
;   for (int s = 0; s < 2; ++s) { const int c0 = s * 4 + hi * 2;
;     const v8i32 a0 = cat8(*reinterpret_cast<const v4i32*>(Kn + KN8SW(r32, c0)), *reinterpret_cast<const v4i32*>(Kn + KN8SW(r32, c0 + 1)));
;     const v8i32 a1 = cat8(*reinterpret_cast<const v4i32*>(Kn + 4096 + KN8SW(r32, c0)), *reinterpret_cast<const v4i32*>(Kn + 4096 + KN8SW(r32, c0 + 1)));
;     p0 = __builtin_amdgcn_mfma_scale_f32_32x32x64_f8f6f4(a0, qf[s], p0, 0, 0, 0, 127, 0, 124);
;     p1 = __builtin_amdgcn_mfma_scale_f32_32x32x64_f8f6f4(a1, qf[s], p1, 0, 0, 0, 127, 0, 124); }
;   { const int c0 = hi * 2;
.Lmla_s1_cont:
	ds_read_b128 v[114:117], v215 offset:16384
	ds_read_b128 v[118:121], v216 offset:16384
	ds_read_b128 v[222:225], v215 offset:20480
	ds_read_b128 v[226:229], v216 offset:20480
	v_exp_f32_e32 v0, v82
	v_exp_f32_e32 v177, v83
	v_exp_f32_e32 v179, v84
	v_exp_f32_e32 v254, v85
	v_add_f32_e32 v219, v0, v177
	v_cvt_pk_fp8_f32 v246, v0, v177
	v_add_f32_e32 v219, v179, v219
	v_add_f32_e32 v219, v254, v219
	v_cvt_pk_fp8_f32 v246, v179, v254 op_sel:[0,0,1]
	s_waitcnt lgkmcnt(2)
	v_mfma_scale_f32_32x32x64_f8f6f4 v[114:129], v[114:121], v[146:153], v[230:245], v194, v193 op_sel_hi:[0,0,0]
	v_exp_f32_e32 v0, v86
	v_exp_f32_e32 v177, v87
	v_exp_f32_e32 v179, v88
	v_exp_f32_e32 v254, v89
	v_add_f32_e32 v219, v0, v219
	v_add_f32_e32 v219, v177, v219
	v_cvt_pk_fp8_f32 v247, v0, v177
	v_add_f32_e32 v219, v179, v219
	v_add_f32_e32 v219, v254, v219
	v_cvt_pk_fp8_f32 v247, v179, v254 op_sel:[0,0,1]
	ds_read_b128 v[82:85], v213 offset:16384
	ds_read_b128 v[86:89], v214 offset:16384
	s_waitcnt lgkmcnt(2)
	v_mfma_scale_f32_32x32x64_f8f6f4 v[98:113], v[222:229], v[146:153], v[230:245], v194, v193 op_sel_hi:[0,0,0]
	ds_read_b128 v[222:225], v213 offset:20480
	ds_read_b128 v[226:229], v214 offset:20480
	v_exp_f32_e32 v0, v90
	v_exp_f32_e32 v177, v91
	v_exp_f32_e32 v179, v92
	v_exp_f32_e32 v254, v93
	v_add_f32_e32 v219, v0, v219
	v_add_f32_e32 v219, v177, v219
	v_cvt_pk_fp8_f32 v248, v0, v177
	v_add_f32_e32 v219, v179, v219
	v_add_f32_e32 v219, v254, v219
	v_cvt_pk_fp8_f32 v248, v179, v254 op_sel:[0,0,1]
	v_exp_f32_e32 v0, v94
	v_exp_f32_e32 v177, v95
	v_exp_f32_e32 v179, v96
	v_exp_f32_e32 v254, v97
	v_add_f32_e32 v219, v0, v219
	v_add_f32_e32 v219, v177, v219
	v_cvt_pk_fp8_f32 v249, v0, v177
	v_add_f32_e32 v219, v179, v219
	v_add_f32_e32 v219, v254, v219
	v_cvt_pk_fp8_f32 v249, v179, v254 op_sel:[0,0,1]
	ds_read_b128 v[90:93], v185 offset:32768
	ds_read_b128 v[94:97], v186 offset:32768
	s_waitcnt lgkmcnt(4)
	v_mfma_scale_f32_32x32x64_f8f6f4 v[114:129], v[82:89], v[138:145], v[114:129], v194, v193 op_sel_hi:[0,0,0]
	v_exp_f32_e32 v0, v66
	v_exp_f32_e32 v177, v67
	v_exp_f32_e32 v179, v68
	v_exp_f32_e32 v254, v69
	v_add_f32_e32 v219, v0, v219
	v_add_f32_e32 v219, v177, v219
	v_cvt_pk_fp8_f32 v250, v0, v177
	v_add_f32_e32 v219, v179, v219
	v_add_f32_e32 v219, v254, v219
	v_cvt_pk_fp8_f32 v250, v179, v254 op_sel:[0,0,1]
	s_waitcnt lgkmcnt(2)
	v_mfma_scale_f32_32x32x64_f8f6f4 v[98:113], v[222:229], v[138:145], v[98:113], v194, v193 op_sel_hi:[0,0,0]
	ds_read_b128 v[222:225], v185 offset:34816
	ds_read_b128 v[226:229], v186 offset:34816
	v_exp_f32_e32 v0, v70
	v_exp_f32_e32 v177, v71
	v_exp_f32_e32 v179, v72
	v_exp_f32_e32 v254, v73
	v_add_f32_e32 v219, v0, v219
	v_add_f32_e32 v219, v177, v219
	v_cvt_pk_fp8_f32 v251, v0, v177
	v_add_f32_e32 v219, v179, v219
	v_add_f32_e32 v219, v254, v219
	v_cvt_pk_fp8_f32 v251, v179, v254 op_sel:[0,0,1]
	v_exp_f32_e32 v0, v74
	v_exp_f32_e32 v177, v75
	v_exp_f32_e32 v179, v76
	v_exp_f32_e32 v254, v77
	v_add_f32_e32 v219, v0, v219
	v_add_f32_e32 v219, v177, v219
	v_cvt_pk_fp8_f32 v252, v0, v177
	v_add_f32_e32 v219, v179, v219
	v_add_f32_e32 v219, v254, v219
	v_cvt_pk_fp8_f32 v252, v179, v254 op_sel:[0,0,1]
	s_waitcnt lgkmcnt(2)
	v_mfma_scale_f32_32x32x64_f8f6f4 v[114:129], v[90:97], v[130:137], v[114:129], v194, v193 op_sel_hi:[0,0,0]
	v_exp_f32_e32 v0, v78
	v_exp_f32_e32 v177, v79
	v_exp_f32_e32 v179, v80
	v_exp_f32_e32 v254, v81
	v_add_f32_e32 v219, v0, v219
	v_add_f32_e32 v219, v177, v219
	v_cvt_pk_fp8_f32 v253, v0, v177
	v_add_f32_e32 v219, v179, v219
	v_add_f32_e32 v219, v254, v219
	v_cvt_pk_fp8_f32 v253, v179, v254 op_sel:[0,0,1]
	ds_read_b128 v[90:93], v185 offset:43008
	ds_read_b128 v[94:97], v186 offset:43008
	ds_read_b128 v[82:85], v185 offset:45056
	ds_read_b128 v[86:89], v186 offset:45056
	ds_read_b128 v[74:77], v185 offset:47104
	ds_read_b128 v[78:81], v186 offset:47104
	ds_read_b128 v[66:69], v185 offset:49152
	ds_read_b128 v[70:73], v186 offset:49152
	s_waitcnt lgkmcnt(8)
	v_mfma_scale_f32_32x32x64_f8f6f4 v[98:113], v[222:229], v[130:137], v[98:113], v194, v193 op_sel_hi:[0,0,0]
	v_mov_b32_e32 v0, v219
	s_nop 1
	v_permlane32_swap_b32_e32 v219, v0
	v_add_f32_e32 v219, v219, v0
	v_fma_f32 v209, v209, v218, v219
	v_max_f32_e32 v177, v114, v115
	v_max3_f32 v177, v177, v116, v117
	v_max3_f32 v177, v177, v118, v119
	v_max3_f32 v177, v177, v120, v121
	v_max3_f32 v177, v177, v122, v123
	v_max3_f32 v177, v177, v124, v125
	v_max3_f32 v177, v177, v126, v127
	v_max3_f32 v177, v177, v128, v129
	s_waitcnt lgkmcnt(6)
	v_mfma_scale_f32_32x32x64_f8f6f4 v[50:65], v[246:253], v[90:97], v[50:65], v194, v194 op_sel_hi:[0,0,0]
	s_waitcnt lgkmcnt(4)
	v_mfma_scale_f32_32x32x64_f8f6f4 v[34:49], v[246:253], v[82:89], v[34:49], v194, v194 op_sel_hi:[0,0,0]
	s_waitcnt vmcnt(0)
	s_waitcnt lgkmcnt(0)
	s_barrier
	s_waitcnt lgkmcnt(2)
	v_mfma_scale_f32_32x32x64_f8f6f4 v[18:33], v[246:253], v[74:81], v[18:33], v194, v194 op_sel_hi:[0,0,0]
	s_add_i32 m0, s98, 0xa800
	s_nop 0
	global_load_lds_dwordx4 v176, s[18:19]
	s_add_i32 m0, s98, 0xc800
	s_nop 0
	global_load_lds_dwordx4 v178, s[16:17]
	v_add_u32_e32 v176, 0x2000, v176
	v_add_u32_e32 v178, 0x20000, v178
	s_waitcnt lgkmcnt(0)
	v_mfma_scale_f32_32x32x64_f8f6f4 v[2:17], v[246:253], v[66:73], v[2:17], v194, v194 op_sel_hi:[0,0,0]
	v_max_f32_e32 v0, v98, v99
	v_max3_f32 v0, v0, v100, v101
	v_max3_f32 v0, v0, v102, v103
	v_max3_f32 v0, v0, v104, v105
	v_max3_f32 v0, v0, v106, v107
	v_max3_f32 v0, v0, v108, v109
	v_max3_f32 v0, v0, v110, v111
	v_max3_f32 v0, v0, v112, v113
	v_max_f32_e32 v177, v177, v0
	v_mov_b32_e32 v0, v177
	v_mov_b32_e32 v221, 1.0
	s_nop 0
	v_permlane32_swap_b32_e32 v177, v0
	v_max_f32_e32 v177, v177, v0
	v_cmp_ge_f32_e32 vcc, s90, v177
	s_cmp_eq_u64 vcc, exec
	s_cbranch_scc0 .Lmla_s2_newmax
; __device__ __forceinline__ void finishSM9(f32x16& p0, f32x16& p1, float alpha, float& l_reg, v8i32& p8) {
; #pragma unroll
;   for (int r = 0; r < 16; ++r) { p0[r] = __builtin_amdgcn_exp2f(p0[r]); p1[r] = __builtin_amdgcn_exp2f(p1[r]); }
;   float ps = 0;
; #pragma unroll
;   for (int r = 0; r < 16; ++r) ps += p0[r];
; #pragma unroll
;   for (int r = 0; r < 16; ++r) ps += p1[r];
;   { auto rr = __builtin_amdgcn_permlane32_swap(__float_as_uint(ps), __float_as_uint(ps), false, false);
;     ps = __uint_as_float(rr[0]) + __uint_as_float(rr[1]); }
;   l_reg = l_reg * alpha + ps;
; #pragma unroll
;   for (int g = 0; g < 4; ++g) {
;     int w = __builtin_amdgcn_cvt_pk_fp8_f32(p0[4 * g], p0[4 * g + 1], 0, false); p8[g] = __builtin_amdgcn_cvt_pk_fp8_f32(p0[4 * g + 2], p0[4 * g + 3], w, true);
;     int u = __builtin_amdgcn_cvt_pk_fp8_f32(p1[4 * g], p1[4 * g + 1], 0, false); p8[4 + g] = __builtin_amdgcn_cvt_pk_fp8_f32(p1[4 * g + 2], p1[4 * g + 3], u, true); }
; }
; __device__ __forceinline__ void pv8(f32x16* o, const char* Vt, const v8i32 p8, int r32, int hi) {
;   const int sw = (r32 >> 2) & 3, a0 = r32 * 64 + (((hi * 2) ^ sw) << 4), a1 = r32 * 64 + (((hi * 2 + 1) ^ sw) << 4);
; #pragma unroll
;   for (int d0 = 0; d0 < 4; ++d0) {
;     const v8i32 vf = cat8(*reinterpret_cast<const v4i32*>(Vt + d0 * 2048 + a0), *reinterpret_cast<const v4i32*>(Vt + d0 * 2048 + a1));
;     o[d0] = __builtin_amdgcn_mfma_scale_f32_32x32x64_f8f6f4(p8, vf, o[d0], 0, 0, 0, 127, 0, 127); }
; }
; __device__ __forceinline__ void qkt9(f32x16& p0, f32x16& p1, const char* Kn, const char* Kr, const v8i32* qf, const float init, int r32, int hi) {
; #pragma unroll
;   for (int r = 0; r < 16; ++r) { p0[r] = init; p1[r] = init; }
; #pragma unroll
;   for (int s = 0; s < 2; ++s) { const int c0 = s * 4 + hi * 2;
;     const v8i32 a0 = cat8(*reinterpret_cast<const v4i32*>(Kn + KN8SW(r32, c0)), *reinterpret_cast<const v4i32*>(Kn + KN8SW(r32, c0 + 1)));
;     const v8i32 a1 = cat8(*reinterpret_cast<const v4i32*>(Kn + 4096 + KN8SW(r32, c0)), *reinterpret_cast<const v4i32*>(Kn + 4096 + KN8SW(r32, c0 + 1)));
;     p0 = __builtin_amdgcn_mfma_scale_f32_32x32x64_f8f6f4(a0, qf[s], p0, 0, 0, 0, 127, 0, 124);
;     p1 = __builtin_amdgcn_mfma_scale_f32_32x32x64_f8f6f4(a1, qf[s], p1, 0, 0, 0, 127, 0, 124); }
;   { const int c0 = hi * 2;
.Lmla_s2_cont:
	ds_read_b128 v[82:85], v215 offset:24576
	ds_read_b128 v[86:89], v216 offset:24576
	ds_read_b128 v[222:225], v215 offset:28672
	ds_read_b128 v[226:229], v216 offset:28672
	v_exp_f32_e32 v0, v114
	v_exp_f32_e32 v177, v115
	v_exp_f32_e32 v179, v116
	v_exp_f32_e32 v254, v117
	v_add_f32_e32 v219, v0, v177
	v_cvt_pk_fp8_f32 v246, v0, v177
	v_add_f32_e32 v219, v179, v219
	v_add_f32_e32 v219, v254, v219
	v_cvt_pk_fp8_f32 v246, v179, v254 op_sel:[0,0,1]
	s_waitcnt lgkmcnt(2)
	v_mfma_scale_f32_32x32x64_f8f6f4 v[82:97], v[82:89], v[146:153], v[230:245], v194, v193 op_sel_hi:[0,0,0]
	v_exp_f32_e32 v0, v118
	v_exp_f32_e32 v177, v119
	v_exp_f32_e32 v179, v120
	v_exp_f32_e32 v254, v121
	v_add_f32_e32 v219, v0, v219
	v_add_f32_e32 v219, v177, v219
	v_cvt_pk_fp8_f32 v247, v0, v177
	v_add_f32_e32 v219, v179, v219
	v_add_f32_e32 v219, v254, v219
	v_cvt_pk_fp8_f32 v247, v179, v254 op_sel:[0,0,1]
	ds_read_b128 v[114:117], v213 offset:24576
	ds_read_b128 v[118:121], v214 offset:24576
	s_waitcnt lgkmcnt(2)
	v_mfma_scale_f32_32x32x64_f8f6f4 v[66:81], v[222:229], v[146:153], v[230:245], v194, v193 op_sel_hi:[0,0,0]
	ds_read_b128 v[222:225], v213 offset:28672
	ds_read_b128 v[226:229], v214 offset:28672
	v_exp_f32_e32 v0, v122
	v_exp_f32_e32 v177, v123
	v_exp_f32_e32 v179, v124
	v_exp_f32_e32 v254, v125
	v_add_f32_e32 v219, v0, v219
	v_add_f32_e32 v219, v177, v219
	v_cvt_pk_fp8_f32 v248, v0, v177
	v_add_f32_e32 v219, v179, v219
	v_add_f32_e32 v219, v254, v219
	v_cvt_pk_fp8_f32 v248, v179, v254 op_sel:[0,0,1]
	v_exp_f32_e32 v0, v126
	v_exp_f32_e32 v177, v127
	v_exp_f32_e32 v179, v128
	v_exp_f32_e32 v254, v129
	v_add_f32_e32 v219, v0, v219
	v_add_f32_e32 v219, v177, v219
	v_cvt_pk_fp8_f32 v249, v0, v177
	v_add_f32_e32 v219, v179, v219
	v_add_f32_e32 v219, v254, v219
	v_cvt_pk_fp8_f32 v249, v179, v254 op_sel:[0,0,1]
	ds_read_b128 v[122:125], v185 offset:36864
	ds_read_b128 v[126:129], v186 offset:36864
	s_waitcnt lgkmcnt(4)
	v_mfma_scale_f32_32x32x64_f8f6f4 v[82:97], v[114:121], v[138:145], v[82:97], v194, v193 op_sel_hi:[0,0,0]
	v_exp_f32_e32 v0, v98
	v_exp_f32_e32 v177, v99
	v_exp_f32_e32 v179, v100
	v_exp_f32_e32 v254, v101
	v_add_f32_e32 v219, v0, v219
	v_add_f32_e32 v219, v177, v219
	v_cvt_pk_fp8_f32 v250, v0, v177
	v_add_f32_e32 v219, v179, v219
	v_add_f32_e32 v219, v254, v219
	v_cvt_pk_fp8_f32 v250, v179, v254 op_sel:[0,0,1]
	s_waitcnt lgkmcnt(2)
	v_mfma_scale_f32_32x32x64_f8f6f4 v[66:81], v[222:229], v[138:145], v[66:81], v194, v193 op_sel_hi:[0,0,0]
	ds_read_b128 v[222:225], v185 offset:38912
	ds_read_b128 v[226:229], v186 offset:38912
	v_exp_f32_e32 v0, v102
	v_exp_f32_e32 v177, v103
	v_exp_f32_e32 v179, v104
	v_exp_f32_e32 v254, v105
	v_add_f32_e32 v219, v0, v219
	v_add_f32_e32 v219, v177, v219
	v_cvt_pk_fp8_f32 v251, v0, v177
	v_add_f32_e32 v219, v179, v219
	v_add_f32_e32 v219, v254, v219
	v_cvt_pk_fp8_f32 v251, v179, v254 op_sel:[0,0,1]
	v_exp_f32_e32 v0, v106
	v_exp_f32_e32 v177, v107
	v_exp_f32_e32 v179, v108
	v_exp_f32_e32 v254, v109
	v_add_f32_e32 v219, v0, v219
	v_add_f32_e32 v219, v177, v219
	v_cvt_pk_fp8_f32 v252, v0, v177
	v_add_f32_e32 v219, v179, v219
	v_add_f32_e32 v219, v254, v219
	v_cvt_pk_fp8_f32 v252, v179, v254 op_sel:[0,0,1]
	s_waitcnt lgkmcnt(2)
	v_mfma_scale_f32_32x32x64_f8f6f4 v[82:97], v[122:129], v[130:137], v[82:97], v194, v193 op_sel_hi:[0,0,0]
	v_exp_f32_e32 v0, v110
	v_exp_f32_e32 v177, v111
	v_exp_f32_e32 v179, v112
	v_exp_f32_e32 v254, v113
	v_add_f32_e32 v219, v0, v219
	v_add_f32_e32 v219, v177, v219
	v_cvt_pk_fp8_f32 v253, v0, v177
	v_add_f32_e32 v219, v179, v219
	v_add_f32_e32 v219, v254, v219
	v_cvt_pk_fp8_f32 v253, v179, v254 op_sel:[0,0,1]
	ds_read_b128 v[122:125], v185 offset:0
	ds_read_b128 v[126:129], v186 offset:0
	ds_read_b128 v[114:117], v185 offset:2048
	ds_read_b128 v[118:121], v186 offset:2048
	ds_read_b128 v[106:109], v185 offset:4096
	ds_read_b128 v[110:113], v186 offset:4096
	ds_read_b128 v[98:101], v185 offset:6144
	ds_read_b128 v[102:105], v186 offset:6144
	s_waitcnt lgkmcnt(8)
	v_mfma_scale_f32_32x32x64_f8f6f4 v[66:81], v[222:229], v[130:137], v[66:81], v194, v193 op_sel_hi:[0,0,0]
	v_mov_b32_e32 v0, v219
	s_nop 1
	v_permlane32_swap_b32_e32 v219, v0
	v_add_f32_e32 v219, v219, v0
	v_fma_f32 v209, v209, v221, v219
	v_max_f32_e32 v177, v82, v83
	v_max3_f32 v177, v177, v84, v85
	v_max3_f32 v177, v177, v86, v87
	v_max3_f32 v177, v177, v88, v89
	v_max3_f32 v177, v177, v90, v91
	v_max3_f32 v177, v177, v92, v93
	v_max3_f32 v177, v177, v94, v95
	v_max3_f32 v177, v177, v96, v97
	s_waitcnt lgkmcnt(6)
	v_mfma_scale_f32_32x32x64_f8f6f4 v[50:65], v[246:253], v[122:129], v[50:65], v194, v194 op_sel_hi:[0,0,0]
	s_waitcnt lgkmcnt(4)
	v_mfma_scale_f32_32x32x64_f8f6f4 v[34:49], v[246:253], v[114:121], v[34:49], v194, v194 op_sel_hi:[0,0,0]
	s_waitcnt vmcnt(0)
	s_waitcnt lgkmcnt(0)
	s_barrier
	s_waitcnt lgkmcnt(2)
	v_mfma_scale_f32_32x32x64_f8f6f4 v[18:33], v[246:253], v[106:113], v[18:33], v194, v194 op_sel_hi:[0,0,0]
	s_add_i32 m0, s98, 0x0
	s_nop 0
	global_load_lds_dwordx4 v176, s[18:19]
	s_add_i32 m0, s98, 0x4000
	s_nop 0
	global_load_lds_dwordx4 v178, s[16:17]
	v_add_u32_e32 v176, 0x2000, v176
	v_add_u32_e32 v178, 0x20000, v178
	s_waitcnt lgkmcnt(0)
	v_mfma_scale_f32_32x32x64_f8f6f4 v[2:17], v[246:253], v[98:105], v[2:17], v194, v194 op_sel_hi:[0,0,0]
	v_max_f32_e32 v0, v66, v67
	v_max3_f32 v0, v0, v68, v69
	v_max3_f32 v0, v0, v70, v71
	v_max3_f32 v0, v0, v72, v73
	v_max3_f32 v0, v0, v74, v75
	v_max3_f32 v0, v0, v76, v77
	v_max3_f32 v0, v0, v78, v79
	v_max3_f32 v0, v0, v80, v81
	v_max_f32_e32 v177, v177, v0
	v_mov_b32_e32 v0, v177
	v_mov_b32_e32 v218, 1.0
	s_nop 0
	v_permlane32_swap_b32_e32 v177, v0
	v_max_f32_e32 v177, v177, v0
	v_cmp_ge_f32_e32 vcc, s90, v177
	s_cmp_eq_u64 vcc, exec
	s_cbranch_scc0 .Lmla_s3_newmax
; __device__ __forceinline__ void finishSM9(f32x16& p0, f32x16& p1, float alpha, float& l_reg, v8i32& p8) {
; #pragma unroll
;   for (int r = 0; r < 16; ++r) { p0[r] = __builtin_amdgcn_exp2f(p0[r]); p1[r] = __builtin_amdgcn_exp2f(p1[r]); }
;   float ps = 0;
; #pragma unroll
;   for (int r = 0; r < 16; ++r) ps += p0[r];
; #pragma unroll
;   for (int r = 0; r < 16; ++r) ps += p1[r];
;   { auto rr = __builtin_amdgcn_permlane32_swap(__float_as_uint(ps), __float_as_uint(ps), false, false);
;     ps = __uint_as_float(rr[0]) + __uint_as_float(rr[1]); }
;   l_reg = l_reg * alpha + ps;
; #pragma unroll
;   for (int g = 0; g < 4; ++g) {
;     int w = __builtin_amdgcn_cvt_pk_fp8_f32(p0[4 * g], p0[4 * g + 1], 0, false); p8[g] = __builtin_amdgcn_cvt_pk_fp8_f32(p0[4 * g + 2], p0[4 * g + 3], w, true);
;     int u = __builtin_amdgcn_cvt_pk_fp8_f32(p1[4 * g], p1[4 * g + 1], 0, false); p8[4 + g] = __builtin_amdgcn_cvt_pk_fp8_f32(p1[4 * g + 2], p1[4 * g + 3], u, true); }
; }
; __device__ __forceinline__ void pv8(f32x16* o, const char* Vt, const v8i32 p8, int r32, int hi) {
;   const int sw = (r32 >> 2) & 3, a0 = r32 * 64 + (((hi * 2) ^ sw) << 4), a1 = r32 * 64 + (((hi * 2 + 1) ^ sw) << 4);
; #pragma unroll
;   for (int d0 = 0; d0 < 4; ++d0) {
;     const v8i32 vf = cat8(*reinterpret_cast<const v4i32*>(Vt + d0 * 2048 + a0), *reinterpret_cast<const v4i32*>(Vt + d0 * 2048 + a1));
;     o[d0] = __builtin_amdgcn_mfma_scale_f32_32x32x64_f8f6f4(p8, vf, o[d0], 0, 0, 0, 127, 0, 127); }
; }
; __device__ __forceinline__ void qkt9(f32x16& p0, f32x16& p1, const char* Kn, const char* Kr, const v8i32* qf, const float init, int r32, int hi) {
; #pragma unroll
;   for (int r = 0; r < 16; ++r) { p0[r] = init; p1[r] = init; }
; #pragma unroll
;   for (int s = 0; s < 2; ++s) { const int c0 = s * 4 + hi * 2;
;     const v8i32 a0 = cat8(*reinterpret_cast<const v4i32*>(Kn + KN8SW(r32, c0)), *reinterpret_cast<const v4i32*>(Kn + KN8SW(r32, c0 + 1)));
;     const v8i32 a1 = cat8(*reinterpret_cast<const v4i32*>(Kn + 4096 + KN8SW(r32, c0)), *reinterpret_cast<const v4i32*>(Kn + 4096 + KN8SW(r32, c0 + 1)));
;     p0 = __builtin_amdgcn_mfma_scale_f32_32x32x64_f8f6f4(a0, qf[s], p0, 0, 0, 0, 127, 0, 124);
;     p1 = __builtin_amdgcn_mfma_scale_f32_32x32x64_f8f6f4(a1, qf[s], p1, 0, 0, 0, 127, 0, 124); }
;   { const int c0 = hi * 2;
.Lmla_s3_cont:
	ds_read_b128 v[114:117], v215 offset:51200
	ds_read_b128 v[118:121], v216 offset:51200
	ds_read_b128 v[222:225], v215 offset:55296
	ds_read_b128 v[226:229], v216 offset:55296
	v_exp_f32_e32 v0, v82
	v_exp_f32_e32 v177, v83
	v_exp_f32_e32 v179, v84
	v_exp_f32_e32 v254, v85
	v_add_f32_e32 v219, v0, v177
	v_cvt_pk_fp8_f32 v246, v0, v177
	v_add_f32_e32 v219, v179, v219
	v_add_f32_e32 v219, v254, v219
	v_cvt_pk_fp8_f32 v246, v179, v254 op_sel:[0,0,1]
	s_waitcnt lgkmcnt(2)
	v_mfma_scale_f32_32x32x64_f8f6f4 v[114:129], v[114:121], v[146:153], v[230:245], v194, v193 op_sel_hi:[0,0,0]
	v_exp_f32_e32 v0, v86
	v_exp_f32_e32 v177, v87
	v_exp_f32_e32 v179, v88
	v_exp_f32_e32 v254, v89
	v_add_f32_e32 v219, v0, v219
	v_add_f32_e32 v219, v177, v219
	v_cvt_pk_fp8_f32 v247, v0, v177
	v_add_f32_e32 v219, v179, v219
	v_add_f32_e32 v219, v254, v219
	v_cvt_pk_fp8_f32 v247, v179, v254 op_sel:[0,0,1]
	ds_read_b128 v[82:85], v213 offset:51200
	ds_read_b128 v[86:89], v214 offset:51200
	s_waitcnt lgkmcnt(2)
	v_mfma_scale_f32_32x32x64_f8f6f4 v[98:113], v[222:229], v[146:153], v[230:245], v194, v193 op_sel_hi:[0,0,0]
	ds_read_b128 v[222:225], v213 offset:55296
	ds_read_b128 v[226:229], v214 offset:55296
	v_exp_f32_e32 v0, v90
	v_exp_f32_e32 v177, v91
	v_exp_f32_e32 v179, v92
	v_exp_f32_e32 v254, v93
	v_add_f32_e32 v219, v0, v219
	v_add_f32_e32 v219, v177, v219
	v_cvt_pk_fp8_f32 v248, v0, v177
	v_add_f32_e32 v219, v179, v219
	v_add_f32_e32 v219, v254, v219
	v_cvt_pk_fp8_f32 v248, v179, v254 op_sel:[0,0,1]
	v_exp_f32_e32 v0, v94
	v_exp_f32_e32 v177, v95
	v_exp_f32_e32 v179, v96
	v_exp_f32_e32 v254, v97
	v_add_f32_e32 v219, v0, v219
	v_add_f32_e32 v219, v177, v219
	v_cvt_pk_fp8_f32 v249, v0, v177
	v_add_f32_e32 v219, v179, v219
	v_add_f32_e32 v219, v254, v219
	v_cvt_pk_fp8_f32 v249, v179, v254 op_sel:[0,0,1]
	ds_read_b128 v[90:93], v185 offset:59392
	ds_read_b128 v[94:97], v186 offset:59392
	s_waitcnt lgkmcnt(4)
	v_mfma_scale_f32_32x32x64_f8f6f4 v[114:129], v[82:89], v[138:145], v[114:129], v194, v193 op_sel_hi:[0,0,0]
	v_exp_f32_e32 v0, v66
	v_exp_f32_e32 v177, v67
	v_exp_f32_e32 v179, v68
	v_exp_f32_e32 v254, v69
	v_add_f32_e32 v219, v0, v219
	v_add_f32_e32 v219, v177, v219
	v_cvt_pk_fp8_f32 v250, v0, v177
	v_add_f32_e32 v219, v179, v219
	v_add_f32_e32 v219, v254, v219
	v_cvt_pk_fp8_f32 v250, v179, v254 op_sel:[0,0,1]
	s_waitcnt lgkmcnt(2)
	v_mfma_scale_f32_32x32x64_f8f6f4 v[98:113], v[222:229], v[138:145], v[98:113], v194, v193 op_sel_hi:[0,0,0]
	ds_read_b128 v[222:225], v185 offset:61440
	ds_read_b128 v[226:229], v186 offset:61440
	v_exp_f32_e32 v0, v70
	v_exp_f32_e32 v177, v71
	v_exp_f32_e32 v179, v72
	v_exp_f32_e32 v254, v73
	v_add_f32_e32 v219, v0, v219
	v_add_f32_e32 v219, v177, v219
	v_cvt_pk_fp8_f32 v251, v0, v177
	v_add_f32_e32 v219, v179, v219
	v_add_f32_e32 v219, v254, v219
	v_cvt_pk_fp8_f32 v251, v179, v254 op_sel:[0,0,1]
	v_exp_f32_e32 v0, v74
	v_exp_f32_e32 v177, v75
	v_exp_f32_e32 v179, v76
	v_exp_f32_e32 v254, v77
	v_add_f32_e32 v219, v0, v219
	v_add_f32_e32 v219, v177, v219
	v_cvt_pk_fp8_f32 v252, v0, v177
	v_add_f32_e32 v219, v179, v219
	v_add_f32_e32 v219, v254, v219
	v_cvt_pk_fp8_f32 v252, v179, v254 op_sel:[0,0,1]
	s_waitcnt lgkmcnt(2)
	v_mfma_scale_f32_32x32x64_f8f6f4 v[114:129], v[90:97], v[130:137], v[114:129], v194, v193 op_sel_hi:[0,0,0]
	v_exp_f32_e32 v0, v78
	v_exp_f32_e32 v177, v79
	v_exp_f32_e32 v179, v80
	v_exp_f32_e32 v254, v81
	v_add_f32_e32 v219, v0, v219
	v_add_f32_e32 v219, v177, v219
	v_cvt_pk_fp8_f32 v253, v0, v177
	v_add_f32_e32 v219, v179, v219
	v_add_f32_e32 v219, v254, v219
	v_cvt_pk_fp8_f32 v253, v179, v254 op_sel:[0,0,1]
	ds_read_b128 v[90:93], v185 offset:8192
	ds_read_b128 v[94:97], v186 offset:8192
	ds_read_b128 v[82:85], v185 offset:10240
	ds_read_b128 v[86:89], v186 offset:10240
	ds_read_b128 v[74:77], v185 offset:12288
	ds_read_b128 v[78:81], v186 offset:12288
	ds_read_b128 v[66:69], v185 offset:14336
	ds_read_b128 v[70:73], v186 offset:14336
	s_waitcnt lgkmcnt(8)
	v_mfma_scale_f32_32x32x64_f8f6f4 v[98:113], v[222:229], v[130:137], v[98:113], v194, v193 op_sel_hi:[0,0,0]
	v_mov_b32_e32 v0, v219
	s_nop 1
	v_permlane32_swap_b32_e32 v219, v0
	v_add_f32_e32 v219, v219, v0
	v_fma_f32 v209, v209, v218, v219
	v_max_f32_e32 v177, v114, v115
	v_max3_f32 v177, v177, v116, v117
	v_max3_f32 v177, v177, v118, v119
	v_max3_f32 v177, v177, v120, v121
	v_max3_f32 v177, v177, v122, v123
	v_max3_f32 v177, v177, v124, v125
	v_max3_f32 v177, v177, v126, v127
	v_max3_f32 v177, v177, v128, v129
	s_waitcnt lgkmcnt(6)
	v_mfma_scale_f32_32x32x64_f8f6f4 v[50:65], v[246:253], v[90:97], v[50:65], v194, v194 op_sel_hi:[0,0,0]
	s_waitcnt lgkmcnt(4)
	v_mfma_scale_f32_32x32x64_f8f6f4 v[34:49], v[246:253], v[82:89], v[34:49], v194, v194 op_sel_hi:[0,0,0]
	s_waitcnt vmcnt(0)
	s_waitcnt lgkmcnt(0)
	s_barrier
	s_waitcnt lgkmcnt(2)
	v_mfma_scale_f32_32x32x64_f8f6f4 v[18:33], v[246:253], v[74:81], v[18:33], v194, v194 op_sel_hi:[0,0,0]
	s_add_i32 m0, s98, 0x2000
	s_nop 0
	global_load_lds_dwordx4 v176, s[18:19]
	s_add_i32 m0, s98, 0x6000
	s_nop 0
	global_load_lds_dwordx4 v178, s[16:17]
	v_add_u32_e32 v176, 0x2000, v176
	v_add_u32_e32 v178, 0x20000, v178
	s_waitcnt lgkmcnt(0)
	v_mfma_scale_f32_32x32x64_f8f6f4 v[2:17], v[246:253], v[66:73], v[2:17], v194, v194 op_sel_hi:[0,0,0]
	v_max_f32_e32 v0, v98, v99
	v_max3_f32 v0, v0, v100, v101
	v_max3_f32 v0, v0, v102, v103
	v_max3_f32 v0, v0, v104, v105
	v_max3_f32 v0, v0, v106, v107
	v_max3_f32 v0, v0, v108, v109
	v_max3_f32 v0, v0, v110, v111
	v_max3_f32 v0, v0, v112, v113
	v_max_f32_e32 v177, v177, v0
	v_mov_b32_e32 v0, v177
	v_mov_b32_e32 v221, 1.0
	s_nop 0
	v_permlane32_swap_b32_e32 v177, v0
	v_max_f32_e32 v177, v177, v0
	v_cmp_ge_f32_e32 vcc, s90, v177
	s_cmp_eq_u64 vcc, exec
	s_cbranch_scc0 .Lmla_s4_newmax
; __device__ __forceinline__ void finishSM9(f32x16& p0, f32x16& p1, float alpha, float& l_reg, v8i32& p8) {
; #pragma unroll
;   for (int r = 0; r < 16; ++r) { p0[r] = __builtin_amdgcn_exp2f(p0[r]); p1[r] = __builtin_amdgcn_exp2f(p1[r]); }
;   float ps = 0;
; #pragma unroll
;   for (int r = 0; r < 16; ++r) ps += p0[r];
; #pragma unroll
;   for (int r = 0; r < 16; ++r) ps += p1[r];
;   { auto rr = __builtin_amdgcn_permlane32_swap(__float_as_uint(ps), __float_as_uint(ps), false, false);
;     ps = __uint_as_float(rr[0]) + __uint_as_float(rr[1]); }
;   l_reg = l_reg * alpha + ps;
; #pragma unroll
;   for (int g = 0; g < 4; ++g) {
;     int w = __builtin_amdgcn_cvt_pk_fp8_f32(p0[4 * g], p0[4 * g + 1], 0, false); p8[g] = __builtin_amdgcn_cvt_pk_fp8_f32(p0[4 * g + 2], p0[4 * g + 3], w, true);
;     int u = __builtin_amdgcn_cvt_pk_fp8_f32(p1[4 * g], p1[4 * g + 1], 0, false); p8[4 + g] = __builtin_amdgcn_cvt_pk_fp8_f32(p1[4 * g + 2], p1[4 * g + 3], u, true); }
; }
; __device__ __forceinline__ void pv8(f32x16* o, const char* Vt, const v8i32 p8, int r32, int hi) {
;   const int sw = (r32 >> 2) & 3, a0 = r32 * 64 + (((hi * 2) ^ sw) << 4), a1 = r32 * 64 + (((hi * 2 + 1) ^ sw) << 4);
; #pragma unroll
;   for (int d0 = 0; d0 < 4; ++d0) {
;     const v8i32 vf = cat8(*reinterpret_cast<const v4i32*>(Vt + d0 * 2048 + a0), *reinterpret_cast<const v4i32*>(Vt + d0 * 2048 + a1));
;     o[d0] = __builtin_amdgcn_mfma_scale_f32_32x32x64_f8f6f4(p8, vf, o[d0], 0, 0, 0, 127, 0, 127); }
; }
; __device__ __forceinline__ void qkt9(f32x16& p0, f32x16& p1, const char* Kn, const char* Kr, const v8i32* qf, const float init, int r32, int hi) {
; #pragma unroll
;   for (int r = 0; r < 16; ++r) { p0[r] = init; p1[r] = init; }
; #pragma unroll
;   for (int s = 0; s < 2; ++s) { const int c0 = s * 4 + hi * 2;
;     const v8i32 a0 = cat8(*reinterpret_cast<const v4i32*>(Kn + KN8SW(r32, c0)), *reinterpret_cast<const v4i32*>(Kn + KN8SW(r32, c0 + 1)));
;     const v8i32 a1 = cat8(*reinterpret_cast<const v4i32*>(Kn + 4096 + KN8SW(r32, c0)), *reinterpret_cast<const v4i32*>(Kn + 4096 + KN8SW(r32, c0 + 1)));
;     p0 = __builtin_amdgcn_mfma_scale_f32_32x32x64_f8f6f4(a0, qf[s], p0, 0, 0, 0, 127, 0, 124);
;     p1 = __builtin_amdgcn_mfma_scale_f32_32x32x64_f8f6f4(a1, qf[s], p1, 0, 0, 0, 127, 0, 124); }
;   { const int c0 = hi * 2;
.Lmla_s4_cont:
	ds_read_b128 v[82:85], v215 offset:16384
	ds_read_b128 v[86:89], v216 offset:16384
	ds_read_b128 v[222:225], v215 offset:20480
	ds_read_b128 v[226:229], v216 offset:20480
	v_exp_f32_e32 v0, v114
	v_exp_f32_e32 v177, v115
	v_exp_f32_e32 v179, v116
	v_exp_f32_e32 v254, v117
	v_add_f32_e32 v219, v0, v177
	v_cvt_pk_fp8_f32 v246, v0, v177
	v_add_f32_e32 v219, v179, v219
	v_add_f32_e32 v219, v254, v219
	v_cvt_pk_fp8_f32 v246, v179, v254 op_sel:[0,0,1]
	s_waitcnt lgkmcnt(2)
	v_mfma_scale_f32_32x32x64_f8f6f4 v[82:97], v[82:89], v[146:153], v[230:245], v194, v193 op_sel_hi:[0,0,0]
	v_exp_f32_e32 v0, v118
	v_exp_f32_e32 v177, v119
	v_exp_f32_e32 v179, v120
	v_exp_f32_e32 v254, v121
	v_add_f32_e32 v219, v0, v219
	v_add_f32_e32 v219, v177, v219
	v_cvt_pk_fp8_f32 v247, v0, v177
	v_add_f32_e32 v219, v179, v219
	v_add_f32_e32 v219, v254, v219
	v_cvt_pk_fp8_f32 v247, v179, v254 op_sel:[0,0,1]
	ds_read_b128 v[114:117], v213 offset:16384
	ds_read_b128 v[118:121], v214 offset:16384
	s_waitcnt lgkmcnt(2)
	v_mfma_scale_f32_32x32x64_f8f6f4 v[66:81], v[222:229], v[146:153], v[230:245], v194, v193 op_sel_hi:[0,0,0]
	ds_read_b128 v[222:225], v213 offset:20480
	ds_read_b128 v[226:229], v214 offset:20480
	v_exp_f32_e32 v0, v122
	v_exp_f32_e32 v177, v123
	v_exp_f32_e32 v179, v124
	v_exp_f32_e32 v254, v125
	v_add_f32_e32 v219, v0, v219
	v_add_f32_e32 v219, v177, v219
	v_cvt_pk_fp8_f32 v248, v0, v177
	v_add_f32_e32 v219, v179, v219
	v_add_f32_e32 v219, v254, v219
	v_cvt_pk_fp8_f32 v248, v179, v254 op_sel:[0,0,1]
	v_exp_f32_e32 v0, v126
	v_exp_f32_e32 v177, v127
	v_exp_f32_e32 v179, v128
	v_exp_f32_e32 v254, v129
	v_add_f32_e32 v219, v0, v219
	v_add_f32_e32 v219, v177, v219
	v_cvt_pk_fp8_f32 v249, v0, v177
	v_add_f32_e32 v219, v179, v219
	v_add_f32_e32 v219, v254, v219
	v_cvt_pk_fp8_f32 v249, v179, v254 op_sel:[0,0,1]
	ds_read_b128 v[122:125], v185 offset:32768
	ds_read_b128 v[126:129], v186 offset:32768
	s_waitcnt lgkmcnt(4)
	v_mfma_scale_f32_32x32x64_f8f6f4 v[82:97], v[114:121], v[138:145], v[82:97], v194, v193 op_sel_hi:[0,0,0]
	v_exp_f32_e32 v0, v98
	v_exp_f32_e32 v177, v99
	v_exp_f32_e32 v179, v100
	v_exp_f32_e32 v254, v101
	v_add_f32_e32 v219, v0, v219
	v_add_f32_e32 v219, v177, v219
	v_cvt_pk_fp8_f32 v250, v0, v177
	v_add_f32_e32 v219, v179, v219
	v_add_f32_e32 v219, v254, v219
	v_cvt_pk_fp8_f32 v250, v179, v254 op_sel:[0,0,1]
	s_waitcnt lgkmcnt(2)
	v_mfma_scale_f32_32x32x64_f8f6f4 v[66:81], v[222:229], v[138:145], v[66:81], v194, v193 op_sel_hi:[0,0,0]
	ds_read_b128 v[222:225], v185 offset:34816
	ds_read_b128 v[226:229], v186 offset:34816
	v_exp_f32_e32 v0, v102
	v_exp_f32_e32 v177, v103
	v_exp_f32_e32 v179, v104
	v_exp_f32_e32 v254, v105
	v_add_f32_e32 v219, v0, v219
	v_add_f32_e32 v219, v177, v219
	v_cvt_pk_fp8_f32 v251, v0, v177
	v_add_f32_e32 v219, v179, v219
	v_add_f32_e32 v219, v254, v219
	v_cvt_pk_fp8_f32 v251, v179, v254 op_sel:[0,0,1]
	v_exp_f32_e32 v0, v106
	v_exp_f32_e32 v177, v107
	v_exp_f32_e32 v179, v108
	v_exp_f32_e32 v254, v109
	v_add_f32_e32 v219, v0, v219
	v_add_f32_e32 v219, v177, v219
	v_cvt_pk_fp8_f32 v252, v0, v177
	v_add_f32_e32 v219, v179, v219
	v_add_f32_e32 v219, v254, v219
	v_cvt_pk_fp8_f32 v252, v179, v254 op_sel:[0,0,1]
	s_waitcnt lgkmcnt(2)
	v_mfma_scale_f32_32x32x64_f8f6f4 v[82:97], v[122:129], v[130:137], v[82:97], v194, v193 op_sel_hi:[0,0,0]
	v_exp_f32_e32 v0, v110
	v_exp_f32_e32 v177, v111
	v_exp_f32_e32 v179, v112
	v_exp_f32_e32 v254, v113
	v_add_f32_e32 v219, v0, v219
	v_add_f32_e32 v219, v177, v219
	v_cvt_pk_fp8_f32 v253, v0, v177
	v_add_f32_e32 v219, v179, v219
	v_add_f32_e32 v219, v254, v219
	v_cvt_pk_fp8_f32 v253, v179, v254 op_sel:[0,0,1]
	ds_read_b128 v[122:125], v185 offset:43008
	ds_read_b128 v[126:129], v186 offset:43008
	ds_read_b128 v[114:117], v185 offset:45056
	ds_read_b128 v[118:121], v186 offset:45056
	ds_read_b128 v[106:109], v185 offset:47104
	ds_read_b128 v[110:113], v186 offset:47104
	ds_read_b128 v[98:101], v185 offset:49152
	ds_read_b128 v[102:105], v186 offset:49152
	s_waitcnt lgkmcnt(8)
	v_mfma_scale_f32_32x32x64_f8f6f4 v[66:81], v[222:229], v[130:137], v[66:81], v194, v193 op_sel_hi:[0,0,0]
	v_mov_b32_e32 v0, v219
	s_nop 1
	v_permlane32_swap_b32_e32 v219, v0
	v_add_f32_e32 v219, v219, v0
	v_fma_f32 v209, v209, v221, v219
	v_max_f32_e32 v177, v82, v83
	v_max3_f32 v177, v177, v84, v85
	v_max3_f32 v177, v177, v86, v87
	v_max3_f32 v177, v177, v88, v89
	v_max3_f32 v177, v177, v90, v91
	v_max3_f32 v177, v177, v92, v93
	v_max3_f32 v177, v177, v94, v95
	v_max3_f32 v177, v177, v96, v97
	s_waitcnt lgkmcnt(6)
	v_mfma_scale_f32_32x32x64_f8f6f4 v[50:65], v[246:253], v[122:129], v[50:65], v194, v194 op_sel_hi:[0,0,0]
	s_waitcnt lgkmcnt(4)
	v_mfma_scale_f32_32x32x64_f8f6f4 v[34:49], v[246:253], v[114:121], v[34:49], v194, v194 op_sel_hi:[0,0,0]
	s_waitcnt vmcnt(0)
	s_waitcnt lgkmcnt(0)
	s_barrier
	s_waitcnt lgkmcnt(2)
	v_mfma_scale_f32_32x32x64_f8f6f4 v[18:33], v[246:253], v[106:113], v[18:33], v194, v194 op_sel_hi:[0,0,0]
	s_add_i32 m0, s98, 0xa800
	s_nop 0
	global_load_lds_dwordx4 v176, s[18:19]
	s_add_i32 m0, s98, 0xc800
	s_nop 0
	global_load_lds_dwordx4 v178, s[16:17]
	v_add_u32_e32 v176, 0x2000, v176
	v_add_u32_e32 v178, 0x20000, v178
	s_waitcnt lgkmcnt(0)
	v_mfma_scale_f32_32x32x64_f8f6f4 v[2:17], v[246:253], v[98:105], v[2:17], v194, v194 op_sel_hi:[0,0,0]
	v_max_f32_e32 v0, v66, v67
	v_max3_f32 v0, v0, v68, v69
	v_max3_f32 v0, v0, v70, v71
	v_max3_f32 v0, v0, v72, v73
	v_max3_f32 v0, v0, v74, v75
	v_max3_f32 v0, v0, v76, v77
	v_max3_f32 v0, v0, v78, v79
	v_max3_f32 v0, v0, v80, v81
	v_max_f32_e32 v177, v177, v0
	v_mov_b32_e32 v0, v177
	v_mov_b32_e32 v218, 1.0
	s_nop 0
	v_permlane32_swap_b32_e32 v177, v0
	v_max_f32_e32 v177, v177, v0
	v_cmp_ge_f32_e32 vcc, s90, v177
	s_cmp_eq_u64 vcc, exec
	s_cbranch_scc0 .Lmla_s5_newmax
; __device__ __forceinline__ void finishSM9(f32x16& p0, f32x16& p1, float alpha, float& l_reg, v8i32& p8) {
; #pragma unroll
;   for (int r = 0; r < 16; ++r) { p0[r] = __builtin_amdgcn_exp2f(p0[r]); p1[r] = __builtin_amdgcn_exp2f(p1[r]); }
;   float ps = 0;
; #pragma unroll
;   for (int r = 0; r < 16; ++r) ps += p0[r];
; #pragma unroll
;   for (int r = 0; r < 16; ++r) ps += p1[r];
;   { auto rr = __builtin_amdgcn_permlane32_swap(__float_as_uint(ps), __float_as_uint(ps), false, false);
;     ps = __uint_as_float(rr[0]) + __uint_as_float(rr[1]); }
;   l_reg = l_reg * alpha + ps;
; #pragma unroll
;   for (int g = 0; g < 4; ++g) {
;     int w = __builtin_amdgcn_cvt_pk_fp8_f32(p0[4 * g], p0[4 * g + 1], 0, false); p8[g] = __builtin_amdgcn_cvt_pk_fp8_f32(p0[4 * g + 2], p0[4 * g + 3], w, true);
;     int u = __builtin_amdgcn_cvt_pk_fp8_f32(p1[4 * g], p1[4 * g + 1], 0, false); p8[4 + g] = __builtin_amdgcn_cvt_pk_fp8_f32(p1[4 * g + 2], p1[4 * g + 3], u, true); }
; }
; __device__ __forceinline__ void pv8(f32x16* o, const char* Vt, const v8i32 p8, int r32, int hi) {
;   const int sw = (r32 >> 2) & 3, a0 = r32 * 64 + (((hi * 2) ^ sw) << 4), a1 = r32 * 64 + (((hi * 2 + 1) ^ sw) << 4);
; #pragma unroll
;   for (int d0 = 0; d0 < 4; ++d0) {
;     const v8i32 vf = cat8(*reinterpret_cast<const v4i32*>(Vt + d0 * 2048 + a0), *reinterpret_cast<const v4i32*>(Vt + d0 * 2048 + a1));
;     o[d0] = __builtin_amdgcn_mfma_scale_f32_32x32x64_f8f6f4(p8, vf, o[d0], 0, 0, 0, 127, 0, 127); }
; }
; __device__ __forceinline__ void qkt9(f32x16& p0, f32x16& p1, const char* Kn, const char* Kr, const v8i32* qf, const float init, int r32, int hi) {
; #pragma unroll
;   for (int r = 0; r < 16; ++r) { p0[r] = init; p1[r] = init; }
; #pragma unroll
;   for (int s = 0; s < 2; ++s) { const int c0 = s * 4 + hi * 2;
;     const v8i32 a0 = cat8(*reinterpret_cast<const v4i32*>(Kn + KN8SW(r32, c0)), *reinterpret_cast<const v4i32*>(Kn + KN8SW(r32, c0 + 1)));
;     const v8i32 a1 = cat8(*reinterpret_cast<const v4i32*>(Kn + 4096 + KN8SW(r32, c0)), *reinterpret_cast<const v4i32*>(Kn + 4096 + KN8SW(r32, c0 + 1)));
;     p0 = __builtin_amdgcn_mfma_scale_f32_32x32x64_f8f6f4(a0, qf[s], p0, 0, 0, 0, 127, 0, 124);
;     p1 = __builtin_amdgcn_mfma_scale_f32_32x32x64_f8f6f4(a1, qf[s], p1, 0, 0, 0, 127, 0, 124); }
;   { const int c0 = hi * 2;
.Lmla_s5_cont:
	s_add_i32 s30, s30, 1
	s_cmpk_lt_u32 s30, 42
	s_cbranch_scc1 .Lmla_stag_loop
	ds_read_b128 v[114:117], v215 offset:24576
	ds_read_b128 v[118:121], v216 offset:24576
	ds_read_b128 v[222:225], v215 offset:28672
	ds_read_b128 v[226:229], v216 offset:28672
	v_exp_f32_e32 v0, v82
	v_exp_f32_e32 v177, v83
	v_exp_f32_e32 v179, v84
	v_exp_f32_e32 v254, v85
	v_add_f32_e32 v219, v0, v177
	v_cvt_pk_fp8_f32 v246, v0, v177
	v_add_f32_e32 v219, v179, v219
	v_add_f32_e32 v219, v254, v219
	v_cvt_pk_fp8_f32 v246, v179, v254 op_sel:[0,0,1]
	s_waitcnt lgkmcnt(2)
	v_mfma_scale_f32_32x32x64_f8f6f4 v[114:129], v[114:121], v[146:153], v[230:245], v194, v193 op_sel_hi:[0,0,0]
	v_exp_f32_e32 v0, v86
	v_exp_f32_e32 v177, v87
	v_exp_f32_e32 v179, v88
	v_exp_f32_e32 v254, v89
	v_add_f32_e32 v219, v0, v219
	v_add_f32_e32 v219, v177, v219
	v_cvt_pk_fp8_f32 v247, v0, v177
	v_add_f32_e32 v219, v179, v219
	v_add_f32_e32 v219, v254, v219
	v_cvt_pk_fp8_f32 v247, v179, v254 op_sel:[0,0,1]
	ds_read_b128 v[82:85], v213 offset:24576
	ds_read_b128 v[86:89], v214 offset:24576
	s_waitcnt lgkmcnt(2)
	v_mfma_scale_f32_32x32x64_f8f6f4 v[98:113], v[222:229], v[146:153], v[230:245], v194, v193 op_sel_hi:[0,0,0]
	ds_read_b128 v[222:225], v213 offset:28672
	ds_read_b128 v[226:229], v214 offset:28672
	v_exp_f32_e32 v0, v90
	v_exp_f32_e32 v177, v91
	v_exp_f32_e32 v179, v92
	v_exp_f32_e32 v254, v93
	v_add_f32_e32 v219, v0, v219
	v_add_f32_e32 v219, v177, v219
	v_cvt_pk_fp8_f32 v248, v0, v177
	v_add_f32_e32 v219, v179, v219
	v_add_f32_e32 v219, v254, v219
	v_cvt_pk_fp8_f32 v248, v179, v254 op_sel:[0,0,1]
	v_exp_f32_e32 v0, v94
	v_exp_f32_e32 v177, v95
	v_exp_f32_e32 v179, v96
	v_exp_f32_e32 v254, v97
	v_add_f32_e32 v219, v0, v219
	v_add_f32_e32 v219, v177, v219
	v_cvt_pk_fp8_f32 v249, v0, v177
	v_add_f32_e32 v219, v179, v219
	v_add_f32_e32 v219, v254, v219
	v_cvt_pk_fp8_f32 v249, v179, v254 op_sel:[0,0,1]
	ds_read_b128 v[90:93], v185 offset:36864
	ds_read_b128 v[94:97], v186 offset:36864
	s_waitcnt lgkmcnt(4)
	v_mfma_scale_f32_32x32x64_f8f6f4 v[114:129], v[82:89], v[138:145], v[114:129], v194, v193 op_sel_hi:[0,0,0]
	v_exp_f32_e32 v0, v66
	v_exp_f32_e32 v177, v67
	v_exp_f32_e32 v179, v68
	v_exp_f32_e32 v254, v69
	v_add_f32_e32 v219, v0, v219
	v_add_f32_e32 v219, v177, v219
	v_cvt_pk_fp8_f32 v250, v0, v177
	v_add_f32_e32 v219, v179, v219
	v_add_f32_e32 v219, v254, v219
	v_cvt_pk_fp8_f32 v250, v179, v254 op_sel:[0,0,1]
	s_waitcnt lgkmcnt(2)
	v_mfma_scale_f32_32x32x64_f8f6f4 v[98:113], v[222:229], v[138:145], v[98:113], v194, v193 op_sel_hi:[0,0,0]
	ds_read_b128 v[222:225], v185 offset:38912
	ds_read_b128 v[226:229], v186 offset:38912
	v_exp_f32_e32 v0, v70
	v_exp_f32_e32 v177, v71
	v_exp_f32_e32 v179, v72
	v_exp_f32_e32 v254, v73
	v_add_f32_e32 v219, v0, v219
	v_add_f32_e32 v219, v177, v219
	v_cvt_pk_fp8_f32 v251, v0, v177
	v_add_f32_e32 v219, v179, v219
	v_add_f32_e32 v219, v254, v219
	v_cvt_pk_fp8_f32 v251, v179, v254 op_sel:[0,0,1]
	v_exp_f32_e32 v0, v74
	v_exp_f32_e32 v177, v75
	v_exp_f32_e32 v179, v76
	v_exp_f32_e32 v254, v77
	v_add_f32_e32 v219, v0, v219
	v_add_f32_e32 v219, v177, v219
	v_cvt_pk_fp8_f32 v252, v0, v177
	v_add_f32_e32 v219, v179, v219
	v_add_f32_e32 v219, v254, v219
	v_cvt_pk_fp8_f32 v252, v179, v254 op_sel:[0,0,1]
	s_waitcnt lgkmcnt(2)
	v_mfma_scale_f32_32x32x64_f8f6f4 v[114:129], v[90:97], v[130:137], v[114:129], v194, v193 op_sel_hi:[0,0,0]
	v_exp_f32_e32 v0, v78
	v_exp_f32_e32 v177, v79
	v_exp_f32_e32 v179, v80
	v_exp_f32_e32 v254, v81
	v_add_f32_e32 v219, v0, v219
	v_add_f32_e32 v219, v177, v219
	v_cvt_pk_fp8_f32 v253, v0, v177
	v_add_f32_e32 v219, v179, v219
	v_add_f32_e32 v219, v254, v219
	v_cvt_pk_fp8_f32 v253, v179, v254 op_sel:[0,0,1]
	ds_read_b128 v[90:93], v185 offset:0
	ds_read_b128 v[94:97], v186 offset:0
	ds_read_b128 v[82:85], v185 offset:2048
	ds_read_b128 v[86:89], v186 offset:2048
	ds_read_b128 v[74:77], v185 offset:4096
	ds_read_b128 v[78:81], v186 offset:4096
	ds_read_b128 v[66:69], v185 offset:6144
	ds_read_b128 v[70:73], v186 offset:6144
	s_waitcnt lgkmcnt(8)
	v_mfma_scale_f32_32x32x64_f8f6f4 v[98:113], v[222:229], v[130:137], v[98:113], v194, v193 op_sel_hi:[0,0,0]
	v_mov_b32_e32 v0, v219
	s_nop 1
	v_permlane32_swap_b32_e32 v219, v0
	v_add_f32_e32 v219, v219, v0
	v_fma_f32 v209, v209, v218, v219
	v_max_f32_e32 v177, v114, v115
	v_max3_f32 v177, v177, v116, v117
	v_max3_f32 v177, v177, v118, v119
	v_max3_f32 v177, v177, v120, v121
	v_max3_f32 v177, v177, v122, v123
	v_max3_f32 v177, v177, v124, v125
	v_max3_f32 v177, v177, v126, v127
	v_max3_f32 v177, v177, v128, v129
	s_waitcnt lgkmcnt(6)
	v_mfma_scale_f32_32x32x64_f8f6f4 v[50:65], v[246:253], v[90:97], v[50:65], v194, v194 op_sel_hi:[0,0,0]
	s_waitcnt lgkmcnt(4)
	v_mfma_scale_f32_32x32x64_f8f6f4 v[34:49], v[246:253], v[82:89], v[34:49], v194, v194 op_sel_hi:[0,0,0]
	s_waitcnt vmcnt(0)
	s_waitcnt lgkmcnt(0)
	s_barrier
	s_waitcnt lgkmcnt(2)
	v_mfma_scale_f32_32x32x64_f8f6f4 v[18:33], v[246:253], v[74:81], v[18:33], v194, v194 op_sel_hi:[0,0,0]
	s_add_i32 m0, s98, 0x0
	s_nop 0
	global_load_lds_dwordx4 v176, s[18:19]
	s_add_i32 m0, s98, 0x4000
	s_nop 0
	global_load_lds_dwordx4 v178, s[16:17]
	v_add_u32_e32 v176, 0x2000, v176
	v_add_u32_e32 v178, 0x20000, v178
	s_waitcnt lgkmcnt(0)
	v_mfma_scale_f32_32x32x64_f8f6f4 v[2:17], v[246:253], v[66:73], v[2:17], v194, v194 op_sel_hi:[0,0,0]
	v_max_f32_e32 v0, v98, v99
	v_max3_f32 v0, v0, v100, v101
	v_max3_f32 v0, v0, v102, v103
	v_max3_f32 v0, v0, v104, v105
	v_max3_f32 v0, v0, v106, v107
	v_max3_f32 v0, v0, v108, v109
	v_max3_f32 v0, v0, v110, v111
	v_max3_f32 v0, v0, v112, v113
	v_max_f32_e32 v177, v177, v0
	v_mov_b32_e32 v0, v177
	v_mov_b32_e32 v221, 1.0
	s_nop 0
	v_permlane32_swap_b32_e32 v177, v0
	v_max_f32_e32 v177, v177, v0
	v_cmp_ge_f32_e32 vcc, s90, v177
	s_cmp_eq_u64 vcc, exec
	s_cbranch_scc0 .Lmla_q0_newmax
; __device__ __forceinline__ void finishSM9(f32x16& p0, f32x16& p1, float alpha, float& l_reg, v8i32& p8) {
; #pragma unroll
;   for (int r = 0; r < 16; ++r) { p0[r] = __builtin_amdgcn_exp2f(p0[r]); p1[r] = __builtin_amdgcn_exp2f(p1[r]); }
;   float ps = 0;
; #pragma unroll
;   for (int r = 0; r < 16; ++r) ps += p0[r];
; #pragma unroll
;   for (int r = 0; r < 16; ++r) ps += p1[r];
;   { auto rr = __builtin_amdgcn_permlane32_swap(__float_as_uint(ps), __float_as_uint(ps), false, false);
;     ps = __uint_as_float(rr[0]) + __uint_as_float(rr[1]); }
;   l_reg = l_reg * alpha + ps;
; #pragma unroll
;   for (int g = 0; g < 4; ++g) {
;     int w = __builtin_amdgcn_cvt_pk_fp8_f32(p0[4 * g], p0[4 * g + 1], 0, false); p8[g] = __builtin_amdgcn_cvt_pk_fp8_f32(p0[4 * g + 2], p0[4 * g + 3], w, true);
;     int u = __builtin_amdgcn_cvt_pk_fp8_f32(p1[4 * g], p1[4 * g + 1], 0, false); p8[4 + g] = __builtin_amdgcn_cvt_pk_fp8_f32(p1[4 * g + 2], p1[4 * g + 3], u, true); }
; }
; __device__ __forceinline__ void pv8(f32x16* o, const char* Vt, const v8i32 p8, int r32, int hi) {
;   const int sw = (r32 >> 2) & 3, a0 = r32 * 64 + (((hi * 2) ^ sw) << 4), a1 = r32 * 64 + (((hi * 2 + 1) ^ sw) << 4);
; #pragma unroll
;   for (int d0 = 0; d0 < 4; ++d0) {
;     const v8i32 vf = cat8(*reinterpret_cast<const v4i32*>(Vt + d0 * 2048 + a0), *reinterpret_cast<const v4i32*>(Vt + d0 * 2048 + a1));
;     o[d0] = __builtin_amdgcn_mfma_scale_f32_32x32x64_f8f6f4(p8, vf, o[d0], 0, 0, 0, 127, 0, 127); }
; }
; __device__ __forceinline__ void qkt9(f32x16& p0, f32x16& p1, const char* Kn, const char* Kr, const v8i32* qf, const float init, int r32, int hi) {
; #pragma unroll
;   for (int r = 0; r < 16; ++r) { p0[r] = init; p1[r] = init; }
; #pragma unroll
;   for (int s = 0; s < 2; ++s) { const int c0 = s * 4 + hi * 2;
;     const v8i32 a0 = cat8(*reinterpret_cast<const v4i32*>(Kn + KN8SW(r32, c0)), *reinterpret_cast<const v4i32*>(Kn + KN8SW(r32, c0 + 1)));
;     const v8i32 a1 = cat8(*reinterpret_cast<const v4i32*>(Kn + 4096 + KN8SW(r32, c0)), *reinterpret_cast<const v4i32*>(Kn + 4096 + KN8SW(r32, c0 + 1)));
;     p0 = __builtin_amdgcn_mfma_scale_f32_32x32x64_f8f6f4(a0, qf[s], p0, 0, 0, 0, 127, 0, 124);
;     p1 = __builtin_amdgcn_mfma_scale_f32_32x32x64_f8f6f4(a1, qf[s], p1, 0, 0, 0, 127, 0, 124); }
;   { const int c0 = hi * 2;
.Lmla_q0_cont:
	ds_read_b128 v[82:85], v215 offset:51200
	ds_read_b128 v[86:89], v216 offset:51200
	ds_read_b128 v[222:225], v215 offset:55296
	ds_read_b128 v[226:229], v216 offset:55296
	v_exp_f32_e32 v0, v114
	v_exp_f32_e32 v177, v115
	v_exp_f32_e32 v179, v116
	v_exp_f32_e32 v254, v117
	v_add_f32_e32 v219, v0, v177
	v_cvt_pk_fp8_f32 v246, v0, v177
	v_add_f32_e32 v219, v179, v219
	v_add_f32_e32 v219, v254, v219
	v_cvt_pk_fp8_f32 v246, v179, v254 op_sel:[0,0,1]
	s_waitcnt lgkmcnt(2)
	v_mfma_scale_f32_32x32x64_f8f6f4 v[82:97], v[82:89], v[146:153], v[230:245], v194, v193 op_sel_hi:[0,0,0]
	v_exp_f32_e32 v0, v118
	v_exp_f32_e32 v177, v119
	v_exp_f32_e32 v179, v120
	v_exp_f32_e32 v254, v121
	v_add_f32_e32 v219, v0, v219
	v_add_f32_e32 v219, v177, v219
	v_cvt_pk_fp8_f32 v247, v0, v177
	v_add_f32_e32 v219, v179, v219
	v_add_f32_e32 v219, v254, v219
	v_cvt_pk_fp8_f32 v247, v179, v254 op_sel:[0,0,1]
	ds_read_b128 v[114:117], v213 offset:51200
	ds_read_b128 v[118:121], v214 offset:51200
	s_waitcnt lgkmcnt(2)
	v_mfma_scale_f32_32x32x64_f8f6f4 v[66:81], v[222:229], v[146:153], v[230:245], v194, v193 op_sel_hi:[0,0,0]
	ds_read_b128 v[222:225], v213 offset:55296
	ds_read_b128 v[226:229], v214 offset:55296
	v_exp_f32_e32 v0, v122
	v_exp_f32_e32 v177, v123
	v_exp_f32_e32 v179, v124
	v_exp_f32_e32 v254, v125
	v_add_f32_e32 v219, v0, v219
	v_add_f32_e32 v219, v177, v219
	v_cvt_pk_fp8_f32 v248, v0, v177
	v_add_f32_e32 v219, v179, v219
	v_add_f32_e32 v219, v254, v219
	v_cvt_pk_fp8_f32 v248, v179, v254 op_sel:[0,0,1]
	v_exp_f32_e32 v0, v126
	v_exp_f32_e32 v177, v127
	v_exp_f32_e32 v179, v128
	v_exp_f32_e32 v254, v129
	v_add_f32_e32 v219, v0, v219
	v_add_f32_e32 v219, v177, v219
	v_cvt_pk_fp8_f32 v249, v0, v177
	v_add_f32_e32 v219, v179, v219
	v_add_f32_e32 v219, v254, v219
	v_cvt_pk_fp8_f32 v249, v179, v254 op_sel:[0,0,1]
	ds_read_b128 v[122:125], v185 offset:59392
	ds_read_b128 v[126:129], v186 offset:59392
	s_waitcnt lgkmcnt(4)
	v_mfma_scale_f32_32x32x64_f8f6f4 v[82:97], v[114:121], v[138:145], v[82:97], v194, v193 op_sel_hi:[0,0,0]
	v_exp_f32_e32 v0, v98
	v_exp_f32_e32 v177, v99
	v_exp_f32_e32 v179, v100
	v_exp_f32_e32 v254, v101
	v_add_f32_e32 v219, v0, v219
	v_add_f32_e32 v219, v177, v219
	v_cvt_pk_fp8_f32 v250, v0, v177
	v_add_f32_e32 v219, v179, v219
	v_add_f32_e32 v219, v254, v219
	v_cvt_pk_fp8_f32 v250, v179, v254 op_sel:[0,0,1]
	s_waitcnt lgkmcnt(2)
	v_mfma_scale_f32_32x32x64_f8f6f4 v[66:81], v[222:229], v[138:145], v[66:81], v194, v193 op_sel_hi:[0,0,0]
	ds_read_b128 v[222:225], v185 offset:61440
	ds_read_b128 v[226:229], v186 offset:61440
	v_exp_f32_e32 v0, v102
	v_exp_f32_e32 v177, v103
	v_exp_f32_e32 v179, v104
	v_exp_f32_e32 v254, v105
	v_add_f32_e32 v219, v0, v219
	v_add_f32_e32 v219, v177, v219
	v_cvt_pk_fp8_f32 v251, v0, v177
	v_add_f32_e32 v219, v179, v219
	v_add_f32_e32 v219, v254, v219
	v_cvt_pk_fp8_f32 v251, v179, v254 op_sel:[0,0,1]
	v_exp_f32_e32 v0, v106
	v_exp_f32_e32 v177, v107
	v_exp_f32_e32 v179, v108
	v_exp_f32_e32 v254, v109
	v_add_f32_e32 v219, v0, v219
	v_add_f32_e32 v219, v177, v219
	v_cvt_pk_fp8_f32 v252, v0, v177
	v_add_f32_e32 v219, v179, v219
	v_add_f32_e32 v219, v254, v219
	v_cvt_pk_fp8_f32 v252, v179, v254 op_sel:[0,0,1]
	s_waitcnt lgkmcnt(2)
	v_mfma_scale_f32_32x32x64_f8f6f4 v[82:97], v[122:129], v[130:137], v[82:97], v194, v193 op_sel_hi:[0,0,0]
	v_exp_f32_e32 v0, v110
	v_exp_f32_e32 v177, v111
	v_exp_f32_e32 v179, v112
	v_exp_f32_e32 v254, v113
	v_add_f32_e32 v219, v0, v219
	v_add_f32_e32 v219, v177, v219
	v_cvt_pk_fp8_f32 v253, v0, v177
	v_add_f32_e32 v219, v179, v219
	v_add_f32_e32 v219, v254, v219
	v_cvt_pk_fp8_f32 v253, v179, v254 op_sel:[0,0,1]
	ds_read_b128 v[122:125], v185 offset:8192
	ds_read_b128 v[126:129], v186 offset:8192
	ds_read_b128 v[114:117], v185 offset:10240
	ds_read_b128 v[118:121], v186 offset:10240
	ds_read_b128 v[106:109], v185 offset:12288
	ds_read_b128 v[110:113], v186 offset:12288
	ds_read_b128 v[98:101], v185 offset:14336
	ds_read_b128 v[102:105], v186 offset:14336
	s_waitcnt lgkmcnt(8)
	v_mfma_scale_f32_32x32x64_f8f6f4 v[66:81], v[222:229], v[130:137], v[66:81], v194, v193 op_sel_hi:[0,0,0]
	v_mov_b32_e32 v0, v219
	s_nop 1
	v_permlane32_swap_b32_e32 v219, v0
	v_add_f32_e32 v219, v219, v0
	v_fma_f32 v209, v209, v221, v219
	v_max_f32_e32 v177, v82, v83
	v_max3_f32 v177, v177, v84, v85
	v_max3_f32 v177, v177, v86, v87
	v_max3_f32 v177, v177, v88, v89
	v_max3_f32 v177, v177, v90, v91
	v_max3_f32 v177, v177, v92, v93
	v_max3_f32 v177, v177, v94, v95
	v_max3_f32 v177, v177, v96, v97
	s_waitcnt lgkmcnt(6)
	v_mfma_scale_f32_32x32x64_f8f6f4 v[50:65], v[246:253], v[122:129], v[50:65], v194, v194 op_sel_hi:[0,0,0]
	s_waitcnt lgkmcnt(4)
	v_mfma_scale_f32_32x32x64_f8f6f4 v[34:49], v[246:253], v[114:121], v[34:49], v194, v194 op_sel_hi:[0,0,0]
	s_waitcnt vmcnt(0)
	s_waitcnt lgkmcnt(0)
	s_barrier
	s_waitcnt lgkmcnt(2)
	v_mfma_scale_f32_32x32x64_f8f6f4 v[18:33], v[246:253], v[106:113], v[18:33], v194, v194 op_sel_hi:[0,0,0]
	s_waitcnt lgkmcnt(0)
	v_mfma_scale_f32_32x32x64_f8f6f4 v[2:17], v[246:253], v[98:105], v[2:17], v194, v194 op_sel_hi:[0,0,0]
	v_max_f32_e32 v0, v66, v67
	v_max3_f32 v0, v0, v68, v69
	v_max3_f32 v0, v0, v70, v71
	v_max3_f32 v0, v0, v72, v73
	v_max3_f32 v0, v0, v74, v75
	v_max3_f32 v0, v0, v76, v77
	v_max3_f32 v0, v0, v78, v79
	v_max3_f32 v0, v0, v80, v81
	v_max_f32_e32 v177, v177, v0
	v_mov_b32_e32 v0, v177
	v_mov_b32_e32 v218, 1.0
	s_nop 0
	v_permlane32_swap_b32_e32 v177, v0
	v_max_f32_e32 v177, v177, v0
	v_cmp_ge_f32_e32 vcc, s90, v177
	s_cmp_eq_u64 vcc, exec
	s_cbranch_scc0 .Lmla_q1_newmax
